# RG-LRU tile phases hand-rewritten: 16-byte conv loads/LDS writes, conv values via identity-fragment MFMA, folded gate constants, wide pass-2 output stage
# speedup vs baseline: 1.0152x; 1.0152x over previous
; __device__ __forceinline__ float fexp(float x) { return __builtin_amdgcn_exp2f(x * 1.4426950408889634f); }
; __device__ __forceinline__ float flog(float x) { return __builtin_amdgcn_logf(x) * 0.6931471805599453f; }
; template <int PASS>
; __device__ __forceinline__ void lru_tile_phase(const Params& p, int jl, int Mrows, char* smem, int tid, int bid) {
;   char* xcL = smem;
;   float* aL = (float*)(smem + 16384);
;   float* uL = (float*)(smem + 16384 + 65536);
;   const u16* P2 = (const u16*)(p.ws + OFF_S);
;   u16* H = (u16*)(p.ws + OFF_LRU_Y);
;   float2* summ = (float2*)(p.ws + OFF_LRU_SUM);
;   const float* carry = (const float*)(p.ws + OFF_LRU_CAR);
;   const u16* Wbd = (const u16*)(p.ws + OFF_WMIX) + 3072 * 1024;
;   const int ntt = Mrows / 64;
;   bf16x8 wb0[8], wb1[8]; float c_ba = 0.f, c_bx = 0.f, c_sp = 0.f; int n_loaded = -1;
;   for (int job = bid; job < ntt * 8; job += gridDim.x) {
;     asm volatile("" : "+v"(tid));
;     const int lane = tid & 63, wid = tid >> 6, l32 = lane & 31, hi = lane >> 5;
;     const int tt = job >> 3, n = job & 7;
;     const bool lat = tt < 512;
;     const int rowbase = lat ? tt * 64 : ML + (tt - 512) * 64;
;     const int sloc = lat ? (tt & 63) * 64 : ((tt - 512) & 3) * 64;
;     const int TT = lat ? SEQL : CTXL;
;     ...
;       const int cbk = wid & 3, dh = wid >> 2;
;       const int chl = cbk * 32 + l32, col = n * 128 + chl;
;       if (n != n_loaded) {
;         const u16* wbase = Wbd + (size_t)n * 16384 + (size_t)chl * 128 + hi * 8;
; #pragma unroll
;         for (int k16 = 0; k16 < 8; ++k16) {
;           wb0[k16] = *(const bf16x8*)(wbase + (size_t)(dh * 2 + 0) * 131072 + k16 * 16);
;           wb1[k16] = *(const bf16x8*)(wbase + (size_t)(dh * 2 + 1) * 131072 + k16 * 16);
;         }
;         const float* pba = dh ? p.in[26] : p.in[21]; const float* pbx = dh ? p.in[28] : p.in[23]; const float* plam = dh ? p.in[29] : p.in[24];
;         c_ba = pba[(size_t)jl * 1024 + col]; c_bx = pbx[(size_t)jl * 1024 + col];
;         c_sp = -8.f * flog(1.f + fexp(-plam[(size_t)jl * 1024 + col]));
;         n_loaded = n;
;       }
.LBB0_216:
	s_andn2_b64 vcc, exec, s[0:1]
	s_cbranch_vccnz .LBB0_229
	s_lshr_b32 s26, s34, 3
	s_cmp_ge_i32 s62, s26
	s_cbranch_scc1 .LBB0_229
	v_readlane_b32 s0, v253, 1
	v_readlane_b32 s1, v253, 2
	s_sub_u32 s0, s0, 0x138
	s_subb_u32 s1, s1, 0
	s_load_dwordx4 s[36:39], s[0:1], 0x90
	s_load_dwordx2 s[40:41], s[0:1], 0xa8
	s_load_dwordx2 s[44:45], s[0:1], 0xb8
	s_load_dwordx2 s[46:47], s[0:1], 0xc0
	s_load_dwordx2 s[42:43], s[0:1], 0xd0
	s_load_dwordx4 s[48:51], s[0:1], 0xe0
	s_load_dwordx2 s[4:5], s[0:1], 0x128
	s_waitcnt lgkmcnt(0)
	s_lshl_b32 s0, s72, 14
	s_add_u32 s36, s36, s0
	s_addc_u32 s37, s37, 0
	s_lshl_b32 s0, s72, 12
	s_add_u32 s38, s38, s0
	s_addc_u32 s39, s39, 0
	s_add_u32 s40, s40, s0
	s_addc_u32 s41, s41, 0
	s_add_u32 s42, s42, s0
	s_addc_u32 s43, s43, 0
	s_add_u32 s44, s44, s0
	s_addc_u32 s45, s45, 0
	s_add_u32 s46, s46, s0
	s_addc_u32 s47, s47, 0
	s_add_u32 s48, s48, s0
	s_addc_u32 s49, s49, 0
	s_add_u32 s50, s50, s0
	s_addc_u32 s51, s51, 0
	s_add_u32 s22, s4, 0x129dc000
	s_addc_u32 s23, s5, 0
	s_add_u32 s24, s4, 0x1325c000
	s_addc_u32 s25, s5, 0
	s_add_u32 s28, s4, 0x1369c000
	s_addc_u32 s29, s5, 0
	s_add_u32 s18, s4, 0x8e00000
	s_addc_u32 s19, s5, 0
	v_and_b32_e32 v80, 63, v203
	v_lshrrev_b32_e32 v81, 6, v203
	v_and_b32_e32 v236, 31, v203
	v_bfe_u32 v237, v203, 5, 1
	v_lshrrev_b32_e32 v84, 4, v203
	v_and_b32_e32 v99, 15, v203
	v_readfirstlane_b32 s0, v81
	s_and_b32 s1, s0, 3
	s_lshr_b32 s16, s0, 2
	s_mov_b32 s27, s0
	v_lshlrev_b32_e32 v190, 1, v84
	v_lshlrev_b32_e32 v191, 4, v99
	v_or_b32_e32 v195, 0, v190
	v_and_b32_e32 v196, 15, v195
	v_xor_b32_e32 v196, v99, v196
	v_lshlrev_b32_e32 v196, 4, v196
	v_lshl_or_b32 v183, v195, 8, v196
	v_or_b32_e32 v195, 1, v190
	v_and_b32_e32 v196, 15, v195
	v_xor_b32_e32 v196, v99, v196
	v_lshlrev_b32_e32 v196, 4, v196
	v_lshl_or_b32 v184, v195, 8, v196
	v_and_b32_e32 v195, 15, v236
	v_xor_b32_e32 v195, v237, v195
	v_lshlrev_b32_e32 v195, 4, v195
	v_lshl_or_b32 v185, v236, 8, v195
	s_lshl_b32 s4, s1, 5
	v_add_u32_e32 v195, s4, v236
	s_lshl_b32 s5, s16, 6
	v_lshl_add_u32 v196, v237, 2, s5
	v_lshlrev_b32_e32 v196, 7, v196
	v_add_u32_e32 v196, v196, v195
	v_lshlrev_b32_e32 v186, 2, v196
	v_add_u32_e32 v186, 0x4000, v186
	v_add_u32_e32 v187, 0x10000, v186
	v_bfe_u32 v196, v236, 3, 1
	v_cmp_eq_u32_e32 vcc, v196, v237
	v_and_b32_e32 v197, 7, v236
	v_lshrrev_b32_e32 v198, 1, v197
	v_and_b32_e32 v197, 1, v197
	v_lshlrev_b32_e32 v197, 4, v197
	v_mov_b32_e32 v199, 0x3f80
	v_lshlrev_b32_e32 v199, v197, v199
	v_cndmask_b32_e32 v199, 0, v199, vcc
	v_lshrrev_b32_e32 v200, 4, v236
	v_cmp_eq_u32_e32 vcc, 0, v200
	v_cmp_eq_u32_e64 s[4:5], 0, v198
	s_and_b64 vcc, vcc, s[4:5]
	v_cndmask_b32_e32 v172, 0, v199, vcc
	v_cmp_eq_u32_e32 vcc, 0, v200
	v_cmp_eq_u32_e64 s[4:5], 1, v198
	s_and_b64 vcc, vcc, s[4:5]
	v_cndmask_b32_e32 v173, 0, v199, vcc
	v_cmp_eq_u32_e32 vcc, 0, v200
	v_cmp_eq_u32_e64 s[4:5], 2, v198
	s_and_b64 vcc, vcc, s[4:5]
	v_cndmask_b32_e32 v174, 0, v199, vcc
	v_cmp_eq_u32_e32 vcc, 0, v200
	v_cmp_eq_u32_e64 s[4:5], 3, v198
	s_and_b64 vcc, vcc, s[4:5]
	v_cndmask_b32_e32 v175, 0, v199, vcc
	v_cmp_eq_u32_e32 vcc, 1, v200
	v_cmp_eq_u32_e64 s[4:5], 0, v198
	s_and_b64 vcc, vcc, s[4:5]
	v_cndmask_b32_e32 v176, 0, v199, vcc
	v_cmp_eq_u32_e32 vcc, 1, v200
	v_cmp_eq_u32_e64 s[4:5], 1, v198
	s_and_b64 vcc, vcc, s[4:5]
	v_cndmask_b32_e32 v177, 0, v199, vcc
	v_cmp_eq_u32_e32 vcc, 1, v200
	v_cmp_eq_u32_e64 s[4:5], 2, v198
	s_and_b64 vcc, vcc, s[4:5]
	v_cndmask_b32_e32 v178, 0, v199, vcc
	v_cmp_eq_u32_e32 vcc, 1, v200
	v_cmp_eq_u32_e64 s[4:5], 3, v198
	s_and_b64 vcc, vcc, s[4:5]
	v_cndmask_b32_e32 v179, 0, v199, vcc
	v_and_b32_e32 v195, 0x7f, v203
	v_bfe_u32 v196, v203, 7, 1
	v_lshl_or_b32 v196, v196, 13, v195
	v_lshlrev_b32_e32 v188, 2, v196
	v_add_u32_e32 v188, 0x4000, v188
	v_bfe_u32 v196, v203, 7, 1
	v_lshl_or_b32 v194, v196, 10, v195
	v_lshrrev_b32_e32 v195, 3, v203
	v_and_b32_e32 v196, 7, v203
	v_lshlrev_b32_e32 v197, 5, v196
	v_lshl_or_b32 v192, v195, 12, v197
	v_lshl_or_b32 v193, v195, 11, v197
	v_lshlrev_b32_e32 v197, 6, v196
	v_lshl_or_b32 v189, v195, 9, v197
	v_add_u32_e32 v189, 0x14000, v189
	s_mov_b32 s6, s62
	s_mov_b32 s30, -1
.Llru2_job:
	s_lshr_b32 s8, s6, 3
	s_and_b32 s7, s6, 7
	s_cmp_eq_u32 s7, s30
	s_cbranch_scc1 .Llru2_nloaded
	s_mov_b32 s30, s7
	s_lshl_b32 s0, s7, 9
	v_lshl_add_u32 v195, v99, 5, s0
	global_load_dwordx4 v[100:103], v195, s[36:37]
	global_load_dwordx4 v[104:107], v195, s[36:37] offset:16
	s_add_u32 s4, s36, 4096
	s_addc_u32 s5, s37, 0
	global_load_dwordx4 v[108:111], v195, s[4:5]
	global_load_dwordx4 v[112:115], v195, s[4:5] offset:16
	s_add_u32 s4, s36, 8192
	s_addc_u32 s5, s37, 0
	global_load_dwordx4 v[116:119], v195, s[4:5]
	global_load_dwordx4 v[120:123], v195, s[4:5] offset:16
	s_add_u32 s4, s36, 12288
	s_addc_u32 s5, s37, 0
	global_load_dwordx4 v[124:127], v195, s[4:5]
	global_load_dwordx4 v[128:131], v195, s[4:5] offset:16
	global_load_dwordx4 v[132:135], v195, s[38:39]
	global_load_dwordx4 v[136:139], v195, s[38:39] offset:16
	s_lshl_b32 s0, s16, 1
	s_lshl_b32 s0, s0, 3
	s_add_u32 s0, s0, s7
	s_lshl_b32 s0, s0, 15
	s_add_u32 s4, s18, s0
	s_addc_u32 s5, s19, 0
	s_and_b32 s0, s27, 3
	s_lshl_b32 s0, s0, 5
	v_add_u32_e32 v196, s0, v236
	v_lshlrev_b32_e32 v196, 8, v196
	v_lshl_or_b32 v196, v237, 4, v196
	global_load_dwordx4 v[140:143], v196, s[4:5] offset:0
	global_load_dwordx4 v[144:147], v196, s[4:5] offset:32
	global_load_dwordx4 v[148:151], v196, s[4:5] offset:64
	global_load_dwordx4 v[152:155], v196, s[4:5] offset:96
	global_load_dwordx4 v[156:159], v196, s[4:5] offset:128
	global_load_dwordx4 v[160:163], v196, s[4:5] offset:160
	global_load_dwordx4 v[164:167], v196, s[4:5] offset:192
	global_load_dwordx4 v[168:171], v196, s[4:5] offset:224
	s_add_u32 s4, s4, 0x40000
	s_addc_u32 s5, s5, 0
	global_load_dwordx4 v[204:207], v196, s[4:5] offset:0
	global_load_dwordx4 v[208:211], v196, s[4:5] offset:32
	global_load_dwordx4 v[212:215], v196, s[4:5] offset:64
	global_load_dwordx4 v[216:219], v196, s[4:5] offset:96
	global_load_dwordx4 v[220:223], v196, s[4:5] offset:128
	global_load_dwordx4 v[224:227], v196, s[4:5] offset:160
	global_load_dwordx4 v[228:231], v196, s[4:5] offset:192
	global_load_dwordx4 v[232:235], v196, s[4:5] offset:224
	s_lshl_b32 s0, s7, 7
	s_and_b32 s1, s27, 3
	s_lshl_b32 s1, s1, 5
	s_add_u32 s0, s0, s1
	v_add_u32_e32 v197, s0, v236
	v_lshlrev_b32_e32 v197, 2, v197
	s_cmp_eq_u32 s16, 0
	s_cselect_b32 s4, s40, s42
	s_cselect_b32 s5, s41, s43
	global_load_dword v180, v197, s[4:5]
	s_cselect_b32 s4, s44, s48
	s_cselect_b32 s5, s45, s49
	global_load_dword v181, v197, s[4:5]
	s_cselect_b32 s4, s46, s50
	s_cselect_b32 s5, s47, s51
	global_load_dword v182, v197, s[4:5]
	s_waitcnt vmcnt(0)
	v_mul_f32_e32 v180, 0xbfb8aa3b, v180
	v_mul_f32_e32 v181, 0xbfb8aa3b, v181
	v_mul_f32_e32 v182, 0xbfb8aa3b, v182
	v_exp_f32_e32 v182, v182
	s_nop 0
	v_add_f32_e32 v182, 1.0, v182
	v_log_f32_e32 v182, v182
	s_nop 0
	v_mul_f32_e32 v182, 0x3f317218, v182
	v_mul_f32_e32 v182, 0xc1000000, v182
	v_mul_f32_e32 v182, 0x3fb8aa3b, v182
; __device__ __forceinline__ u16 f2bf(float x) { return (u16)(cvtpk(x, 0.f) & 0xffffu); }
; template <int PASS>
; __device__ __forceinline__ void lru_tile_phase(const Params& p, int jl, int Mrows, char* smem, int tid, int bid) {
;     ...
;     const int TT = lat ? SEQL : CTXL;
;     unsigned gv[16]; float carry_in = 0.f;
;     if (PASS == 2) {
;       const int ch = tid & 127, tg = tid >> 7;
; #pragma unroll
;       for (int i = 0; i < 16; ++i) gv[i] = P2[(size_t)(rowbase + tg * 16 + i) * 2048 + n * 128 + ch];
;       if (tid < 256) carry_in = carry[(size_t)(tt * 2 + (tid >> 7)) * 1024 + n * 128 + (tid & 127)];
;     }
;     {
;       const int ch = tid & 127, tg = tid >> 7, t0 = tg * 16;
;       const int col = n * 128 + ch;
;       float cw0 = p.in[18][(size_t)(jl * 4 + 0) * 1024 + col], cw1 = p.in[18][(size_t)(jl * 4 + 1) * 1024 + col];
;       float cw2 = p.in[18][(size_t)(jl * 4 + 2) * 1024 + col], cw3 = p.in[18][(size_t)(jl * 4 + 3) * 1024 + col];
;       const float cb = p.in[19][(size_t)jl * 1024 + col];
;       float xb[19]; unsigned xraw[19];
;       const u16* xsrc = P2 + (size_t)(rowbase - sloc) * 2048 + 1024 + col;
; #pragma unroll
;       for (int i = 0; i < 19; ++i) {
;         const int s = sloc + t0 + i - 2;
;         const int sc = s < 0 ? 0 : (s >= TT ? TT - 1 : s);
;         xraw[i] = xsrc[(size_t)sc * 2048];
;       }
; #pragma unroll
;       for (int i = 0; i < 19; ++i) {
;         const int s = sloc + t0 + i - 2;
;         xb[i] = (s >= 0 && s < TT) ? __uint_as_float(xraw[i] << 16) : 0.f;
;       }
; #pragma unroll
;       for (int i = 0; i < 16; ++i) {
;         const float xc = cb + cw0 * xb[i] + cw1 * xb[i + 1] + cw2 * xb[i + 2] + cw3 * xb[i + 3];
;         *(u16*)(xcL + swz256(t0 + i, ch >> 3) + (ch & 7) * 2) = f2bf(xc);
;       }
;     }
;     __syncthreads();
.Llru2_nloaded:
	s_movk_i32 s0, 0x1000
	s_cmp_lt_u32 s8, 512
	s_cselect_b32 s4, 0, 512
	s_cselect_b32 s5, 0, 0x8000
	s_cselect_b32 s1, 63, 3
	s_cselect_b32 s11, s0, 0x100
	s_sub_u32 s0, s8, s4
	s_lshl_b32 s9, s0, 6
	s_add_u32 s9, s9, s5
	s_and_b32 s10, s0, s1
	s_lshl_b32 s10, s10, 6
	s_cmp_eq_u32 s10, 0
	s_cselect_b32 s4, 0, -2
	s_add_u32 s0, s10, 64
	s_cmp_eq_u32 s0, s11
	s_cselect_b32 s5, 63, 0x41
	s_lshl_b32 s0, s9, 12
	s_lshl_b32 s1, s7, 8
	s_add_u32 s0, s0, s1
	s_add_u32 s20, s92, s0
	s_addc_u32 s21, s93, 0
	s_sub_u32 s0, s20, 0x1800
	s_subb_u32 s1, s21, 0
	v_add_u32_e32 v44, -2, v190
	v_max_i32_e32 v49, s4, v44
	v_min_i32_e32 v49, s5, v49
	v_add_u32_e32 v195, 2, v49
	v_lshl_add_u32 v195, v195, 12, v191
	global_load_dwordx4 v[0:3], v195, s[0:1]
	v_add_u32_e32 v45, -1, v190
	v_max_i32_e32 v50, s4, v45
	v_min_i32_e32 v50, s5, v50
	v_add_u32_e32 v195, 2, v50
	v_lshl_add_u32 v195, v195, 12, v191
	global_load_dwordx4 v[4:7], v195, s[0:1]
	v_add_u32_e32 v46, 0, v190
	v_max_i32_e32 v51, s4, v46
	v_min_i32_e32 v51, s5, v51
	v_add_u32_e32 v195, 2, v51
	v_lshl_add_u32 v195, v195, 12, v191
	global_load_dwordx4 v[8:11], v195, s[0:1]
	v_add_u32_e32 v47, 1, v190
	v_max_i32_e32 v52, s4, v47
	v_min_i32_e32 v52, s5, v52
	v_add_u32_e32 v195, 2, v52
	v_lshl_add_u32 v195, v195, 12, v191
	global_load_dwordx4 v[12:15], v195, s[0:1]
	v_add_u32_e32 v48, 2, v190
	v_max_i32_e32 v53, s4, v48
	v_min_i32_e32 v53, s5, v53
	v_add_u32_e32 v195, 2, v53
	v_lshl_add_u32 v195, v195, 12, v191
	global_load_dwordx4 v[16:19], v195, s[0:1]
	global_load_dwordx4 v[92:95], v192, s[20:21]
	global_load_dwordx4 v[244:247], v192, s[20:21] offset:16
	s_lshl_b32 s0, s8, 11
	s_lshl_b32 s1, s7, 7
	s_add_u32 s0, s0, s1
	s_lshl_b32 s0, s0, 2
	s_add_u32 s0, s24, s0
	s_addc_u32 s1, s25, 0
	v_lshlrev_b32_e32 v196, 2, v194
	global_load_dword v252, v196, s[0:1]
	v_mov_b32_e32 v20, v132
	v_mov_b32_e32 v21, v133
	v_mov_b32_e32 v22, v134
	v_mov_b32_e32 v23, v135
	v_mov_b32_e32 v24, v136
	v_mov_b32_e32 v25, v137
	v_mov_b32_e32 v26, v138
	v_mov_b32_e32 v27, v139
	v_mov_b32_e32 v28, v132
	v_mov_b32_e32 v29, v133
	v_mov_b32_e32 v30, v134
	v_mov_b32_e32 v31, v135
	v_mov_b32_e32 v32, v136
	v_mov_b32_e32 v33, v137
	v_mov_b32_e32 v34, v138
	v_mov_b32_e32 v35, v139
	s_waitcnt vmcnt(7)
	v_cmp_eq_u32_e32 vcc, v44, v49
	s_nop 1
	v_cndmask_b32_e32 v0, 0, v0, vcc
	v_cndmask_b32_e32 v1, 0, v1, vcc
	v_cndmask_b32_e32 v2, 0, v2, vcc
	v_cndmask_b32_e32 v3, 0, v3, vcc
	v_lshlrev_b32_e32 v36, 16, v0
	v_and_b32_e32 v37, 0xffff0000, v0
	v_lshlrev_b32_e32 v38, 16, v1
	v_and_b32_e32 v39, 0xffff0000, v1
	v_lshlrev_b32_e32 v40, 16, v2
	v_and_b32_e32 v41, 0xffff0000, v2
	v_lshlrev_b32_e32 v42, 16, v3
	v_and_b32_e32 v43, 0xffff0000, v3
	v_fmac_f32_e32 v20, v100, v36
	v_fmac_f32_e32 v21, v101, v37
	v_fmac_f32_e32 v22, v102, v38
	v_fmac_f32_e32 v23, v103, v39
	v_fmac_f32_e32 v24, v104, v40
	v_fmac_f32_e32 v25, v105, v41
	v_fmac_f32_e32 v26, v106, v42
	v_fmac_f32_e32 v27, v107, v43
	s_waitcnt vmcnt(6)
	v_cmp_eq_u32_e32 vcc, v45, v50
	s_nop 1
	v_cndmask_b32_e32 v4, 0, v4, vcc
	v_cndmask_b32_e32 v5, 0, v5, vcc
	v_cndmask_b32_e32 v6, 0, v6, vcc
	v_cndmask_b32_e32 v7, 0, v7, vcc
	v_lshlrev_b32_e32 v36, 16, v4
	v_and_b32_e32 v37, 0xffff0000, v4
	v_lshlrev_b32_e32 v38, 16, v5
	v_and_b32_e32 v39, 0xffff0000, v5
	v_lshlrev_b32_e32 v40, 16, v6
	v_and_b32_e32 v41, 0xffff0000, v6
	v_lshlrev_b32_e32 v42, 16, v7
	v_and_b32_e32 v43, 0xffff0000, v7
	v_fmac_f32_e32 v20, v108, v36
	v_fmac_f32_e32 v21, v109, v37
	v_fmac_f32_e32 v22, v110, v38
	v_fmac_f32_e32 v23, v111, v39
	v_fmac_f32_e32 v24, v112, v40
	v_fmac_f32_e32 v25, v113, v41
	v_fmac_f32_e32 v26, v114, v42
	v_fmac_f32_e32 v27, v115, v43
	v_fmac_f32_e32 v28, v100, v36
	v_fmac_f32_e32 v29, v101, v37
	v_fmac_f32_e32 v30, v102, v38
	v_fmac_f32_e32 v31, v103, v39
	v_fmac_f32_e32 v32, v104, v40
	v_fmac_f32_e32 v33, v105, v41
	v_fmac_f32_e32 v34, v106, v42
	v_fmac_f32_e32 v35, v107, v43
	s_waitcnt vmcnt(5)
	v_cmp_eq_u32_e32 vcc, v46, v51
	s_nop 1
	v_cndmask_b32_e32 v8, 0, v8, vcc
	v_cndmask_b32_e32 v9, 0, v9, vcc
	v_cndmask_b32_e32 v10, 0, v10, vcc
	v_cndmask_b32_e32 v11, 0, v11, vcc
	v_lshlrev_b32_e32 v36, 16, v8
	v_and_b32_e32 v37, 0xffff0000, v8
	v_lshlrev_b32_e32 v38, 16, v9
	v_and_b32_e32 v39, 0xffff0000, v9
	v_lshlrev_b32_e32 v40, 16, v10
	v_and_b32_e32 v41, 0xffff0000, v10
	v_lshlrev_b32_e32 v42, 16, v11
	v_and_b32_e32 v43, 0xffff0000, v11
	v_fmac_f32_e32 v20, v116, v36
	v_fmac_f32_e32 v21, v117, v37
	v_fmac_f32_e32 v22, v118, v38
	v_fmac_f32_e32 v23, v119, v39
	v_fmac_f32_e32 v24, v120, v40
	v_fmac_f32_e32 v25, v121, v41
	v_fmac_f32_e32 v26, v122, v42
	v_fmac_f32_e32 v27, v123, v43
	v_fmac_f32_e32 v28, v108, v36
	v_fmac_f32_e32 v29, v109, v37
	v_fmac_f32_e32 v30, v110, v38
	v_fmac_f32_e32 v31, v111, v39
	v_fmac_f32_e32 v32, v112, v40
	v_fmac_f32_e32 v33, v113, v41
	v_fmac_f32_e32 v34, v114, v42
	v_fmac_f32_e32 v35, v115, v43
	s_waitcnt vmcnt(4)
	v_cmp_eq_u32_e32 vcc, v47, v52
	s_nop 1
	v_cndmask_b32_e32 v12, 0, v12, vcc
	v_cndmask_b32_e32 v13, 0, v13, vcc
	v_cndmask_b32_e32 v14, 0, v14, vcc
	v_cndmask_b32_e32 v15, 0, v15, vcc
	v_lshlrev_b32_e32 v36, 16, v12
	v_and_b32_e32 v37, 0xffff0000, v12
	v_lshlrev_b32_e32 v38, 16, v13
	v_and_b32_e32 v39, 0xffff0000, v13
	v_lshlrev_b32_e32 v40, 16, v14
	v_and_b32_e32 v41, 0xffff0000, v14
	v_lshlrev_b32_e32 v42, 16, v15
	v_and_b32_e32 v43, 0xffff0000, v15
	v_fmac_f32_e32 v20, v124, v36
	v_fmac_f32_e32 v21, v125, v37
	v_fmac_f32_e32 v22, v126, v38
	v_fmac_f32_e32 v23, v127, v39
	v_fmac_f32_e32 v24, v128, v40
	v_fmac_f32_e32 v25, v129, v41
	v_fmac_f32_e32 v26, v130, v42
	v_fmac_f32_e32 v27, v131, v43
	v_fmac_f32_e32 v28, v116, v36
	v_fmac_f32_e32 v29, v117, v37
	v_fmac_f32_e32 v30, v118, v38
	v_fmac_f32_e32 v31, v119, v39
	v_fmac_f32_e32 v32, v120, v40
	v_fmac_f32_e32 v33, v121, v41
	v_fmac_f32_e32 v34, v122, v42
	v_fmac_f32_e32 v35, v123, v43
	s_waitcnt vmcnt(3)
	v_cmp_eq_u32_e32 vcc, v48, v53
	s_nop 1
	v_cndmask_b32_e32 v16, 0, v16, vcc
	v_cndmask_b32_e32 v17, 0, v17, vcc
	v_cndmask_b32_e32 v18, 0, v18, vcc
	v_cndmask_b32_e32 v19, 0, v19, vcc
	v_lshlrev_b32_e32 v36, 16, v16
	v_and_b32_e32 v37, 0xffff0000, v16
	v_lshlrev_b32_e32 v38, 16, v17
	v_and_b32_e32 v39, 0xffff0000, v17
	v_lshlrev_b32_e32 v40, 16, v18
	v_and_b32_e32 v41, 0xffff0000, v18
	v_lshlrev_b32_e32 v42, 16, v19
	v_and_b32_e32 v43, 0xffff0000, v19
	v_fmac_f32_e32 v28, v124, v36
	v_fmac_f32_e32 v29, v125, v37
	v_fmac_f32_e32 v30, v126, v38
	v_fmac_f32_e32 v31, v127, v39
	v_fmac_f32_e32 v32, v128, v40
	v_fmac_f32_e32 v33, v129, v41
	v_fmac_f32_e32 v34, v130, v42
	v_fmac_f32_e32 v35, v131, v43
	v_cvt_pk_bf16_f32 v36, v20, v21
	v_cvt_pk_bf16_f32 v37, v22, v23
	v_cvt_pk_bf16_f32 v38, v24, v25
	v_cvt_pk_bf16_f32 v39, v26, v27
	v_cvt_pk_bf16_f32 v40, v28, v29
	v_cvt_pk_bf16_f32 v41, v30, v31
	v_cvt_pk_bf16_f32 v42, v32, v33
	v_cvt_pk_bf16_f32 v43, v34, v35
	ds_write_b128 v183, v[36:39]
	ds_write_b128 v184, v[40:43]
	s_waitcnt lgkmcnt(0)
	s_barrier
; __device__ __forceinline__ float bf2f(u16 x) { return __uint_as_float(((unsigned)x) << 16); }
; __device__ __forceinline__ float fexp(float x) { return __builtin_amdgcn_exp2f(x * 1.4426950408889634f); }
; __device__ __forceinline__ int crow(int r, int hi) { return (r & 3) + 8 * (r >> 2) + 4 * hi; }
; template <int PASS>
; __device__ __forceinline__ void lru_tile_phase(const Params& p, int jl, int Mrows, char* smem, int tid, int bid) {
;     ...
; #pragma unroll
;       for (int tb = 0; tb < 2; ++tb) {
;         f32x16 acc0, acc1;
; #pragma unroll
;         for (int r = 0; r < 16; ++r) { acc0[r] = 0.f; acc1[r] = 0.f; }
;         bf16x8 af[8];
; #pragma unroll
;         for (int k16 = 0; k16 < 8; ++k16) af[k16] = *(const bf16x8*)(xcL + swz256(tb * 32 + l32, k16 * 2 + hi));
; #pragma unroll
;         for (int k16 = 0; k16 < 8; ++k16) {
;           acc0 = __builtin_amdgcn_mfma_f32_32x32x16_bf16(af[k16], wb0[k16], acc0, 0, 0, 0);
;           acc1 = __builtin_amdgcn_mfma_f32_32x32x16_bf16(af[k16], wb1[k16], acc1, 0, 0, 0);
;         }
; #pragma unroll
;         for (int r = 0; r < 16; ++r) {
;           const int tok = tb * 32 + crow(r, hi);
;           const float xc = bf2f(*(const u16*)(xcL + swz256(tok, chl >> 3) + (chl & 7) * 2));
;           const float la = c_sp * __builtin_amdgcn_rcpf(1.f + fexp(-(acc0[r] + c_ba)));
;           const float ii = __builtin_amdgcn_rcpf(1.f + fexp(-(acc1[r] + c_bx)));
;           const float av = fexp(la);
;           aL[(dh * 64 + tok) * 128 + chl] = av;
;           uL[(dh * 64 + tok) * 128 + chl] = __builtin_amdgcn_sqrtf(fmaxf(1.f - av * av, 0.f)) * (ii * xc);
;         }
	ds_read_b128 v[48:51], v185 offset:0
	v_xor_b32_e32 v196, 32, v185
	ds_read_b128 v[52:55], v196 offset:0
	v_xor_b32_e32 v195, 64, v185
	ds_read_b128 v[56:59], v195 offset:0
	v_xor_b32_e32 v196, 96, v185
	ds_read_b128 v[60:63], v196 offset:0
	v_xor_b32_e32 v195, 128, v185
	ds_read_b128 v[64:67], v195 offset:0
	v_xor_b32_e32 v196, 160, v185
	ds_read_b128 v[68:71], v196 offset:0
	v_xor_b32_e32 v195, 192, v185
	ds_read_b128 v[72:75], v195 offset:0
	v_xor_b32_e32 v196, 224, v185
	ds_read_b128 v[76:79], v196 offset:0
	s_waitcnt lgkmcnt(7)
	v_mfma_f32_32x32x16_bf16 v[0:15], v[48:51], v[140:143], 0
	v_mfma_f32_32x32x16_bf16 v[16:31], v[48:51], v[204:207], 0
	s_waitcnt lgkmcnt(6)
	v_mfma_f32_32x32x16_bf16 v[0:15], v[52:55], v[144:147], v[0:15]
	v_mfma_f32_32x32x16_bf16 v[16:31], v[52:55], v[208:211], v[16:31]
	s_waitcnt lgkmcnt(5)
	v_mfma_f32_32x32x16_bf16 v[0:15], v[56:59], v[148:151], v[0:15]
	v_mfma_f32_32x32x16_bf16 v[16:31], v[56:59], v[212:215], v[16:31]
	s_waitcnt lgkmcnt(4)
	v_mfma_f32_32x32x16_bf16 v[0:15], v[60:63], v[152:155], v[0:15]
	v_mfma_f32_32x32x16_bf16 v[16:31], v[60:63], v[216:219], v[16:31]
	s_waitcnt lgkmcnt(3)
	v_mfma_f32_32x32x16_bf16 v[0:15], v[64:67], v[156:159], v[0:15]
	v_mfma_f32_32x32x16_bf16 v[16:31], v[64:67], v[220:223], v[16:31]
	s_waitcnt lgkmcnt(2)
	v_mfma_f32_32x32x16_bf16 v[0:15], v[68:71], v[160:163], v[0:15]
	v_mfma_f32_32x32x16_bf16 v[16:31], v[68:71], v[224:227], v[16:31]
	s_waitcnt lgkmcnt(1)
	v_mfma_f32_32x32x16_bf16 v[0:15], v[72:75], v[164:167], v[0:15]
	v_mfma_f32_32x32x16_bf16 v[16:31], v[72:75], v[228:231], v[16:31]
	s_waitcnt lgkmcnt(0)
	v_mfma_f32_32x32x16_bf16 v[0:15], v[76:79], v[168:171], v[0:15]
	v_mfma_f32_32x32x16_bf16 v[16:31], v[76:79], v[232:235], v[16:31]
	s_and_b32 s0, s27, 3
	s_cmp_eq_u32 s0, 0
	s_cbranch_scc0 .Llru2_id0_0
	v_mfma_f32_32x32x16_bf16 v[32:47], v[48:51], v[172:175], 0
	v_mfma_f32_32x32x16_bf16 v[32:47], v[52:55], v[176:179], v[32:47]
.Llru2_id0_0:
	s_cmp_eq_u32 s0, 1
	s_cbranch_scc0 .Llru2_id0_1
	v_mfma_f32_32x32x16_bf16 v[32:47], v[56:59], v[172:175], 0
	v_mfma_f32_32x32x16_bf16 v[32:47], v[60:63], v[176:179], v[32:47]
.Llru2_id0_1:
	s_cmp_eq_u32 s0, 2
	s_cbranch_scc0 .Llru2_id0_2
	v_mfma_f32_32x32x16_bf16 v[32:47], v[64:67], v[172:175], 0
	v_mfma_f32_32x32x16_bf16 v[32:47], v[68:71], v[176:179], v[32:47]
.Llru2_id0_2:
	s_cmp_eq_u32 s0, 3
	s_cbranch_scc0 .Llru2_id0_3
	v_mfma_f32_32x32x16_bf16 v[32:47], v[72:75], v[172:175], 0
	v_mfma_f32_32x32x16_bf16 v[32:47], v[76:79], v[176:179], v[32:47]
.Llru2_id0_3:
	s_nop 7
	s_nop 7
	v_mov_b32_e32 v80, v180
	v_fmac_f32_e32 v80, 0xbfb8aa3b, v0
	v_mov_b32_e32 v81, v181
	v_fmac_f32_e32 v81, 0xbfb8aa3b, v16
	v_exp_f32_e32 v80, v80
	v_exp_f32_e32 v81, v81
	v_add_f32_e32 v80, 1.0, v80
	v_add_f32_e32 v81, 1.0, v81
	v_rcp_f32_e32 v80, v80
	v_rcp_f32_e32 v81, v81
	s_nop 0
	v_mul_f32_e32 v80, v182, v80
	v_mul_f32_e32 v81, v81, v32
	v_exp_f32_e32 v80, v80
	s_nop 0
	v_fma_f32 v82, -v80, v80, 1.0
	v_max_f32_e32 v82, 0, v82
	v_sqrt_f32_e32 v82, v82
	ds_write_b32 v186, v80 offset:0
	v_mul_f32_e32 v82, v82, v81
	ds_write_b32 v187, v82 offset:0
	v_mov_b32_e32 v88, v180
	v_fmac_f32_e32 v88, 0xbfb8aa3b, v1
	v_mov_b32_e32 v89, v181
	v_fmac_f32_e32 v89, 0xbfb8aa3b, v17
	v_exp_f32_e32 v88, v88
	v_exp_f32_e32 v89, v89
	v_add_f32_e32 v88, 1.0, v88
	v_add_f32_e32 v89, 1.0, v89
	v_rcp_f32_e32 v88, v88
	v_rcp_f32_e32 v89, v89
	s_nop 0
	v_mul_f32_e32 v88, v182, v88
	v_mul_f32_e32 v89, v89, v33
	v_exp_f32_e32 v88, v88
	s_nop 0
	v_fma_f32 v90, -v88, v88, 1.0
	v_max_f32_e32 v90, 0, v90
	v_sqrt_f32_e32 v90, v90
	ds_write_b32 v186, v88 offset:512
	v_mul_f32_e32 v90, v90, v89
	ds_write_b32 v187, v90 offset:512
	v_mov_b32_e32 v80, v180
	v_fmac_f32_e32 v80, 0xbfb8aa3b, v2
	v_mov_b32_e32 v81, v181
	v_fmac_f32_e32 v81, 0xbfb8aa3b, v18
	v_exp_f32_e32 v80, v80
	v_exp_f32_e32 v81, v81
	v_add_f32_e32 v80, 1.0, v80
	v_add_f32_e32 v81, 1.0, v81
	v_rcp_f32_e32 v80, v80
	v_rcp_f32_e32 v81, v81
	s_nop 0
	v_mul_f32_e32 v80, v182, v80
	v_mul_f32_e32 v81, v81, v34
	v_exp_f32_e32 v80, v80
	s_nop 0
	v_fma_f32 v82, -v80, v80, 1.0
	v_max_f32_e32 v82, 0, v82
	v_sqrt_f32_e32 v82, v82
	ds_write_b32 v186, v80 offset:1024
	v_mul_f32_e32 v82, v82, v81
	ds_write_b32 v187, v82 offset:1024
	v_mov_b32_e32 v88, v180
	v_fmac_f32_e32 v88, 0xbfb8aa3b, v3
	v_mov_b32_e32 v89, v181
	v_fmac_f32_e32 v89, 0xbfb8aa3b, v19
	v_exp_f32_e32 v88, v88
	v_exp_f32_e32 v89, v89
	v_add_f32_e32 v88, 1.0, v88
	v_add_f32_e32 v89, 1.0, v89
	v_rcp_f32_e32 v88, v88
	v_rcp_f32_e32 v89, v89
	s_nop 0
	v_mul_f32_e32 v88, v182, v88
	v_mul_f32_e32 v89, v89, v35
	v_exp_f32_e32 v88, v88
	s_nop 0
	v_fma_f32 v90, -v88, v88, 1.0
	v_max_f32_e32 v90, 0, v90
	v_sqrt_f32_e32 v90, v90
	ds_write_b32 v186, v88 offset:1536
	v_mul_f32_e32 v90, v90, v89
	ds_write_b32 v187, v90 offset:1536
	v_mov_b32_e32 v80, v180
	v_fmac_f32_e32 v80, 0xbfb8aa3b, v4
	v_mov_b32_e32 v81, v181
	v_fmac_f32_e32 v81, 0xbfb8aa3b, v20
	v_exp_f32_e32 v80, v80
	v_exp_f32_e32 v81, v81
	v_add_f32_e32 v80, 1.0, v80
	v_add_f32_e32 v81, 1.0, v81
	v_rcp_f32_e32 v80, v80
	v_rcp_f32_e32 v81, v81
	s_nop 0
	v_mul_f32_e32 v80, v182, v80
	v_mul_f32_e32 v81, v81, v36
	v_exp_f32_e32 v80, v80
	s_nop 0
	v_fma_f32 v82, -v80, v80, 1.0
	v_max_f32_e32 v82, 0, v82
	v_sqrt_f32_e32 v82, v82
	ds_write_b32 v186, v80 offset:4096
	v_mul_f32_e32 v82, v82, v81
	ds_write_b32 v187, v82 offset:4096
	v_mov_b32_e32 v88, v180
	v_fmac_f32_e32 v88, 0xbfb8aa3b, v5
	v_mov_b32_e32 v89, v181
	v_fmac_f32_e32 v89, 0xbfb8aa3b, v21
	v_exp_f32_e32 v88, v88
	v_exp_f32_e32 v89, v89
	v_add_f32_e32 v88, 1.0, v88
	v_add_f32_e32 v89, 1.0, v89
	v_rcp_f32_e32 v88, v88
	v_rcp_f32_e32 v89, v89
	s_nop 0
; __device__ __forceinline__ float bf2f(u16 x) { return __uint_as_float(((unsigned)x) << 16); }
; __device__ __forceinline__ float fexp(float x) { return __builtin_amdgcn_exp2f(x * 1.4426950408889634f); }
; __device__ __forceinline__ int crow(int r, int hi) { return (r & 3) + 8 * (r >> 2) + 4 * hi; }
; template <int PASS>
; __device__ __forceinline__ void lru_tile_phase(const Params& p, int jl, int Mrows, char* smem, int tid, int bid) {
;     ...
;         for (int k16 = 0; k16 < 8; ++k16) af[k16] = *(const bf16x8*)(xcL + swz256(tb * 32 + l32, k16 * 2 + hi));
;     ...
;         for (int r = 0; r < 16; ++r) {
;           const int tok = tb * 32 + crow(r, hi);
;           const float xc = bf2f(*(const u16*)(xcL + swz256(tok, chl >> 3) + (chl & 7) * 2));
;           const float la = c_sp * __builtin_amdgcn_rcpf(1.f + fexp(-(acc0[r] + c_ba)));
;           const float ii = __builtin_amdgcn_rcpf(1.f + fexp(-(acc1[r] + c_bx)));
;           const float av = fexp(la);
;           aL[(dh * 64 + tok) * 128 + chl] = av;
;           uL[(dh * 64 + tok) * 128 + chl] = __builtin_amdgcn_sqrtf(fmaxf(1.f - av * av, 0.f)) * (ii * xc);
;         }
	v_mul_f32_e32 v88, v182, v88
	v_mul_f32_e32 v89, v89, v37
	v_exp_f32_e32 v88, v88
	s_nop 0
	v_fma_f32 v90, -v88, v88, 1.0
	v_max_f32_e32 v90, 0, v90
	v_sqrt_f32_e32 v90, v90
	ds_write_b32 v186, v88 offset:4608
	v_mul_f32_e32 v90, v90, v89
	ds_write_b32 v187, v90 offset:4608
	v_mov_b32_e32 v80, v180
	v_fmac_f32_e32 v80, 0xbfb8aa3b, v6
	v_mov_b32_e32 v81, v181
	v_fmac_f32_e32 v81, 0xbfb8aa3b, v22
	v_exp_f32_e32 v80, v80
	v_exp_f32_e32 v81, v81
	v_add_f32_e32 v80, 1.0, v80
	v_add_f32_e32 v81, 1.0, v81
	v_rcp_f32_e32 v80, v80
	v_rcp_f32_e32 v81, v81
	s_nop 0
	v_mul_f32_e32 v80, v182, v80
	v_mul_f32_e32 v81, v81, v38
	v_exp_f32_e32 v80, v80
	s_nop 0
	v_fma_f32 v82, -v80, v80, 1.0
	v_max_f32_e32 v82, 0, v82
	v_sqrt_f32_e32 v82, v82
	ds_write_b32 v186, v80 offset:5120
	v_mul_f32_e32 v82, v82, v81
	ds_write_b32 v187, v82 offset:5120
	v_mov_b32_e32 v88, v180
	v_fmac_f32_e32 v88, 0xbfb8aa3b, v7
	v_mov_b32_e32 v89, v181
	v_fmac_f32_e32 v89, 0xbfb8aa3b, v23
	v_exp_f32_e32 v88, v88
	v_exp_f32_e32 v89, v89
	v_add_f32_e32 v88, 1.0, v88
	v_add_f32_e32 v89, 1.0, v89
	v_rcp_f32_e32 v88, v88
	v_rcp_f32_e32 v89, v89
	s_nop 0
	v_mul_f32_e32 v88, v182, v88
	v_mul_f32_e32 v89, v89, v39
	v_exp_f32_e32 v88, v88
	s_nop 0
	v_fma_f32 v90, -v88, v88, 1.0
	v_max_f32_e32 v90, 0, v90
	v_sqrt_f32_e32 v90, v90
	ds_write_b32 v186, v88 offset:5632
	v_mul_f32_e32 v90, v90, v89
	ds_write_b32 v187, v90 offset:5632
	v_mov_b32_e32 v80, v180
	v_fmac_f32_e32 v80, 0xbfb8aa3b, v8
	v_mov_b32_e32 v81, v181
	v_fmac_f32_e32 v81, 0xbfb8aa3b, v24
	v_exp_f32_e32 v80, v80
	v_exp_f32_e32 v81, v81
	v_add_f32_e32 v80, 1.0, v80
	v_add_f32_e32 v81, 1.0, v81
	v_rcp_f32_e32 v80, v80
	v_rcp_f32_e32 v81, v81
	s_nop 0
	v_mul_f32_e32 v80, v182, v80
	v_mul_f32_e32 v81, v81, v40
	v_exp_f32_e32 v80, v80
	s_nop 0
	v_fma_f32 v82, -v80, v80, 1.0
	v_max_f32_e32 v82, 0, v82
	v_sqrt_f32_e32 v82, v82
	ds_write_b32 v186, v80 offset:8192
	v_mul_f32_e32 v82, v82, v81
	ds_write_b32 v187, v82 offset:8192
	v_mov_b32_e32 v88, v180
	v_fmac_f32_e32 v88, 0xbfb8aa3b, v9
	v_mov_b32_e32 v89, v181
	v_fmac_f32_e32 v89, 0xbfb8aa3b, v25
	v_exp_f32_e32 v88, v88
	v_exp_f32_e32 v89, v89
	v_add_f32_e32 v88, 1.0, v88
	v_add_f32_e32 v89, 1.0, v89
	v_rcp_f32_e32 v88, v88
	v_rcp_f32_e32 v89, v89
	s_nop 0
	v_mul_f32_e32 v88, v182, v88
	v_mul_f32_e32 v89, v89, v41
	v_exp_f32_e32 v88, v88
	s_nop 0
	v_fma_f32 v90, -v88, v88, 1.0
	v_max_f32_e32 v90, 0, v90
	v_sqrt_f32_e32 v90, v90
	ds_write_b32 v186, v88 offset:8704
	v_mul_f32_e32 v90, v90, v89
	ds_write_b32 v187, v90 offset:8704
	v_mov_b32_e32 v80, v180
	v_fmac_f32_e32 v80, 0xbfb8aa3b, v10
	v_mov_b32_e32 v81, v181
	v_fmac_f32_e32 v81, 0xbfb8aa3b, v26
	v_exp_f32_e32 v80, v80
	v_exp_f32_e32 v81, v81
	v_add_f32_e32 v80, 1.0, v80
	v_add_f32_e32 v81, 1.0, v81
	v_rcp_f32_e32 v80, v80
	v_rcp_f32_e32 v81, v81
	s_nop 0
	v_mul_f32_e32 v80, v182, v80
	v_mul_f32_e32 v81, v81, v42
	v_exp_f32_e32 v80, v80
	s_nop 0
	v_fma_f32 v82, -v80, v80, 1.0
	v_max_f32_e32 v82, 0, v82
	v_sqrt_f32_e32 v82, v82
	ds_write_b32 v186, v80 offset:9216
	v_mul_f32_e32 v82, v82, v81
	ds_write_b32 v187, v82 offset:9216
	v_mov_b32_e32 v88, v180
	v_fmac_f32_e32 v88, 0xbfb8aa3b, v11
	v_mov_b32_e32 v89, v181
	v_fmac_f32_e32 v89, 0xbfb8aa3b, v27
	v_exp_f32_e32 v88, v88
	v_exp_f32_e32 v89, v89
	v_add_f32_e32 v88, 1.0, v88
	v_add_f32_e32 v89, 1.0, v89
	v_rcp_f32_e32 v88, v88
	v_rcp_f32_e32 v89, v89
	s_nop 0
	v_mul_f32_e32 v88, v182, v88
	v_mul_f32_e32 v89, v89, v43
	v_exp_f32_e32 v88, v88
	s_nop 0
	v_fma_f32 v90, -v88, v88, 1.0
	v_max_f32_e32 v90, 0, v90
	v_sqrt_f32_e32 v90, v90
	ds_write_b32 v186, v88 offset:9728
	v_mul_f32_e32 v90, v90, v89
	ds_write_b32 v187, v90 offset:9728
	v_mov_b32_e32 v80, v180
	v_fmac_f32_e32 v80, 0xbfb8aa3b, v12
	v_mov_b32_e32 v81, v181
	v_fmac_f32_e32 v81, 0xbfb8aa3b, v28
	v_exp_f32_e32 v80, v80
	v_exp_f32_e32 v81, v81
	v_add_f32_e32 v80, 1.0, v80
	v_add_f32_e32 v81, 1.0, v81
	v_rcp_f32_e32 v80, v80
	v_rcp_f32_e32 v81, v81
	s_nop 0
	v_mul_f32_e32 v80, v182, v80
	v_mul_f32_e32 v81, v81, v44
	v_exp_f32_e32 v80, v80
	s_nop 0
	v_fma_f32 v82, -v80, v80, 1.0
	v_max_f32_e32 v82, 0, v82
	v_sqrt_f32_e32 v82, v82
	ds_write_b32 v186, v80 offset:12288
	v_mul_f32_e32 v82, v82, v81
	ds_write_b32 v187, v82 offset:12288
	v_mov_b32_e32 v88, v180
	v_fmac_f32_e32 v88, 0xbfb8aa3b, v13
	v_mov_b32_e32 v89, v181
	v_fmac_f32_e32 v89, 0xbfb8aa3b, v29
	v_exp_f32_e32 v88, v88
	v_exp_f32_e32 v89, v89
	v_add_f32_e32 v88, 1.0, v88
	v_add_f32_e32 v89, 1.0, v89
	v_rcp_f32_e32 v88, v88
	v_rcp_f32_e32 v89, v89
	s_nop 0
	v_mul_f32_e32 v88, v182, v88
	v_mul_f32_e32 v89, v89, v45
	v_exp_f32_e32 v88, v88
	s_nop 0
	v_fma_f32 v90, -v88, v88, 1.0
	v_max_f32_e32 v90, 0, v90
	v_sqrt_f32_e32 v90, v90
	ds_write_b32 v186, v88 offset:12800
	v_mul_f32_e32 v90, v90, v89
	ds_write_b32 v187, v90 offset:12800
	v_mov_b32_e32 v80, v180
	v_fmac_f32_e32 v80, 0xbfb8aa3b, v14
	v_mov_b32_e32 v81, v181
	v_fmac_f32_e32 v81, 0xbfb8aa3b, v30
	v_exp_f32_e32 v80, v80
	v_exp_f32_e32 v81, v81
	v_add_f32_e32 v80, 1.0, v80
	v_add_f32_e32 v81, 1.0, v81
	v_rcp_f32_e32 v80, v80
	v_rcp_f32_e32 v81, v81
	s_nop 0
	v_mul_f32_e32 v80, v182, v80
	v_mul_f32_e32 v81, v81, v46
	v_exp_f32_e32 v80, v80
	s_nop 0
	v_fma_f32 v82, -v80, v80, 1.0
	v_max_f32_e32 v82, 0, v82
	v_sqrt_f32_e32 v82, v82
	ds_write_b32 v186, v80 offset:13312
	v_mul_f32_e32 v82, v82, v81
	ds_write_b32 v187, v82 offset:13312
	v_mov_b32_e32 v88, v180
	v_fmac_f32_e32 v88, 0xbfb8aa3b, v15
	v_mov_b32_e32 v89, v181
	v_fmac_f32_e32 v89, 0xbfb8aa3b, v31
	v_exp_f32_e32 v88, v88
	v_exp_f32_e32 v89, v89
	v_add_f32_e32 v88, 1.0, v88
	v_add_f32_e32 v89, 1.0, v89
	v_rcp_f32_e32 v88, v88
	v_rcp_f32_e32 v89, v89
	s_nop 0
	v_mul_f32_e32 v88, v182, v88
	v_mul_f32_e32 v89, v89, v47
	v_exp_f32_e32 v88, v88
	s_nop 0
	v_fma_f32 v90, -v88, v88, 1.0
	v_max_f32_e32 v90, 0, v90
	v_sqrt_f32_e32 v90, v90
	ds_write_b32 v186, v88 offset:13824
	v_mul_f32_e32 v90, v90, v89
	ds_write_b32 v187, v90 offset:13824
	ds_read_b128 v[48:51], v185 offset:8192
	v_xor_b32_e32 v196, 32, v185
	ds_read_b128 v[52:55], v196 offset:8192
	v_xor_b32_e32 v195, 64, v185
	ds_read_b128 v[56:59], v195 offset:8192
	v_xor_b32_e32 v196, 96, v185
	ds_read_b128 v[60:63], v196 offset:8192
	v_xor_b32_e32 v195, 128, v185
	ds_read_b128 v[64:67], v195 offset:8192
	v_xor_b32_e32 v196, 160, v185
	ds_read_b128 v[68:71], v196 offset:8192
	v_xor_b32_e32 v195, 192, v185
	ds_read_b128 v[72:75], v195 offset:8192
	v_xor_b32_e32 v196, 224, v185
	ds_read_b128 v[76:79], v196 offset:8192
	s_waitcnt lgkmcnt(7)
; template <int PASS>
; __device__ __forceinline__ void lru_tile_phase(const Params& p, int jl, int Mrows, char* smem, int tid, int bid) {
;     ...
; #pragma unroll
;         for (int k16 = 0; k16 < 8; ++k16) {
;           acc0 = __builtin_amdgcn_mfma_f32_32x32x16_bf16(af[k16], wb0[k16], acc0, 0, 0, 0);
;           acc1 = __builtin_amdgcn_mfma_f32_32x32x16_bf16(af[k16], wb1[k16], acc1, 0, 0, 0);
;         }
	v_mfma_f32_32x32x16_bf16 v[0:15], v[48:51], v[140:143], 0
	v_mfma_f32_32x32x16_bf16 v[16:31], v[48:51], v[204:207], 0
	s_waitcnt lgkmcnt(6)
	v_mfma_f32_32x32x16_bf16 v[0:15], v[52:55], v[144:147], v[0:15]
	v_mfma_f32_32x32x16_bf16 v[16:31], v[52:55], v[208:211], v[16:31]
	s_waitcnt lgkmcnt(5)
	v_mfma_f32_32x32x16_bf16 v[0:15], v[56:59], v[148:151], v[0:15]
	v_mfma_f32_32x32x16_bf16 v[16:31], v[56:59], v[212:215], v[16:31]
	s_waitcnt lgkmcnt(4)
	v_mfma_f32_32x32x16_bf16 v[0:15], v[60:63], v[152:155], v[0:15]
	v_mfma_f32_32x32x16_bf16 v[16:31], v[60:63], v[216:219], v[16:31]
	s_waitcnt lgkmcnt(3)
	v_mfma_f32_32x32x16_bf16 v[0:15], v[64:67], v[156:159], v[0:15]
	v_mfma_f32_32x32x16_bf16 v[16:31], v[64:67], v[220:223], v[16:31]
	s_waitcnt lgkmcnt(2)
	v_mfma_f32_32x32x16_bf16 v[0:15], v[68:71], v[160:163], v[0:15]
	v_mfma_f32_32x32x16_bf16 v[16:31], v[68:71], v[224:227], v[16:31]
	s_waitcnt lgkmcnt(1)
	v_mfma_f32_32x32x16_bf16 v[0:15], v[72:75], v[164:167], v[0:15]
	v_mfma_f32_32x32x16_bf16 v[16:31], v[72:75], v[228:231], v[16:31]
	s_waitcnt lgkmcnt(0)
	v_mfma_f32_32x32x16_bf16 v[0:15], v[76:79], v[168:171], v[0:15]
	v_mfma_f32_32x32x16_bf16 v[16:31], v[76:79], v[232:235], v[16:31]
	s_and_b32 s0, s27, 3
	s_cmp_eq_u32 s0, 0
	s_cbranch_scc0 .Llru2_id1_0
	v_mfma_f32_32x32x16_bf16 v[32:47], v[48:51], v[172:175], 0
	v_mfma_f32_32x32x16_bf16 v[32:47], v[52:55], v[176:179], v[32:47]

; __device__ __forceinline__ float bf2f(u16 x) { return __uint_as_float(((unsigned)x) << 16); }
; __device__ __forceinline__ float fexp(float x) { return __builtin_amdgcn_exp2f(x * 1.4426950408889634f); }
; __device__ __forceinline__ int crow(int r, int hi) { return (r & 3) + 8 * (r >> 2) + 4 * hi; }
; template <int PASS>
; __device__ __forceinline__ void lru_tile_phase(const Params& p, int jl, int Mrows, char* smem, int tid, int bid) {
;     ...
;         for (int r = 0; r < 16; ++r) {
;           const int tok = tb * 32 + crow(r, hi);
;           const float xc = bf2f(*(const u16*)(xcL + swz256(tok, chl >> 3) + (chl & 7) * 2));
;           const float la = c_sp * __builtin_amdgcn_rcpf(1.f + fexp(-(acc0[r] + c_ba)));
;           const float ii = __builtin_amdgcn_rcpf(1.f + fexp(-(acc1[r] + c_bx)));
;           const float av = fexp(la);
;           aL[(dh * 64 + tok) * 128 + chl] = av;
;           uL[(dh * 64 + tok) * 128 + chl] = __builtin_amdgcn_sqrtf(fmaxf(1.f - av * av, 0.f)) * (ii * xc);
;         }
.Llru2_id1_3:
	s_nop 7
	s_nop 7
	v_mov_b32_e32 v80, v180
	v_fmac_f32_e32 v80, 0xbfb8aa3b, v0
	v_mov_b32_e32 v81, v181
	v_fmac_f32_e32 v81, 0xbfb8aa3b, v16
	v_exp_f32_e32 v80, v80
	v_exp_f32_e32 v81, v81
	v_add_f32_e32 v80, 1.0, v80
	v_add_f32_e32 v81, 1.0, v81
	v_rcp_f32_e32 v80, v80
	v_rcp_f32_e32 v81, v81
	s_nop 0
	v_mul_f32_e32 v80, v182, v80
	v_mul_f32_e32 v81, v81, v32
	v_exp_f32_e32 v80, v80
	s_nop 0
	v_fma_f32 v82, -v80, v80, 1.0
	v_max_f32_e32 v82, 0, v82
	v_sqrt_f32_e32 v82, v82
	ds_write_b32 v186, v80 offset:16384
	v_mul_f32_e32 v82, v82, v81
	ds_write_b32 v187, v82 offset:16384
	v_mov_b32_e32 v88, v180
	v_fmac_f32_e32 v88, 0xbfb8aa3b, v1
	v_mov_b32_e32 v89, v181
	v_fmac_f32_e32 v89, 0xbfb8aa3b, v17
	v_exp_f32_e32 v88, v88
	v_exp_f32_e32 v89, v89
	v_add_f32_e32 v88, 1.0, v88
	v_add_f32_e32 v89, 1.0, v89
	v_rcp_f32_e32 v88, v88
	v_rcp_f32_e32 v89, v89
	s_nop 0
	v_mul_f32_e32 v88, v182, v88
	v_mul_f32_e32 v89, v89, v33
	v_exp_f32_e32 v88, v88
	s_nop 0
	v_fma_f32 v90, -v88, v88, 1.0
	v_max_f32_e32 v90, 0, v90
	v_sqrt_f32_e32 v90, v90
	ds_write_b32 v186, v88 offset:16896
	v_mul_f32_e32 v90, v90, v89
	ds_write_b32 v187, v90 offset:16896
	v_mov_b32_e32 v80, v180
	v_fmac_f32_e32 v80, 0xbfb8aa3b, v2
	v_mov_b32_e32 v81, v181
	v_fmac_f32_e32 v81, 0xbfb8aa3b, v18
	v_exp_f32_e32 v80, v80
	v_exp_f32_e32 v81, v81
	v_add_f32_e32 v80, 1.0, v80
	v_add_f32_e32 v81, 1.0, v81
	v_rcp_f32_e32 v80, v80
	v_rcp_f32_e32 v81, v81
	s_nop 0
	v_mul_f32_e32 v80, v182, v80
	v_mul_f32_e32 v81, v81, v34
	v_exp_f32_e32 v80, v80
	s_nop 0
	v_fma_f32 v82, -v80, v80, 1.0
	v_max_f32_e32 v82, 0, v82
	v_sqrt_f32_e32 v82, v82
	ds_write_b32 v186, v80 offset:17408
	v_mul_f32_e32 v82, v82, v81
	ds_write_b32 v187, v82 offset:17408
	v_mov_b32_e32 v88, v180
	v_fmac_f32_e32 v88, 0xbfb8aa3b, v3
	v_mov_b32_e32 v89, v181
	v_fmac_f32_e32 v89, 0xbfb8aa3b, v19
	v_exp_f32_e32 v88, v88
	v_exp_f32_e32 v89, v89
	v_add_f32_e32 v88, 1.0, v88
	v_add_f32_e32 v89, 1.0, v89
	v_rcp_f32_e32 v88, v88
	v_rcp_f32_e32 v89, v89
	s_nop 0
	v_mul_f32_e32 v88, v182, v88
	v_mul_f32_e32 v89, v89, v35
	v_exp_f32_e32 v88, v88
	s_nop 0
	v_fma_f32 v90, -v88, v88, 1.0
	v_max_f32_e32 v90, 0, v90
	v_sqrt_f32_e32 v90, v90
	ds_write_b32 v186, v88 offset:17920
	v_mul_f32_e32 v90, v90, v89
	ds_write_b32 v187, v90 offset:17920
	v_mov_b32_e32 v80, v180
	v_fmac_f32_e32 v80, 0xbfb8aa3b, v4
	v_mov_b32_e32 v81, v181
	v_fmac_f32_e32 v81, 0xbfb8aa3b, v20
	v_exp_f32_e32 v80, v80
	v_exp_f32_e32 v81, v81
	v_add_f32_e32 v80, 1.0, v80
	v_add_f32_e32 v81, 1.0, v81
	v_rcp_f32_e32 v80, v80
	v_rcp_f32_e32 v81, v81
	s_nop 0
	v_mul_f32_e32 v80, v182, v80
	v_mul_f32_e32 v81, v81, v36
	v_exp_f32_e32 v80, v80
	s_nop 0
	v_fma_f32 v82, -v80, v80, 1.0
	v_max_f32_e32 v82, 0, v82
	v_sqrt_f32_e32 v82, v82
	ds_write_b32 v186, v80 offset:20480
	v_mul_f32_e32 v82, v82, v81
	ds_write_b32 v187, v82 offset:20480
	v_mov_b32_e32 v88, v180
	v_fmac_f32_e32 v88, 0xbfb8aa3b, v5
	v_mov_b32_e32 v89, v181
	v_fmac_f32_e32 v89, 0xbfb8aa3b, v21
	v_exp_f32_e32 v88, v88
	v_exp_f32_e32 v89, v89
	v_add_f32_e32 v88, 1.0, v88
	v_add_f32_e32 v89, 1.0, v89
	v_rcp_f32_e32 v88, v88
	v_rcp_f32_e32 v89, v89
	s_nop 0
	v_mul_f32_e32 v88, v182, v88
	v_mul_f32_e32 v89, v89, v37
	v_exp_f32_e32 v88, v88
	s_nop 0
	v_fma_f32 v90, -v88, v88, 1.0
	v_max_f32_e32 v90, 0, v90
	v_sqrt_f32_e32 v90, v90
	ds_write_b32 v186, v88 offset:20992
	v_mul_f32_e32 v90, v90, v89
	ds_write_b32 v187, v90 offset:20992
	v_mov_b32_e32 v80, v180
	v_fmac_f32_e32 v80, 0xbfb8aa3b, v6
	v_mov_b32_e32 v81, v181
	v_fmac_f32_e32 v81, 0xbfb8aa3b, v22
	v_exp_f32_e32 v80, v80
	v_exp_f32_e32 v81, v81
	v_add_f32_e32 v80, 1.0, v80
	v_add_f32_e32 v81, 1.0, v81
	v_rcp_f32_e32 v80, v80
	v_rcp_f32_e32 v81, v81
	s_nop 0
	v_mul_f32_e32 v80, v182, v80
	v_mul_f32_e32 v81, v81, v38
	v_exp_f32_e32 v80, v80
	s_nop 0
	v_fma_f32 v82, -v80, v80, 1.0
	v_max_f32_e32 v82, 0, v82
	v_sqrt_f32_e32 v82, v82
	ds_write_b32 v186, v80 offset:21504
	v_mul_f32_e32 v82, v82, v81
	ds_write_b32 v187, v82 offset:21504
	v_mov_b32_e32 v88, v180
	v_fmac_f32_e32 v88, 0xbfb8aa3b, v7
	v_mov_b32_e32 v89, v181
	v_fmac_f32_e32 v89, 0xbfb8aa3b, v23
	v_exp_f32_e32 v88, v88
	v_exp_f32_e32 v89, v89
	v_add_f32_e32 v88, 1.0, v88
	v_add_f32_e32 v89, 1.0, v89
	v_rcp_f32_e32 v88, v88
	v_rcp_f32_e32 v89, v89
	s_nop 0
	v_mul_f32_e32 v88, v182, v88
	v_mul_f32_e32 v89, v89, v39
	v_exp_f32_e32 v88, v88
	s_nop 0
	v_fma_f32 v90, -v88, v88, 1.0
	v_max_f32_e32 v90, 0, v90
	v_sqrt_f32_e32 v90, v90
	ds_write_b32 v186, v88 offset:22016
	v_mul_f32_e32 v90, v90, v89
	ds_write_b32 v187, v90 offset:22016
	v_mov_b32_e32 v80, v180
	v_fmac_f32_e32 v80, 0xbfb8aa3b, v8
	v_mov_b32_e32 v81, v181
	v_fmac_f32_e32 v81, 0xbfb8aa3b, v24
	v_exp_f32_e32 v80, v80
	v_exp_f32_e32 v81, v81
	v_add_f32_e32 v80, 1.0, v80
	v_add_f32_e32 v81, 1.0, v81
	v_rcp_f32_e32 v80, v80
	v_rcp_f32_e32 v81, v81
	s_nop 0
	v_mul_f32_e32 v80, v182, v80
	v_mul_f32_e32 v81, v81, v40
	v_exp_f32_e32 v80, v80
	s_nop 0
	v_fma_f32 v82, -v80, v80, 1.0
	v_max_f32_e32 v82, 0, v82
	v_sqrt_f32_e32 v82, v82
	ds_write_b32 v186, v80 offset:24576
	v_mul_f32_e32 v82, v82, v81
	ds_write_b32 v187, v82 offset:24576
	v_mov_b32_e32 v88, v180
	v_fmac_f32_e32 v88, 0xbfb8aa3b, v9
	v_mov_b32_e32 v89, v181
	v_fmac_f32_e32 v89, 0xbfb8aa3b, v25
	v_exp_f32_e32 v88, v88
	v_exp_f32_e32 v89, v89
	v_add_f32_e32 v88, 1.0, v88
	v_add_f32_e32 v89, 1.0, v89
	v_rcp_f32_e32 v88, v88
	v_rcp_f32_e32 v89, v89
	s_nop 0
	v_mul_f32_e32 v88, v182, v88
	v_mul_f32_e32 v89, v89, v41
	v_exp_f32_e32 v88, v88
	s_nop 0
	v_fma_f32 v90, -v88, v88, 1.0
	v_max_f32_e32 v90, 0, v90
	v_sqrt_f32_e32 v90, v90
	ds_write_b32 v186, v88 offset:25088
	v_mul_f32_e32 v90, v90, v89
; template <int PASS>
; __device__ __forceinline__ void lru_tile_phase(const Params& p, int jl, int Mrows, char* smem, int tid, int bid) {
;     ...
;     __syncthreads();
;     if (tid < 256) {
;       const int dir = tid >> 7, ch = tid & 127;
;       const size_t sidx = (size_t)(tt * 2 + dir) * 1024 + n * 128 + ch;
;       float hst = 0.f, ap = 1.f;
;       if (PASS == 2) hst = carry_in;
;       const float* ap_ = aL + (dir * 64) * 128 + ch;
;       float* up_ = uL + (dir * 64) * 128 + ch;
; #pragma unroll 1
;       for (int i0 = 0; i0 < 64; i0 += 16) {
;         float av[16], uv[16];
; #pragma unroll
;         for (int k = 0; k < 16; ++k) { const int t = dir ? 63 - (i0 + k) : i0 + k; av[k] = ap_[t * 128]; uv[k] = up_[t * 128]; }
; #pragma unroll
;         for (int k = 0; k < 16; ++k) { hst = fmaf(av[k], hst, uv[k]); if (PASS == 1) ap *= av[k]; else uv[k] = hst; }
;         if (PASS == 2) {
; #pragma unroll
;           for (int k = 0; k < 16; ++k) { const int t = dir ? 63 - (i0 + k) : i0 + k; up_[t * 128] = uv[k]; }
;         }
;       }
	ds_write_b32 v187, v90 offset:25088
	v_mov_b32_e32 v80, v180
	v_fmac_f32_e32 v80, 0xbfb8aa3b, v10
	v_mov_b32_e32 v81, v181
	v_fmac_f32_e32 v81, 0xbfb8aa3b, v26
	v_exp_f32_e32 v80, v80
	v_exp_f32_e32 v81, v81
	v_add_f32_e32 v80, 1.0, v80
	v_add_f32_e32 v81, 1.0, v81
	v_rcp_f32_e32 v80, v80
	v_rcp_f32_e32 v81, v81
	s_nop 0
	v_mul_f32_e32 v80, v182, v80
	v_mul_f32_e32 v81, v81, v42
	v_exp_f32_e32 v80, v80
	s_nop 0
	v_fma_f32 v82, -v80, v80, 1.0
	v_max_f32_e32 v82, 0, v82
	v_sqrt_f32_e32 v82, v82
	ds_write_b32 v186, v80 offset:25600
	v_mul_f32_e32 v82, v82, v81
	ds_write_b32 v187, v82 offset:25600
	v_mov_b32_e32 v88, v180
	v_fmac_f32_e32 v88, 0xbfb8aa3b, v11
	v_mov_b32_e32 v89, v181
	v_fmac_f32_e32 v89, 0xbfb8aa3b, v27
	v_exp_f32_e32 v88, v88
	v_exp_f32_e32 v89, v89
	v_add_f32_e32 v88, 1.0, v88
	v_add_f32_e32 v89, 1.0, v89
	v_rcp_f32_e32 v88, v88
	v_rcp_f32_e32 v89, v89
	s_nop 0
	v_mul_f32_e32 v88, v182, v88
	v_mul_f32_e32 v89, v89, v43
	v_exp_f32_e32 v88, v88
	s_nop 0
	v_fma_f32 v90, -v88, v88, 1.0
	v_max_f32_e32 v90, 0, v90
	v_sqrt_f32_e32 v90, v90
	ds_write_b32 v186, v88 offset:26112
	v_mul_f32_e32 v90, v90, v89
	ds_write_b32 v187, v90 offset:26112
	v_mov_b32_e32 v80, v180
	v_fmac_f32_e32 v80, 0xbfb8aa3b, v12
	v_mov_b32_e32 v81, v181
	v_fmac_f32_e32 v81, 0xbfb8aa3b, v28
	v_exp_f32_e32 v80, v80
	v_exp_f32_e32 v81, v81
	v_add_f32_e32 v80, 1.0, v80
	v_add_f32_e32 v81, 1.0, v81
	v_rcp_f32_e32 v80, v80
	v_rcp_f32_e32 v81, v81
	s_nop 0
	v_mul_f32_e32 v80, v182, v80
	v_mul_f32_e32 v81, v81, v44
	v_exp_f32_e32 v80, v80
	s_nop 0
	v_fma_f32 v82, -v80, v80, 1.0
	v_max_f32_e32 v82, 0, v82
	v_sqrt_f32_e32 v82, v82
	ds_write_b32 v186, v80 offset:28672
	v_mul_f32_e32 v82, v82, v81
	ds_write_b32 v187, v82 offset:28672
	v_mov_b32_e32 v88, v180
	v_fmac_f32_e32 v88, 0xbfb8aa3b, v13
	v_mov_b32_e32 v89, v181
	v_fmac_f32_e32 v89, 0xbfb8aa3b, v29
	v_exp_f32_e32 v88, v88
	v_exp_f32_e32 v89, v89
	v_add_f32_e32 v88, 1.0, v88
	v_add_f32_e32 v89, 1.0, v89
	v_rcp_f32_e32 v88, v88
	v_rcp_f32_e32 v89, v89
	s_nop 0
	v_mul_f32_e32 v88, v182, v88
	v_mul_f32_e32 v89, v89, v45
	v_exp_f32_e32 v88, v88
	s_nop 0
	v_fma_f32 v90, -v88, v88, 1.0
	v_max_f32_e32 v90, 0, v90
	v_sqrt_f32_e32 v90, v90
	ds_write_b32 v186, v88 offset:29184
	v_mul_f32_e32 v90, v90, v89
	ds_write_b32 v187, v90 offset:29184
	v_mov_b32_e32 v80, v180
	v_fmac_f32_e32 v80, 0xbfb8aa3b, v14
	v_mov_b32_e32 v81, v181
	v_fmac_f32_e32 v81, 0xbfb8aa3b, v30
	v_exp_f32_e32 v80, v80
	v_exp_f32_e32 v81, v81
	v_add_f32_e32 v80, 1.0, v80
	v_add_f32_e32 v81, 1.0, v81
	v_rcp_f32_e32 v80, v80
	v_rcp_f32_e32 v81, v81
	s_nop 0
	v_mul_f32_e32 v80, v182, v80
	v_mul_f32_e32 v81, v81, v46
	v_exp_f32_e32 v80, v80
	s_nop 0
	v_fma_f32 v82, -v80, v80, 1.0
	v_max_f32_e32 v82, 0, v82
	v_sqrt_f32_e32 v82, v82
	ds_write_b32 v186, v80 offset:29696
	v_mul_f32_e32 v82, v82, v81
	ds_write_b32 v187, v82 offset:29696
	v_mov_b32_e32 v88, v180
	v_fmac_f32_e32 v88, 0xbfb8aa3b, v15
	v_mov_b32_e32 v89, v181
	v_fmac_f32_e32 v89, 0xbfb8aa3b, v31
	v_exp_f32_e32 v88, v88
	v_exp_f32_e32 v89, v89
	v_add_f32_e32 v88, 1.0, v88
	v_add_f32_e32 v89, 1.0, v89
	v_rcp_f32_e32 v88, v88
	v_rcp_f32_e32 v89, v89
	s_nop 0
	v_mul_f32_e32 v88, v182, v88
	v_mul_f32_e32 v89, v89, v47
	v_exp_f32_e32 v88, v88
	s_nop 0
	v_fma_f32 v90, -v88, v88, 1.0
	v_max_f32_e32 v90, 0, v90
	v_sqrt_f32_e32 v90, v90
	ds_write_b32 v186, v88 offset:30208
	v_mul_f32_e32 v90, v90, v89
	ds_write_b32 v187, v90 offset:30208
	s_waitcnt lgkmcnt(0)
	s_barrier
	s_cmp_gt_u32 s27, 3
	s_cbranch_scc1 .Llru2_scan_done
	s_waitcnt vmcnt(0)
	v_mov_b32_e32 v96, v252
	v_add_u32_e32 v195, 0x10000, v188
	s_cmp_gt_u32 s27, 1
	s_cbranch_scc1 .Llru2_scan_bwd
	ds_read2st64_b32 v[0:1], v188 offset0:0 offset1:2
	ds_read2st64_b32 v[2:3], v188 offset0:4 offset1:6
	ds_read2st64_b32 v[4:5], v188 offset0:8 offset1:10
	ds_read2st64_b32 v[6:7], v188 offset0:12 offset1:14
	ds_read2st64_b32 v[8:9], v195 offset0:0 offset1:2
	ds_read2st64_b32 v[10:11], v195 offset0:4 offset1:6
	ds_read2st64_b32 v[12:13], v195 offset0:8 offset1:10
	ds_read2st64_b32 v[14:15], v195 offset0:12 offset1:14
	s_waitcnt lgkmcnt(0)
	ds_read2st64_b32 v[16:17], v188 offset0:16 offset1:18
	ds_read2st64_b32 v[18:19], v188 offset0:20 offset1:22
	ds_read2st64_b32 v[20:21], v188 offset0:24 offset1:26
	ds_read2st64_b32 v[22:23], v188 offset0:28 offset1:30
	ds_read2st64_b32 v[24:25], v195 offset0:16 offset1:18
	ds_read2st64_b32 v[26:27], v195 offset0:20 offset1:22
	ds_read2st64_b32 v[28:29], v195 offset0:24 offset1:26
	ds_read2st64_b32 v[30:31], v195 offset0:28 offset1:30
	v_fma_f32 v96, v0, v96, v8
	v_mov_b32_e32 v32, v96
	v_fma_f32 v96, v1, v96, v9
	v_mov_b32_e32 v33, v96
	v_fma_f32 v96, v2, v96, v10
	v_mov_b32_e32 v34, v96
	v_fma_f32 v96, v3, v96, v11
	v_mov_b32_e32 v35, v96
	v_fma_f32 v96, v4, v96, v12
	v_mov_b32_e32 v36, v96
	v_fma_f32 v96, v5, v96, v13
	v_mov_b32_e32 v37, v96
	v_fma_f32 v96, v6, v96, v14
	v_mov_b32_e32 v38, v96
	v_fma_f32 v96, v7, v96, v15
	v_mov_b32_e32 v39, v96
	ds_write2st64_b32 v195, v32, v33 offset0:0 offset1:2
	ds_write2st64_b32 v195, v34, v35 offset0:4 offset1:6
	ds_write2st64_b32 v195, v36, v37 offset0:8 offset1:10
	ds_write2st64_b32 v195, v38, v39 offset0:12 offset1:14
	s_waitcnt lgkmcnt(0)
; template <int PASS>
; __device__ __forceinline__ void lru_tile_phase(const Params& p, int jl, int Mrows, char* smem, int tid, int bid) {
;     ...
;       for (int i0 = 0; i0 < 64; i0 += 16) {
;         float av[16], uv[16];
; #pragma unroll
;         for (int k = 0; k < 16; ++k) { const int t = dir ? 63 - (i0 + k) : i0 + k; av[k] = ap_[t * 128]; uv[k] = up_[t * 128]; }
; #pragma unroll
;         for (int k = 0; k < 16; ++k) { hst = fmaf(av[k], hst, uv[k]); if (PASS == 1) ap *= av[k]; else uv[k] = hst; }
;         if (PASS == 2) {
; #pragma unroll
;           for (int k = 0; k < 16; ++k) { const int t = dir ? 63 - (i0 + k) : i0 + k; up_[t * 128] = uv[k]; }
;         }
	ds_read2st64_b32 v[0:1], v188 offset0:32 offset1:34
	ds_read2st64_b32 v[2:3], v188 offset0:36 offset1:38
	ds_read2st64_b32 v[4:5], v188 offset0:40 offset1:42
	ds_read2st64_b32 v[6:7], v188 offset0:44 offset1:46
	ds_read2st64_b32 v[8:9], v195 offset0:32 offset1:34
	ds_read2st64_b32 v[10:11], v195 offset0:36 offset1:38
	ds_read2st64_b32 v[12:13], v195 offset0:40 offset1:42
	ds_read2st64_b32 v[14:15], v195 offset0:44 offset1:46
	v_fma_f32 v96, v16, v96, v24
	v_mov_b32_e32 v32, v96
	v_fma_f32 v96, v17, v96, v25
	v_mov_b32_e32 v33, v96
	v_fma_f32 v96, v18, v96, v26
	v_mov_b32_e32 v34, v96
	v_fma_f32 v96, v19, v96, v27
	v_mov_b32_e32 v35, v96
	v_fma_f32 v96, v20, v96, v28
	v_mov_b32_e32 v36, v96
	v_fma_f32 v96, v21, v96, v29
	v_mov_b32_e32 v37, v96
	v_fma_f32 v96, v22, v96, v30
	v_mov_b32_e32 v38, v96
	v_fma_f32 v96, v23, v96, v31
	v_mov_b32_e32 v39, v96
	ds_write2st64_b32 v195, v32, v33 offset0:16 offset1:18
	ds_write2st64_b32 v195, v34, v35 offset0:20 offset1:22
	ds_write2st64_b32 v195, v36, v37 offset0:24 offset1:26
	ds_write2st64_b32 v195, v38, v39 offset0:28 offset1:30
	s_waitcnt lgkmcnt(0)
	ds_read2st64_b32 v[16:17], v188 offset0:48 offset1:50
	ds_read2st64_b32 v[18:19], v188 offset0:52 offset1:54
	ds_read2st64_b32 v[20:21], v188 offset0:56 offset1:58
	ds_read2st64_b32 v[22:23], v188 offset0:60 offset1:62
	ds_read2st64_b32 v[24:25], v195 offset0:48 offset1:50
	ds_read2st64_b32 v[26:27], v195 offset0:52 offset1:54
	ds_read2st64_b32 v[28:29], v195 offset0:56 offset1:58
	ds_read2st64_b32 v[30:31], v195 offset0:60 offset1:62
	v_fma_f32 v96, v0, v96, v8
	v_mov_b32_e32 v32, v96
	v_fma_f32 v96, v1, v96, v9
	v_mov_b32_e32 v33, v96
	v_fma_f32 v96, v2, v96, v10
	v_mov_b32_e32 v34, v96
	v_fma_f32 v96, v3, v96, v11
	v_mov_b32_e32 v35, v96
	v_fma_f32 v96, v4, v96, v12
	v_mov_b32_e32 v36, v96
	v_fma_f32 v96, v5, v96, v13
	v_mov_b32_e32 v37, v96
	v_fma_f32 v96, v6, v96, v14
	v_mov_b32_e32 v38, v96
	v_fma_f32 v96, v7, v96, v15
	v_mov_b32_e32 v39, v96
	ds_write2st64_b32 v195, v32, v33 offset0:32 offset1:34
	ds_write2st64_b32 v195, v34, v35 offset0:36 offset1:38
	ds_write2st64_b32 v195, v36, v37 offset0:40 offset1:42
	ds_write2st64_b32 v195, v38, v39 offset0:44 offset1:46
	s_waitcnt lgkmcnt(0)
	ds_read2st64_b32 v[0:1], v188 offset0:64 offset1:66
	ds_read2st64_b32 v[2:3], v188 offset0:68 offset1:70
	ds_read2st64_b32 v[4:5], v188 offset0:72 offset1:74
	ds_read2st64_b32 v[6:7], v188 offset0:76 offset1:78
	ds_read2st64_b32 v[8:9], v195 offset0:64 offset1:66
	ds_read2st64_b32 v[10:11], v195 offset0:68 offset1:70
	ds_read2st64_b32 v[12:13], v195 offset0:72 offset1:74
	ds_read2st64_b32 v[14:15], v195 offset0:76 offset1:78
	v_fma_f32 v96, v16, v96, v24
	v_mov_b32_e32 v32, v96
	v_fma_f32 v96, v17, v96, v25
	v_mov_b32_e32 v33, v96
	v_fma_f32 v96, v18, v96, v26
	v_mov_b32_e32 v34, v96
	v_fma_f32 v96, v19, v96, v27
	v_mov_b32_e32 v35, v96
	v_fma_f32 v96, v20, v96, v28
	v_mov_b32_e32 v36, v96
	v_fma_f32 v96, v21, v96, v29
	v_mov_b32_e32 v37, v96
	v_fma_f32 v96, v22, v96, v30
	v_mov_b32_e32 v38, v96
	v_fma_f32 v96, v23, v96, v31
	v_mov_b32_e32 v39, v96
	ds_write2st64_b32 v195, v32, v33 offset0:48 offset1:50
	ds_write2st64_b32 v195, v34, v35 offset0:52 offset1:54
	ds_write2st64_b32 v195, v36, v37 offset0:56 offset1:58
	ds_write2st64_b32 v195, v38, v39 offset0:60 offset1:62
	s_waitcnt lgkmcnt(0)
	ds_read2st64_b32 v[16:17], v188 offset0:80 offset1:82
	ds_read2st64_b32 v[18:19], v188 offset0:84 offset1:86
	ds_read2st64_b32 v[20:21], v188 offset0:88 offset1:90
	ds_read2st64_b32 v[22:23], v188 offset0:92 offset1:94
	ds_read2st64_b32 v[24:25], v195 offset0:80 offset1:82
	ds_read2st64_b32 v[26:27], v195 offset0:84 offset1:86
	ds_read2st64_b32 v[28:29], v195 offset0:88 offset1:90
	ds_read2st64_b32 v[30:31], v195 offset0:92 offset1:94
	v_fma_f32 v96, v0, v96, v8
	v_mov_b32_e32 v32, v96
	v_fma_f32 v96, v1, v96, v9
	v_mov_b32_e32 v33, v96
	v_fma_f32 v96, v2, v96, v10
	v_mov_b32_e32 v34, v96
	v_fma_f32 v96, v3, v96, v11
	v_mov_b32_e32 v35, v96
	v_fma_f32 v96, v4, v96, v12
	v_mov_b32_e32 v36, v96
	v_fma_f32 v96, v5, v96, v13
	v_mov_b32_e32 v37, v96
	v_fma_f32 v96, v6, v96, v14
	v_mov_b32_e32 v38, v96
	v_fma_f32 v96, v7, v96, v15
	v_mov_b32_e32 v39, v96
	ds_write2st64_b32 v195, v32, v33 offset0:64 offset1:66
	ds_write2st64_b32 v195, v34, v35 offset0:68 offset1:70
	ds_write2st64_b32 v195, v36, v37 offset0:72 offset1:74
	ds_write2st64_b32 v195, v38, v39 offset0:76 offset1:78
	s_waitcnt lgkmcnt(0)
	ds_read2st64_b32 v[0:1], v188 offset0:96 offset1:98
	ds_read2st64_b32 v[2:3], v188 offset0:100 offset1:102
	ds_read2st64_b32 v[4:5], v188 offset0:104 offset1:106
	ds_read2st64_b32 v[6:7], v188 offset0:108 offset1:110
	ds_read2st64_b32 v[8:9], v195 offset0:96 offset1:98
	ds_read2st64_b32 v[10:11], v195 offset0:100 offset1:102
	ds_read2st64_b32 v[12:13], v195 offset0:104 offset1:106
	ds_read2st64_b32 v[14:15], v195 offset0:108 offset1:110
	v_fma_f32 v96, v16, v96, v24
	v_mov_b32_e32 v32, v96
	v_fma_f32 v96, v17, v96, v25
	v_mov_b32_e32 v33, v96
	v_fma_f32 v96, v18, v96, v26
	v_mov_b32_e32 v34, v96
	v_fma_f32 v96, v19, v96, v27
	v_mov_b32_e32 v35, v96
	v_fma_f32 v96, v20, v96, v28
	v_mov_b32_e32 v36, v96
	v_fma_f32 v96, v21, v96, v29
	v_mov_b32_e32 v37, v96
	v_fma_f32 v96, v22, v96, v30
	v_mov_b32_e32 v38, v96
	v_fma_f32 v96, v23, v96, v31
	v_mov_b32_e32 v39, v96
	ds_write2st64_b32 v195, v32, v33 offset0:80 offset1:82
	ds_write2st64_b32 v195, v34, v35 offset0:84 offset1:86
	ds_write2st64_b32 v195, v36, v37 offset0:88 offset1:90
	ds_write2st64_b32 v195, v38, v39 offset0:92 offset1:94
	s_waitcnt lgkmcnt(0)
; template <int PASS>
; __device__ __forceinline__ void lru_tile_phase(const Params& p, int jl, int Mrows, char* smem, int tid, int bid) {
;     ...
;       const float* ap_ = aL + (dir * 64) * 128 + ch;
;       float* up_ = uL + (dir * 64) * 128 + ch;
; #pragma unroll 1
;       for (int i0 = 0; i0 < 64; i0 += 16) {
;         float av[16], uv[16];
; #pragma unroll
;         for (int k = 0; k < 16; ++k) { const int t = dir ? 63 - (i0 + k) : i0 + k; av[k] = ap_[t * 128]; uv[k] = up_[t * 128]; }
; #pragma unroll
;         for (int k = 0; k < 16; ++k) { hst = fmaf(av[k], hst, uv[k]); if (PASS == 1) ap *= av[k]; else uv[k] = hst; }
;         if (PASS == 2) {
; #pragma unroll
;           for (int k = 0; k < 16; ++k) { const int t = dir ? 63 - (i0 + k) : i0 + k; up_[t * 128] = uv[k]; }
;         }
	ds_read2st64_b32 v[16:17], v188 offset0:112 offset1:114
	ds_read2st64_b32 v[18:19], v188 offset0:116 offset1:118
	ds_read2st64_b32 v[20:21], v188 offset0:120 offset1:122
	ds_read2st64_b32 v[22:23], v188 offset0:124 offset1:126
	ds_read2st64_b32 v[24:25], v195 offset0:112 offset1:114
	ds_read2st64_b32 v[26:27], v195 offset0:116 offset1:118
	ds_read2st64_b32 v[28:29], v195 offset0:120 offset1:122
	ds_read2st64_b32 v[30:31], v195 offset0:124 offset1:126
	v_fma_f32 v96, v0, v96, v8
	v_mov_b32_e32 v32, v96
	v_fma_f32 v96, v1, v96, v9
	v_mov_b32_e32 v33, v96
	v_fma_f32 v96, v2, v96, v10
	v_mov_b32_e32 v34, v96
	v_fma_f32 v96, v3, v96, v11
	v_mov_b32_e32 v35, v96
	v_fma_f32 v96, v4, v96, v12
	v_mov_b32_e32 v36, v96
	v_fma_f32 v96, v5, v96, v13
	v_mov_b32_e32 v37, v96
	v_fma_f32 v96, v6, v96, v14
	v_mov_b32_e32 v38, v96
	v_fma_f32 v96, v7, v96, v15
	v_mov_b32_e32 v39, v96
	ds_write2st64_b32 v195, v32, v33 offset0:96 offset1:98
	ds_write2st64_b32 v195, v34, v35 offset0:100 offset1:102
	ds_write2st64_b32 v195, v36, v37 offset0:104 offset1:106
	ds_write2st64_b32 v195, v38, v39 offset0:108 offset1:110
	s_waitcnt lgkmcnt(0)
	v_fma_f32 v96, v16, v96, v24
	v_mov_b32_e32 v32, v96
	v_fma_f32 v96, v17, v96, v25
	v_mov_b32_e32 v33, v96
	v_fma_f32 v96, v18, v96, v26
	v_mov_b32_e32 v34, v96
	v_fma_f32 v96, v19, v96, v27
	v_mov_b32_e32 v35, v96
	v_fma_f32 v96, v20, v96, v28
	v_mov_b32_e32 v36, v96
	v_fma_f32 v96, v21, v96, v29
	v_mov_b32_e32 v37, v96
	v_fma_f32 v96, v22, v96, v30
	v_mov_b32_e32 v38, v96
	v_fma_f32 v96, v23, v96, v31
	v_mov_b32_e32 v39, v96
	ds_write2st64_b32 v195, v32, v33 offset0:112 offset1:114
	ds_write2st64_b32 v195, v34, v35 offset0:116 offset1:118
	ds_write2st64_b32 v195, v36, v37 offset0:120 offset1:122
	ds_write2st64_b32 v195, v38, v39 offset0:124 offset1:126
	s_branch .Llru2_scan_store
.Llru2_scan_bwd:
	ds_read2st64_b32 v[0:1], v188 offset0:126 offset1:124
	ds_read2st64_b32 v[2:3], v188 offset0:122 offset1:120
	ds_read2st64_b32 v[4:5], v188 offset0:118 offset1:116
	ds_read2st64_b32 v[6:7], v188 offset0:114 offset1:112
	ds_read2st64_b32 v[8:9], v195 offset0:126 offset1:124
	ds_read2st64_b32 v[10:11], v195 offset0:122 offset1:120
	ds_read2st64_b32 v[12:13], v195 offset0:118 offset1:116
	ds_read2st64_b32 v[14:15], v195 offset0:114 offset1:112
	s_waitcnt lgkmcnt(0)
	ds_read2st64_b32 v[16:17], v188 offset0:110 offset1:108
	ds_read2st64_b32 v[18:19], v188 offset0:106 offset1:104
	ds_read2st64_b32 v[20:21], v188 offset0:102 offset1:100
	ds_read2st64_b32 v[22:23], v188 offset0:98 offset1:96
	ds_read2st64_b32 v[24:25], v195 offset0:110 offset1:108
	ds_read2st64_b32 v[26:27], v195 offset0:106 offset1:104
	ds_read2st64_b32 v[28:29], v195 offset0:102 offset1:100
	ds_read2st64_b32 v[30:31], v195 offset0:98 offset1:96
	v_fma_f32 v96, v0, v96, v8
	v_mov_b32_e32 v32, v96
	v_fma_f32 v96, v1, v96, v9
	v_mov_b32_e32 v33, v96
	v_fma_f32 v96, v2, v96, v10
	v_mov_b32_e32 v34, v96
	v_fma_f32 v96, v3, v96, v11
	v_mov_b32_e32 v35, v96
	v_fma_f32 v96, v4, v96, v12
	v_mov_b32_e32 v36, v96
	v_fma_f32 v96, v5, v96, v13
	v_mov_b32_e32 v37, v96
	v_fma_f32 v96, v6, v96, v14
	v_mov_b32_e32 v38, v96
	v_fma_f32 v96, v7, v96, v15
	v_mov_b32_e32 v39, v96
	ds_write2st64_b32 v195, v32, v33 offset0:126 offset1:124
	ds_write2st64_b32 v195, v34, v35 offset0:122 offset1:120
	ds_write2st64_b32 v195, v36, v37 offset0:118 offset1:116
	ds_write2st64_b32 v195, v38, v39 offset0:114 offset1:112
	s_waitcnt lgkmcnt(0)
	ds_read2st64_b32 v[0:1], v188 offset0:94 offset1:92
	ds_read2st64_b32 v[2:3], v188 offset0:90 offset1:88
	ds_read2st64_b32 v[4:5], v188 offset0:86 offset1:84
	ds_read2st64_b32 v[6:7], v188 offset0:82 offset1:80
	ds_read2st64_b32 v[8:9], v195 offset0:94 offset1:92
	ds_read2st64_b32 v[10:11], v195 offset0:90 offset1:88
	ds_read2st64_b32 v[12:13], v195 offset0:86 offset1:84
	ds_read2st64_b32 v[14:15], v195 offset0:82 offset1:80
	v_fma_f32 v96, v16, v96, v24
	v_mov_b32_e32 v32, v96
	v_fma_f32 v96, v17, v96, v25
	v_mov_b32_e32 v33, v96
	v_fma_f32 v96, v18, v96, v26
	v_mov_b32_e32 v34, v96
	v_fma_f32 v96, v19, v96, v27
	v_mov_b32_e32 v35, v96
	v_fma_f32 v96, v20, v96, v28
	v_mov_b32_e32 v36, v96
	v_fma_f32 v96, v21, v96, v29
	v_mov_b32_e32 v37, v96
	v_fma_f32 v96, v22, v96, v30
	v_mov_b32_e32 v38, v96
	v_fma_f32 v96, v23, v96, v31
	v_mov_b32_e32 v39, v96
	ds_write2st64_b32 v195, v32, v33 offset0:110 offset1:108
	ds_write2st64_b32 v195, v34, v35 offset0:106 offset1:104
	ds_write2st64_b32 v195, v36, v37 offset0:102 offset1:100
	ds_write2st64_b32 v195, v38, v39 offset0:98 offset1:96
	s_waitcnt lgkmcnt(0)
	ds_read2st64_b32 v[16:17], v188 offset0:78 offset1:76
	ds_read2st64_b32 v[18:19], v188 offset0:74 offset1:72
	ds_read2st64_b32 v[20:21], v188 offset0:70 offset1:68
	ds_read2st64_b32 v[22:23], v188 offset0:66 offset1:64
	ds_read2st64_b32 v[24:25], v195 offset0:78 offset1:76
	ds_read2st64_b32 v[26:27], v195 offset0:74 offset1:72
	ds_read2st64_b32 v[28:29], v195 offset0:70 offset1:68
	ds_read2st64_b32 v[30:31], v195 offset0:66 offset1:64
	v_fma_f32 v96, v0, v96, v8
	v_mov_b32_e32 v32, v96
	v_fma_f32 v96, v1, v96, v9
	v_mov_b32_e32 v33, v96
	v_fma_f32 v96, v2, v96, v10
	v_mov_b32_e32 v34, v96
	v_fma_f32 v96, v3, v96, v11
	v_mov_b32_e32 v35, v96
	v_fma_f32 v96, v4, v96, v12
	v_mov_b32_e32 v36, v96
	v_fma_f32 v96, v5, v96, v13
	v_mov_b32_e32 v37, v96
	v_fma_f32 v96, v6, v96, v14
	v_mov_b32_e32 v38, v96
	v_fma_f32 v96, v7, v96, v15
	v_mov_b32_e32 v39, v96
	ds_write2st64_b32 v195, v32, v33 offset0:94 offset1:92
	ds_write2st64_b32 v195, v34, v35 offset0:90 offset1:88
	ds_write2st64_b32 v195, v36, v37 offset0:86 offset1:84
	ds_write2st64_b32 v195, v38, v39 offset0:82 offset1:80
	s_waitcnt lgkmcnt(0)
; template <int PASS>
; __device__ __forceinline__ void lru_tile_phase(const Params& p, int jl, int Mrows, char* smem, int tid, int bid) {
;     ...
;       const float* ap_ = aL + (dir * 64) * 128 + ch;
;       float* up_ = uL + (dir * 64) * 128 + ch;
; #pragma unroll 1
;       for (int i0 = 0; i0 < 64; i0 += 16) {
;         float av[16], uv[16];
; #pragma unroll
;         for (int k = 0; k < 16; ++k) { const int t = dir ? 63 - (i0 + k) : i0 + k; av[k] = ap_[t * 128]; uv[k] = up_[t * 128]; }
; #pragma unroll
;         for (int k = 0; k < 16; ++k) { hst = fmaf(av[k], hst, uv[k]); if (PASS == 1) ap *= av[k]; else uv[k] = hst; }
;         if (PASS == 2) {
; #pragma unroll
;           for (int k = 0; k < 16; ++k) { const int t = dir ? 63 - (i0 + k) : i0 + k; up_[t * 128] = uv[k]; }
;         }
	ds_read2st64_b32 v[0:1], v188 offset0:62 offset1:60
	ds_read2st64_b32 v[2:3], v188 offset0:58 offset1:56
	ds_read2st64_b32 v[4:5], v188 offset0:54 offset1:52
	ds_read2st64_b32 v[6:7], v188 offset0:50 offset1:48
	ds_read2st64_b32 v[8:9], v195 offset0:62 offset1:60
	ds_read2st64_b32 v[10:11], v195 offset0:58 offset1:56
	ds_read2st64_b32 v[12:13], v195 offset0:54 offset1:52
	ds_read2st64_b32 v[14:15], v195 offset0:50 offset1:48
	v_fma_f32 v96, v16, v96, v24
	v_mov_b32_e32 v32, v96
	v_fma_f32 v96, v17, v96, v25
	v_mov_b32_e32 v33, v96
	v_fma_f32 v96, v18, v96, v26
	v_mov_b32_e32 v34, v96
	v_fma_f32 v96, v19, v96, v27
	v_mov_b32_e32 v35, v96
	v_fma_f32 v96, v20, v96, v28
	v_mov_b32_e32 v36, v96
	v_fma_f32 v96, v21, v96, v29
	v_mov_b32_e32 v37, v96
	v_fma_f32 v96, v22, v96, v30
	v_mov_b32_e32 v38, v96
	v_fma_f32 v96, v23, v96, v31
	v_mov_b32_e32 v39, v96
	ds_write2st64_b32 v195, v32, v33 offset0:78 offset1:76
	ds_write2st64_b32 v195, v34, v35 offset0:74 offset1:72
	ds_write2st64_b32 v195, v36, v37 offset0:70 offset1:68
	ds_write2st64_b32 v195, v38, v39 offset0:66 offset1:64
	s_waitcnt lgkmcnt(0)
	ds_read2st64_b32 v[16:17], v188 offset0:46 offset1:44
	ds_read2st64_b32 v[18:19], v188 offset0:42 offset1:40
	ds_read2st64_b32 v[20:21], v188 offset0:38 offset1:36
	ds_read2st64_b32 v[22:23], v188 offset0:34 offset1:32
	ds_read2st64_b32 v[24:25], v195 offset0:46 offset1:44
	ds_read2st64_b32 v[26:27], v195 offset0:42 offset1:40
	ds_read2st64_b32 v[28:29], v195 offset0:38 offset1:36
	ds_read2st64_b32 v[30:31], v195 offset0:34 offset1:32
	v_fma_f32 v96, v0, v96, v8
	v_mov_b32_e32 v32, v96
	v_fma_f32 v96, v1, v96, v9
	v_mov_b32_e32 v33, v96
	v_fma_f32 v96, v2, v96, v10
	v_mov_b32_e32 v34, v96
	v_fma_f32 v96, v3, v96, v11
	v_mov_b32_e32 v35, v96
	v_fma_f32 v96, v4, v96, v12
	v_mov_b32_e32 v36, v96
	v_fma_f32 v96, v5, v96, v13
	v_mov_b32_e32 v37, v96
	v_fma_f32 v96, v6, v96, v14
	v_mov_b32_e32 v38, v96
	v_fma_f32 v96, v7, v96, v15
	v_mov_b32_e32 v39, v96
	ds_write2st64_b32 v195, v32, v33 offset0:62 offset1:60
	ds_write2st64_b32 v195, v34, v35 offset0:58 offset1:56
	ds_write2st64_b32 v195, v36, v37 offset0:54 offset1:52
	ds_write2st64_b32 v195, v38, v39 offset0:50 offset1:48
	s_waitcnt lgkmcnt(0)
	ds_read2st64_b32 v[0:1], v188 offset0:30 offset1:28
	ds_read2st64_b32 v[2:3], v188 offset0:26 offset1:24
	ds_read2st64_b32 v[4:5], v188 offset0:22 offset1:20
	ds_read2st64_b32 v[6:7], v188 offset0:18 offset1:16
	ds_read2st64_b32 v[8:9], v195 offset0:30 offset1:28
	ds_read2st64_b32 v[10:11], v195 offset0:26 offset1:24
	ds_read2st64_b32 v[12:13], v195 offset0:22 offset1:20
	ds_read2st64_b32 v[14:15], v195 offset0:18 offset1:16
	v_fma_f32 v96, v16, v96, v24
	v_mov_b32_e32 v32, v96
	v_fma_f32 v96, v17, v96, v25
	v_mov_b32_e32 v33, v96
	v_fma_f32 v96, v18, v96, v26
	v_mov_b32_e32 v34, v96
	v_fma_f32 v96, v19, v96, v27
	v_mov_b32_e32 v35, v96
	v_fma_f32 v96, v20, v96, v28
	v_mov_b32_e32 v36, v96
	v_fma_f32 v96, v21, v96, v29
	v_mov_b32_e32 v37, v96
	v_fma_f32 v96, v22, v96, v30
	v_mov_b32_e32 v38, v96
	v_fma_f32 v96, v23, v96, v31
	v_mov_b32_e32 v39, v96
	ds_write2st64_b32 v195, v32, v33 offset0:46 offset1:44
	ds_write2st64_b32 v195, v34, v35 offset0:42 offset1:40
	ds_write2st64_b32 v195, v36, v37 offset0:38 offset1:36
	ds_write2st64_b32 v195, v38, v39 offset0:34 offset1:32
	s_waitcnt lgkmcnt(0)
	ds_read2st64_b32 v[16:17], v188 offset0:14 offset1:12
	ds_read2st64_b32 v[18:19], v188 offset0:10 offset1:8
	ds_read2st64_b32 v[20:21], v188 offset0:6 offset1:4
	ds_read2st64_b32 v[22:23], v188 offset0:2 offset1:0
	ds_read2st64_b32 v[24:25], v195 offset0:14 offset1:12
	ds_read2st64_b32 v[26:27], v195 offset0:10 offset1:8
	ds_read2st64_b32 v[28:29], v195 offset0:6 offset1:4
	ds_read2st64_b32 v[30:31], v195 offset0:2 offset1:0
	v_fma_f32 v96, v0, v96, v8
	v_mov_b32_e32 v32, v96
	v_fma_f32 v96, v1, v96, v9
	v_mov_b32_e32 v33, v96
	v_fma_f32 v96, v2, v96, v10
	v_mov_b32_e32 v34, v96
	v_fma_f32 v96, v3, v96, v11
	v_mov_b32_e32 v35, v96
	v_fma_f32 v96, v4, v96, v12
	v_mov_b32_e32 v36, v96
	v_fma_f32 v96, v5, v96, v13
	v_mov_b32_e32 v37, v96
	v_fma_f32 v96, v6, v96, v14
	v_mov_b32_e32 v38, v96
	v_fma_f32 v96, v7, v96, v15
	v_mov_b32_e32 v39, v96
	ds_write2st64_b32 v195, v32, v33 offset0:30 offset1:28
	ds_write2st64_b32 v195, v34, v35 offset0:26 offset1:24
	ds_write2st64_b32 v195, v36, v37 offset0:22 offset1:20
	ds_write2st64_b32 v195, v38, v39 offset0:18 offset1:16
	s_waitcnt lgkmcnt(0)
	v_fma_f32 v96, v16, v96, v24
	v_mov_b32_e32 v32, v96
	v_fma_f32 v96, v17, v96, v25
	v_mov_b32_e32 v33, v96
	v_fma_f32 v96, v18, v96, v26
	v_mov_b32_e32 v34, v96
	v_fma_f32 v96, v19, v96, v27
	v_mov_b32_e32 v35, v96
	v_fma_f32 v96, v20, v96, v28
	v_mov_b32_e32 v36, v96
	v_fma_f32 v96, v21, v96, v29
	v_mov_b32_e32 v37, v96
	v_fma_f32 v96, v22, v96, v30
	v_mov_b32_e32 v38, v96
	v_fma_f32 v96, v23, v96, v31
	v_mov_b32_e32 v39, v96
	ds_write2st64_b32 v195, v32, v33 offset0:14 offset1:12
	ds_write2st64_b32 v195, v34, v35 offset0:10 offset1:8
	ds_write2st64_b32 v195, v36, v37 offset0:6 offset1:4
	ds_write2st64_b32 v195, v38, v39 offset0:2 offset1:0
; __device__ __forceinline__ u16 f2bf(float x) { return (u16)(cvtpk(x, 0.f) & 0xffffu); }
; __device__ __forceinline__ float fexp(float x) { return __builtin_amdgcn_exp2f(x * 1.4426950408889634f); }
; template <int PASS>
; __device__ __forceinline__ void lru_tile_phase(const Params& p, int jl, int Mrows, char* smem, int tid, int bid) {
;     ...
;     if (PASS == 2) {
;       __syncthreads();
;       const int ch = tid & 127, tg = tid >> 7;
;       const int col = n * 128 + ch;
;       float hsv[16];
; #pragma unroll
;       for (int i = 0; i < 16; ++i) { const int t = tg * 16 + i; hsv[i] = uL[(0 * 64 + t) * 128 + ch] + uL[(1 * 64 + t) * 128 + ch]; }
; #pragma unroll
;       for (int i = 0; i < 16; ++i) {
;         const int t = tg * 16 + i;
;         const float hs = hsv[i];
;         const float gt = __uint_as_float(gv[i] << 16);
;         const float z2 = 1.5957691216057308f * (gt + 0.044715f * gt * gt * gt);
;         const float gl = gt * __builtin_amdgcn_rcpf(1.f + fexp(-z2));
;         H[(size_t)(rowbase + t) * 1024 + col] = f2bf(hs * gl);
;       }
;     }
.Llru2_scan_store:
.Llru2_scan_done:
	s_waitcnt vmcnt(0) lgkmcnt(0)
	s_barrier
	ds_read_b128 v[0:3], v189 offset:0
	ds_read_b128 v[4:7], v189 offset:16
	ds_read_b128 v[8:11], v189 offset:32
	ds_read_b128 v[12:15], v189 offset:48
	ds_read_b128 v[32:35], v189 offset:32768
	ds_read_b128 v[36:39], v189 offset:32784
	ds_read_b128 v[40:43], v189 offset:32800
	ds_read_b128 v[44:47], v189 offset:32816
	s_lshl_b32 s0, s9, 11
	s_lshl_b32 s1, s7, 8
	s_add_u32 s0, s0, s1
	s_add_u32 s0, s28, s0
	s_addc_u32 s1, s29, 0
	s_waitcnt lgkmcnt(0)
	v_add_f32_e32 v64, v0, v32
	v_lshlrev_b32_e32 v80, 16, v92
	v_mul_f32_e32 v81, 0x3d372713, v80
	v_mul_f32_e32 v81, v81, v80
	v_fma_f32 v81, v81, v80, v80
	v_mul_f32_e32 v81, 0x3fcc422a, v81
	v_mul_f32_e32 v81, 0xbfb8aa3b, v81
	v_exp_f32_e32 v81, v81
	s_nop 0
	v_add_f32_e32 v81, 1.0, v81
	v_rcp_f32_e32 v81, v81
	s_nop 0
	v_mul_f32_e32 v81, v80, v81
	v_mul_f32_e32 v64, v64, v81
	v_add_f32_e32 v65, v1, v33
	v_and_b32_e32 v80, 0xffff0000, v92
	v_mul_f32_e32 v81, 0x3d372713, v80
	v_mul_f32_e32 v81, v81, v80
	v_fma_f32 v81, v81, v80, v80
	v_mul_f32_e32 v81, 0x3fcc422a, v81
	v_mul_f32_e32 v81, 0xbfb8aa3b, v81
	v_exp_f32_e32 v81, v81
	s_nop 0
	v_add_f32_e32 v81, 1.0, v81
	v_rcp_f32_e32 v81, v81
	s_nop 0
	v_mul_f32_e32 v81, v80, v81
	v_mul_f32_e32 v65, v65, v81
	v_add_f32_e32 v66, v2, v34
	v_lshlrev_b32_e32 v80, 16, v93
	v_mul_f32_e32 v81, 0x3d372713, v80
	v_mul_f32_e32 v81, v81, v80
	v_fma_f32 v81, v81, v80, v80
	v_mul_f32_e32 v81, 0x3fcc422a, v81
	v_mul_f32_e32 v81, 0xbfb8aa3b, v81
	v_exp_f32_e32 v81, v81
	s_nop 0
	v_add_f32_e32 v81, 1.0, v81
	v_rcp_f32_e32 v81, v81
	s_nop 0
	v_mul_f32_e32 v81, v80, v81
	v_mul_f32_e32 v66, v66, v81
	v_add_f32_e32 v67, v3, v35
	v_and_b32_e32 v80, 0xffff0000, v93
	v_mul_f32_e32 v81, 0x3d372713, v80
	v_mul_f32_e32 v81, v81, v80
	v_fma_f32 v81, v81, v80, v80
	v_mul_f32_e32 v81, 0x3fcc422a, v81
	v_mul_f32_e32 v81, 0xbfb8aa3b, v81
	v_exp_f32_e32 v81, v81
	s_nop 0
	v_add_f32_e32 v81, 1.0, v81
	v_rcp_f32_e32 v81, v81
	s_nop 0
	v_mul_f32_e32 v81, v80, v81
	v_mul_f32_e32 v67, v67, v81
	v_add_f32_e32 v68, v4, v36
	v_lshlrev_b32_e32 v80, 16, v94
	v_mul_f32_e32 v81, 0x3d372713, v80
	v_mul_f32_e32 v81, v81, v80
	v_fma_f32 v81, v81, v80, v80
	v_mul_f32_e32 v81, 0x3fcc422a, v81
	v_mul_f32_e32 v81, 0xbfb8aa3b, v81
	v_exp_f32_e32 v81, v81
	s_nop 0
	v_add_f32_e32 v81, 1.0, v81
	v_rcp_f32_e32 v81, v81
	s_nop 0
	v_mul_f32_e32 v81, v80, v81
	v_mul_f32_e32 v68, v68, v81
	v_add_f32_e32 v69, v5, v37
	v_and_b32_e32 v80, 0xffff0000, v94
	v_mul_f32_e32 v81, 0x3d372713, v80
	v_mul_f32_e32 v81, v81, v80
	v_fma_f32 v81, v81, v80, v80
	v_mul_f32_e32 v81, 0x3fcc422a, v81
	v_mul_f32_e32 v81, 0xbfb8aa3b, v81
	v_exp_f32_e32 v81, v81
	s_nop 0
	v_add_f32_e32 v81, 1.0, v81
	v_rcp_f32_e32 v81, v81
	s_nop 0
	v_mul_f32_e32 v81, v80, v81
	v_mul_f32_e32 v69, v69, v81
	v_add_f32_e32 v70, v6, v38
	v_lshlrev_b32_e32 v80, 16, v95
	v_mul_f32_e32 v81, 0x3d372713, v80
	v_mul_f32_e32 v81, v81, v80
	v_fma_f32 v81, v81, v80, v80
	v_mul_f32_e32 v81, 0x3fcc422a, v81
	v_mul_f32_e32 v81, 0xbfb8aa3b, v81
	v_exp_f32_e32 v81, v81
	s_nop 0
	v_add_f32_e32 v81, 1.0, v81
	v_rcp_f32_e32 v81, v81
	s_nop 0
	v_mul_f32_e32 v81, v80, v81
	v_mul_f32_e32 v70, v70, v81
	v_add_f32_e32 v71, v7, v39
	v_and_b32_e32 v80, 0xffff0000, v95
	v_mul_f32_e32 v81, 0x3d372713, v80
	v_mul_f32_e32 v81, v81, v80
	v_fma_f32 v81, v81, v80, v80
	v_mul_f32_e32 v81, 0x3fcc422a, v81
	v_mul_f32_e32 v81, 0xbfb8aa3b, v81
	v_exp_f32_e32 v81, v81
	s_nop 0
	v_add_f32_e32 v81, 1.0, v81
	v_rcp_f32_e32 v81, v81
	s_nop 0
	v_mul_f32_e32 v81, v80, v81
	v_mul_f32_e32 v71, v71, v81
	v_add_f32_e32 v72, v8, v40
	v_lshlrev_b32_e32 v80, 16, v244
	v_mul_f32_e32 v81, 0x3d372713, v80
	v_mul_f32_e32 v81, v81, v80
	v_fma_f32 v81, v81, v80, v80
	v_mul_f32_e32 v81, 0x3fcc422a, v81
	v_mul_f32_e32 v81, 0xbfb8aa3b, v81
; __device__ __forceinline__ u16 f2bf(float x) { return (u16)(cvtpk(x, 0.f) & 0xffffu); }
; __device__ __forceinline__ float fexp(float x) { return __builtin_amdgcn_exp2f(x * 1.4426950408889634f); }
; template <int PASS>
; __device__ __forceinline__ void lru_tile_phase(const Params& p, int jl, int Mrows, char* smem, int tid, int bid) {
;     ...
;   for (int job = bid; job < ntt * 8; job += gridDim.x) {
;     ...
;       for (int i = 0; i < 16; ++i) {
;         const int t = tg * 16 + i;
;         const float hs = hsv[i];
;         const float gt = __uint_as_float(gv[i] << 16);
;         const float z2 = 1.5957691216057308f * (gt + 0.044715f * gt * gt * gt);
;         const float gl = gt * __builtin_amdgcn_rcpf(1.f + fexp(-z2));
;         H[(size_t)(rowbase + t) * 1024 + col] = f2bf(hs * gl);
;       }
;     }
;     __syncthreads();
;   }
	v_exp_f32_e32 v81, v81
	s_nop 0
	v_add_f32_e32 v81, 1.0, v81
	v_rcp_f32_e32 v81, v81
	s_nop 0
	v_mul_f32_e32 v81, v80, v81
	v_mul_f32_e32 v72, v72, v81
	v_add_f32_e32 v73, v9, v41
	v_and_b32_e32 v80, 0xffff0000, v244
	v_mul_f32_e32 v81, 0x3d372713, v80
	v_mul_f32_e32 v81, v81, v80
	v_fma_f32 v81, v81, v80, v80
	v_mul_f32_e32 v81, 0x3fcc422a, v81
	v_mul_f32_e32 v81, 0xbfb8aa3b, v81
	v_exp_f32_e32 v81, v81
	s_nop 0
	v_add_f32_e32 v81, 1.0, v81
	v_rcp_f32_e32 v81, v81
	s_nop 0
	v_mul_f32_e32 v81, v80, v81
	v_mul_f32_e32 v73, v73, v81
	v_add_f32_e32 v74, v10, v42
	v_lshlrev_b32_e32 v80, 16, v245
	v_mul_f32_e32 v81, 0x3d372713, v80
	v_mul_f32_e32 v81, v81, v80
	v_fma_f32 v81, v81, v80, v80
	v_mul_f32_e32 v81, 0x3fcc422a, v81
	v_mul_f32_e32 v81, 0xbfb8aa3b, v81
	v_exp_f32_e32 v81, v81
	s_nop 0
	v_add_f32_e32 v81, 1.0, v81
	v_rcp_f32_e32 v81, v81
	s_nop 0
	v_mul_f32_e32 v81, v80, v81
	v_mul_f32_e32 v74, v74, v81
	v_add_f32_e32 v75, v11, v43
	v_and_b32_e32 v80, 0xffff0000, v245
	v_mul_f32_e32 v81, 0x3d372713, v80
	v_mul_f32_e32 v81, v81, v80
	v_fma_f32 v81, v81, v80, v80
	v_mul_f32_e32 v81, 0x3fcc422a, v81
	v_mul_f32_e32 v81, 0xbfb8aa3b, v81
	v_exp_f32_e32 v81, v81
	s_nop 0
	v_add_f32_e32 v81, 1.0, v81
	v_rcp_f32_e32 v81, v81
	s_nop 0
	v_mul_f32_e32 v81, v80, v81
	v_mul_f32_e32 v75, v75, v81
	v_add_f32_e32 v76, v12, v44
	v_lshlrev_b32_e32 v80, 16, v246
	v_mul_f32_e32 v81, 0x3d372713, v80
	v_mul_f32_e32 v81, v81, v80
	v_fma_f32 v81, v81, v80, v80
	v_mul_f32_e32 v81, 0x3fcc422a, v81
	v_mul_f32_e32 v81, 0xbfb8aa3b, v81
	v_exp_f32_e32 v81, v81
	s_nop 0
	v_add_f32_e32 v81, 1.0, v81
	v_rcp_f32_e32 v81, v81
	s_nop 0
	v_mul_f32_e32 v81, v80, v81
	v_mul_f32_e32 v76, v76, v81
	v_add_f32_e32 v77, v13, v45
	v_and_b32_e32 v80, 0xffff0000, v246
	v_mul_f32_e32 v81, 0x3d372713, v80
	v_mul_f32_e32 v81, v81, v80
	v_fma_f32 v81, v81, v80, v80
	v_mul_f32_e32 v81, 0x3fcc422a, v81
	v_mul_f32_e32 v81, 0xbfb8aa3b, v81
	v_exp_f32_e32 v81, v81
	s_nop 0
	v_add_f32_e32 v81, 1.0, v81
	v_rcp_f32_e32 v81, v81
	s_nop 0
	v_mul_f32_e32 v81, v80, v81
	v_mul_f32_e32 v77, v77, v81
	v_add_f32_e32 v78, v14, v46
	v_lshlrev_b32_e32 v80, 16, v247
	v_mul_f32_e32 v81, 0x3d372713, v80
	v_mul_f32_e32 v81, v81, v80
	v_fma_f32 v81, v81, v80, v80
	v_mul_f32_e32 v81, 0x3fcc422a, v81
	v_mul_f32_e32 v81, 0xbfb8aa3b, v81
	v_exp_f32_e32 v81, v81
	s_nop 0
	v_add_f32_e32 v81, 1.0, v81
	v_rcp_f32_e32 v81, v81
	s_nop 0
	v_mul_f32_e32 v81, v80, v81
	v_mul_f32_e32 v78, v78, v81
	v_add_f32_e32 v79, v15, v47
	v_and_b32_e32 v80, 0xffff0000, v247
	v_mul_f32_e32 v81, 0x3d372713, v80
	v_mul_f32_e32 v81, v81, v80
	v_fma_f32 v81, v81, v80, v80
	v_mul_f32_e32 v81, 0x3fcc422a, v81
	v_mul_f32_e32 v81, 0xbfb8aa3b, v81
	v_exp_f32_e32 v81, v81
	s_nop 0
	v_add_f32_e32 v81, 1.0, v81
	v_rcp_f32_e32 v81, v81
	s_nop 0
	v_mul_f32_e32 v81, v80, v81
	v_mul_f32_e32 v79, v79, v81
	v_cvt_pk_bf16_f32 v48, v64, v65
	v_cvt_pk_bf16_f32 v49, v66, v67
	v_cvt_pk_bf16_f32 v50, v68, v69
	v_cvt_pk_bf16_f32 v51, v70, v71
	v_cvt_pk_bf16_f32 v52, v72, v73
	v_cvt_pk_bf16_f32 v53, v74, v75
	v_cvt_pk_bf16_f32 v54, v76, v77
	v_cvt_pk_bf16_f32 v55, v78, v79
	global_store_dwordx4 v193, v[48:51], s[0:1]
	global_store_dwordx4 v193, v[52:55], s[0:1] offset:16
	s_waitcnt vmcnt(0) lgkmcnt(0)
	s_barrier
	s_add_u32 s6, s6, s71
	s_cmp_lt_u32 s6, 0x1100
	s_cbranch_scc1 .Llru2_job
	v_readlane_b32 s36, v255, 11
	v_readlane_b32 s37, v255, 12
	v_readlane_b32 s38, v255, 13
	v_readlane_b32 s39, v255, 14
	v_readlane_b32 s40, v255, 15
	v_readlane_b32 s41, v255, 16
	v_readlane_b32 s42, v255, 17
	v_readlane_b32 s43, v255, 18
	v_readlane_b32 s44, v255, 19
	v_readlane_b32 s45, v255, 20
	v_readlane_b32 s46, v255, 21
	v_readlane_b32 s47, v255, 22
	v_readlane_b32 s48, v255, 23
	v_readlane_b32 s49, v255, 24
	v_readlane_b32 s50, v255, 25
	v_readlane_b32 s51, v255, 26

; __device__ __forceinline__ float fexp(float x) { return __builtin_amdgcn_exp2f(x * 1.4426950408889634f); }
; __device__ __forceinline__ float flog(float x) { return __builtin_amdgcn_logf(x) * 0.6931471805599453f; }
; template <int PASS>
; __device__ __forceinline__ void lru_tile_phase(const Params& p, int jl, int Mrows, char* smem, int tid, int bid) {
;   char* xcL = smem;
;   float* aL = (float*)(smem + 16384);
;   float* uL = (float*)(smem + 16384 + 65536);
;   const u16* P2 = (const u16*)(p.ws + OFF_S);
;   u16* H = (u16*)(p.ws + OFF_LRU_Y);
;   float2* summ = (float2*)(p.ws + OFF_LRU_SUM);
;   const float* carry = (const float*)(p.ws + OFF_LRU_CAR);
;   const u16* Wbd = (const u16*)(p.ws + OFF_WMIX) + 3072 * 1024;
;   const int ntt = Mrows / 64;
;   bf16x8 wb0[8], wb1[8]; float c_ba = 0.f, c_bx = 0.f, c_sp = 0.f; int n_loaded = -1;
;   for (int job = bid; job < ntt * 8; job += gridDim.x) {
;     asm volatile("" : "+v"(tid));
;     const int lane = tid & 63, wid = tid >> 6, l32 = lane & 31, hi = lane >> 5;
;     const int tt = job >> 3, n = job & 7;
;     const bool lat = tt < 512;
;     const int rowbase = lat ? tt * 64 : ML + (tt - 512) * 64;
;     const int sloc = lat ? (tt & 63) * 64 : ((tt - 512) & 3) * 64;
;     const int TT = lat ? SEQL : CTXL;
;     ...
;       const int cbk = wid & 3, dh = wid >> 2;
;       const int chl = cbk * 32 + l32, col = n * 128 + chl;
;       if (n != n_loaded) {
;         const u16* wbase = Wbd + (size_t)n * 16384 + (size_t)chl * 128 + hi * 8;
; #pragma unroll
;         for (int k16 = 0; k16 < 8; ++k16) {
;           wb0[k16] = *(const bf16x8*)(wbase + (size_t)(dh * 2 + 0) * 131072 + k16 * 16);
;           wb1[k16] = *(const bf16x8*)(wbase + (size_t)(dh * 2 + 1) * 131072 + k16 * 16);
;         }
;         const float* pba = dh ? p.in[26] : p.in[21]; const float* pbx = dh ? p.in[28] : p.in[23]; const float* plam = dh ? p.in[29] : p.in[24];
;         c_ba = pba[(size_t)jl * 1024 + col]; c_bx = pbx[(size_t)jl * 1024 + col];
;         c_sp = -8.f * flog(1.f + fexp(-plam[(size_t)jl * 1024 + col]));
;         n_loaded = n;
;       }
.LBB0_248:
	s_andn2_b64 vcc, exec, s[0:1]
	s_cbranch_vccnz .LBB0_260
	s_cmpk_gt_i32 s62, 0x10ff
	s_cbranch_scc1 .LBB0_260
	v_readlane_b32 s0, v253, 1
	v_readlane_b32 s1, v253, 2
	s_sub_u32 s0, s0, 0x138
	s_subb_u32 s1, s1, 0
	s_load_dwordx4 s[36:39], s[0:1], 0x90
	s_load_dwordx2 s[40:41], s[0:1], 0xa8
	s_load_dwordx2 s[44:45], s[0:1], 0xb8
	s_load_dwordx2 s[46:47], s[0:1], 0xc0
	s_load_dwordx2 s[42:43], s[0:1], 0xd0
	s_load_dwordx4 s[48:51], s[0:1], 0xe0
	s_load_dwordx2 s[4:5], s[0:1], 0x128
	s_waitcnt lgkmcnt(0)
	s_lshl_b32 s0, s72, 14
	s_add_u32 s36, s36, s0
	s_addc_u32 s37, s37, 0
	s_lshl_b32 s0, s72, 12
	s_add_u32 s38, s38, s0
	s_addc_u32 s39, s39, 0
	s_add_u32 s40, s40, s0
	s_addc_u32 s41, s41, 0
	s_add_u32 s42, s42, s0
	s_addc_u32 s43, s43, 0
	s_add_u32 s44, s44, s0
	s_addc_u32 s45, s45, 0
	s_add_u32 s46, s46, s0
	s_addc_u32 s47, s47, 0
	s_add_u32 s48, s48, s0
	s_addc_u32 s49, s49, 0
	s_add_u32 s50, s50, s0
	s_addc_u32 s51, s51, 0
	s_add_u32 s22, s4, 0x129dc000
	s_addc_u32 s23, s5, 0
	s_add_u32 s24, s4, 0x1325c000
	s_addc_u32 s25, s5, 0
	s_add_u32 s28, s4, 0x1369c000
	s_addc_u32 s29, s5, 0
	s_add_u32 s18, s4, 0x8e00000
	s_addc_u32 s19, s5, 0
	v_and_b32_e32 v80, 63, v203
	v_lshrrev_b32_e32 v81, 6, v203
	v_and_b32_e32 v236, 31, v203
	v_bfe_u32 v237, v203, 5, 1
	v_lshrrev_b32_e32 v84, 4, v203
	v_and_b32_e32 v99, 15, v203
	v_readfirstlane_b32 s0, v81
	s_and_b32 s1, s0, 3
	s_lshr_b32 s16, s0, 2
	s_mov_b32 s27, s0
	v_lshlrev_b32_e32 v190, 1, v84
	v_lshlrev_b32_e32 v191, 4, v99
	v_or_b32_e32 v195, 0, v190
	v_and_b32_e32 v196, 15, v195
	v_xor_b32_e32 v196, v99, v196
	v_lshlrev_b32_e32 v196, 4, v196
	v_lshl_or_b32 v183, v195, 8, v196
	v_or_b32_e32 v195, 1, v190
	v_and_b32_e32 v196, 15, v195
	v_xor_b32_e32 v196, v99, v196
	v_lshlrev_b32_e32 v196, 4, v196
	v_lshl_or_b32 v184, v195, 8, v196
	v_and_b32_e32 v195, 15, v236
	v_xor_b32_e32 v195, v237, v195
	v_lshlrev_b32_e32 v195, 4, v195
	v_lshl_or_b32 v185, v236, 8, v195
	s_lshl_b32 s4, s1, 5
	v_add_u32_e32 v195, s4, v236
	s_lshl_b32 s5, s16, 6
	v_lshl_add_u32 v196, v237, 2, s5
	v_lshlrev_b32_e32 v196, 7, v196
	v_add_u32_e32 v196, v196, v195
	v_lshlrev_b32_e32 v186, 2, v196
	v_add_u32_e32 v186, 0x4000, v186
	v_add_u32_e32 v187, 0x10000, v186
	v_bfe_u32 v196, v236, 3, 1
	v_cmp_eq_u32_e32 vcc, v196, v237
	v_and_b32_e32 v197, 7, v236
	v_lshrrev_b32_e32 v198, 1, v197
	v_and_b32_e32 v197, 1, v197
	v_lshlrev_b32_e32 v197, 4, v197
	v_mov_b32_e32 v199, 0x3f80
	v_lshlrev_b32_e32 v199, v197, v199
	v_cndmask_b32_e32 v199, 0, v199, vcc
	v_lshrrev_b32_e32 v200, 4, v236
	v_cmp_eq_u32_e32 vcc, 0, v200
	v_cmp_eq_u32_e64 s[4:5], 0, v198
	s_and_b64 vcc, vcc, s[4:5]
	v_cndmask_b32_e32 v172, 0, v199, vcc
	v_cmp_eq_u32_e32 vcc, 0, v200
	v_cmp_eq_u32_e64 s[4:5], 1, v198
	s_and_b64 vcc, vcc, s[4:5]
	v_cndmask_b32_e32 v173, 0, v199, vcc
	v_cmp_eq_u32_e32 vcc, 0, v200
	v_cmp_eq_u32_e64 s[4:5], 2, v198
	s_and_b64 vcc, vcc, s[4:5]
	v_cndmask_b32_e32 v174, 0, v199, vcc
	v_cmp_eq_u32_e32 vcc, 0, v200
	v_cmp_eq_u32_e64 s[4:5], 3, v198
	s_and_b64 vcc, vcc, s[4:5]
	v_cndmask_b32_e32 v175, 0, v199, vcc
	v_cmp_eq_u32_e32 vcc, 1, v200
	v_cmp_eq_u32_e64 s[4:5], 0, v198
	s_and_b64 vcc, vcc, s[4:5]
	v_cndmask_b32_e32 v176, 0, v199, vcc
	v_cmp_eq_u32_e32 vcc, 1, v200
	v_cmp_eq_u32_e64 s[4:5], 1, v198
	s_and_b64 vcc, vcc, s[4:5]
	v_cndmask_b32_e32 v177, 0, v199, vcc
	v_cmp_eq_u32_e32 vcc, 1, v200
	v_cmp_eq_u32_e64 s[4:5], 2, v198
	s_and_b64 vcc, vcc, s[4:5]
	v_cndmask_b32_e32 v178, 0, v199, vcc
	v_cmp_eq_u32_e32 vcc, 1, v200
	v_cmp_eq_u32_e64 s[4:5], 3, v198
	s_and_b64 vcc, vcc, s[4:5]
	v_cndmask_b32_e32 v179, 0, v199, vcc
	v_and_b32_e32 v195, 0x7f, v203
	v_bfe_u32 v196, v203, 7, 1
	v_lshl_or_b32 v196, v196, 13, v195
	v_lshlrev_b32_e32 v188, 2, v196
	v_add_u32_e32 v188, 0x4000, v188
	v_bfe_u32 v196, v203, 7, 1
	v_lshl_or_b32 v194, v196, 10, v195
	s_mov_b32 s6, s62
	s_mov_b32 s26, -1
.Llru1_job:
	s_lshr_b32 s8, s6, 3
	s_and_b32 s7, s6, 7
	s_cmp_eq_u32 s7, s26
	s_cbranch_scc1 .Llru1_nloaded
	s_mov_b32 s26, s7
	s_lshl_b32 s0, s7, 9
	v_lshl_add_u32 v195, v99, 5, s0
	global_load_dwordx4 v[100:103], v195, s[36:37]
	global_load_dwordx4 v[104:107], v195, s[36:37] offset:16
	s_add_u32 s4, s36, 4096
	s_addc_u32 s5, s37, 0
	global_load_dwordx4 v[108:111], v195, s[4:5]
	global_load_dwordx4 v[112:115], v195, s[4:5] offset:16
	s_add_u32 s4, s36, 8192
	s_addc_u32 s5, s37, 0
	global_load_dwordx4 v[116:119], v195, s[4:5]
	global_load_dwordx4 v[120:123], v195, s[4:5] offset:16
	s_add_u32 s4, s36, 12288
	s_addc_u32 s5, s37, 0
	global_load_dwordx4 v[124:127], v195, s[4:5]
	global_load_dwordx4 v[128:131], v195, s[4:5] offset:16
	global_load_dwordx4 v[132:135], v195, s[38:39]
	global_load_dwordx4 v[136:139], v195, s[38:39] offset:16
	s_lshl_b32 s0, s16, 1
	s_lshl_b32 s0, s0, 3
	s_add_u32 s0, s0, s7
	s_lshl_b32 s0, s0, 15
	s_add_u32 s4, s18, s0
	s_addc_u32 s5, s19, 0
	s_and_b32 s0, s27, 3
	s_lshl_b32 s0, s0, 5
	v_add_u32_e32 v196, s0, v236
	v_lshlrev_b32_e32 v196, 8, v196
	v_lshl_or_b32 v196, v237, 4, v196
	global_load_dwordx4 v[140:143], v196, s[4:5] offset:0
	global_load_dwordx4 v[144:147], v196, s[4:5] offset:32
	global_load_dwordx4 v[148:151], v196, s[4:5] offset:64
	global_load_dwordx4 v[152:155], v196, s[4:5] offset:96
	global_load_dwordx4 v[156:159], v196, s[4:5] offset:128
	global_load_dwordx4 v[160:163], v196, s[4:5] offset:160
	global_load_dwordx4 v[164:167], v196, s[4:5] offset:192
	global_load_dwordx4 v[168:171], v196, s[4:5] offset:224
	s_add_u32 s4, s4, 0x40000
	s_addc_u32 s5, s5, 0
	global_load_dwordx4 v[204:207], v196, s[4:5] offset:0
	global_load_dwordx4 v[208:211], v196, s[4:5] offset:32
	global_load_dwordx4 v[212:215], v196, s[4:5] offset:64
	global_load_dwordx4 v[216:219], v196, s[4:5] offset:96
	global_load_dwordx4 v[220:223], v196, s[4:5] offset:128
	global_load_dwordx4 v[224:227], v196, s[4:5] offset:160
	global_load_dwordx4 v[228:231], v196, s[4:5] offset:192
	global_load_dwordx4 v[232:235], v196, s[4:5] offset:224
	s_lshl_b32 s0, s7, 7
	s_and_b32 s1, s27, 3
	s_lshl_b32 s1, s1, 5
	s_add_u32 s0, s0, s1
	v_add_u32_e32 v197, s0, v236
	v_lshlrev_b32_e32 v197, 2, v197
	s_cmp_eq_u32 s16, 0
	s_cselect_b32 s4, s40, s42
	s_cselect_b32 s5, s41, s43
	global_load_dword v180, v197, s[4:5]
	s_cselect_b32 s4, s44, s48
	s_cselect_b32 s5, s45, s49
	global_load_dword v181, v197, s[4:5]
	s_cselect_b32 s4, s46, s50
	s_cselect_b32 s5, s47, s51
	global_load_dword v182, v197, s[4:5]
	s_waitcnt vmcnt(0)
	v_mul_f32_e32 v180, 0xbfb8aa3b, v180
	v_mul_f32_e32 v181, 0xbfb8aa3b, v181
	v_mul_f32_e32 v182, 0xbfb8aa3b, v182
	v_exp_f32_e32 v182, v182
	s_nop 0
	v_add_f32_e32 v182, 1.0, v182
	v_log_f32_e32 v182, v182
	s_nop 0
	v_mul_f32_e32 v182, 0x3f317218, v182
	v_mul_f32_e32 v182, 0xc1000000, v182
	v_mul_f32_e32 v182, 0x3fb8aa3b, v182
; __device__ __forceinline__ u16 f2bf(float x) { return (u16)(cvtpk(x, 0.f) & 0xffffu); }
; template <int PASS>
; __device__ __forceinline__ void lru_tile_phase(const Params& p, int jl, int Mrows, char* smem, int tid, int bid) {
;     ...
;     const int TT = lat ? SEQL : CTXL;
;     unsigned gv[16]; float carry_in = 0.f;
;     if (PASS == 2) {
;       const int ch = tid & 127, tg = tid >> 7;
; #pragma unroll
;       for (int i = 0; i < 16; ++i) gv[i] = P2[(size_t)(rowbase + tg * 16 + i) * 2048 + n * 128 + ch];
;       if (tid < 256) carry_in = carry[(size_t)(tt * 2 + (tid >> 7)) * 1024 + n * 128 + (tid & 127)];
;     }
;     {
;       const int ch = tid & 127, tg = tid >> 7, t0 = tg * 16;
;       const int col = n * 128 + ch;
;       float cw0 = p.in[18][(size_t)(jl * 4 + 0) * 1024 + col], cw1 = p.in[18][(size_t)(jl * 4 + 1) * 1024 + col];
;       float cw2 = p.in[18][(size_t)(jl * 4 + 2) * 1024 + col], cw3 = p.in[18][(size_t)(jl * 4 + 3) * 1024 + col];
;       const float cb = p.in[19][(size_t)jl * 1024 + col];
;       float xb[19]; unsigned xraw[19];
;       const u16* xsrc = P2 + (size_t)(rowbase - sloc) * 2048 + 1024 + col;
; #pragma unroll
;       for (int i = 0; i < 19; ++i) {
;         const int s = sloc + t0 + i - 2;
;         const int sc = s < 0 ? 0 : (s >= TT ? TT - 1 : s);
;         xraw[i] = xsrc[(size_t)sc * 2048];
;       }
; #pragma unroll
;       for (int i = 0; i < 19; ++i) {
;         const int s = sloc + t0 + i - 2;
;         xb[i] = (s >= 0 && s < TT) ? __uint_as_float(xraw[i] << 16) : 0.f;
;       }
; #pragma unroll
;       for (int i = 0; i < 16; ++i) {
;         const float xc = cb + cw0 * xb[i] + cw1 * xb[i + 1] + cw2 * xb[i + 2] + cw3 * xb[i + 3];
;         *(u16*)(xcL + swz256(t0 + i, ch >> 3) + (ch & 7) * 2) = f2bf(xc);
;       }
;     }
;     __syncthreads();
.Llru1_nloaded:
	s_movk_i32 s0, 0x1000
	s_cmp_lt_u32 s8, 512
	s_cselect_b32 s4, 0, 512
	s_cselect_b32 s5, 0, 0x8000
	s_cselect_b32 s1, 63, 3
	s_cselect_b32 s11, s0, 0x100
	s_sub_u32 s0, s8, s4
	s_lshl_b32 s9, s0, 6
	s_add_u32 s9, s9, s5
	s_and_b32 s10, s0, s1
	s_lshl_b32 s10, s10, 6
	s_cmp_eq_u32 s10, 0
	s_cselect_b32 s4, 0, -2
	s_add_u32 s0, s10, 64
	s_cmp_eq_u32 s0, s11
	s_cselect_b32 s5, 63, 0x41
	s_lshl_b32 s0, s9, 12
	s_lshl_b32 s1, s7, 8
	s_add_u32 s0, s0, s1
	s_add_u32 s20, s92, s0
	s_addc_u32 s21, s93, 0
	s_sub_u32 s0, s20, 0x1800
	s_subb_u32 s1, s21, 0
	v_add_u32_e32 v44, -2, v190
	v_max_i32_e32 v49, s4, v44
	v_min_i32_e32 v49, s5, v49
	v_add_u32_e32 v195, 2, v49
	v_lshl_add_u32 v195, v195, 12, v191
	global_load_dwordx4 v[0:3], v195, s[0:1]
	v_add_u32_e32 v45, -1, v190
	v_max_i32_e32 v50, s4, v45
	v_min_i32_e32 v50, s5, v50
	v_add_u32_e32 v195, 2, v50
	v_lshl_add_u32 v195, v195, 12, v191
	global_load_dwordx4 v[4:7], v195, s[0:1]
	v_add_u32_e32 v46, 0, v190
	v_max_i32_e32 v51, s4, v46
	v_min_i32_e32 v51, s5, v51
	v_add_u32_e32 v195, 2, v51
	v_lshl_add_u32 v195, v195, 12, v191
	global_load_dwordx4 v[8:11], v195, s[0:1]
	v_add_u32_e32 v47, 1, v190
	v_max_i32_e32 v52, s4, v47
	v_min_i32_e32 v52, s5, v52
	v_add_u32_e32 v195, 2, v52
	v_lshl_add_u32 v195, v195, 12, v191
	global_load_dwordx4 v[12:15], v195, s[0:1]
	v_add_u32_e32 v48, 2, v190
	v_max_i32_e32 v53, s4, v48
	v_min_i32_e32 v53, s5, v53
	v_add_u32_e32 v195, 2, v53
	v_lshl_add_u32 v195, v195, 12, v191
	global_load_dwordx4 v[16:19], v195, s[0:1]
	v_mov_b32_e32 v20, v132
	v_mov_b32_e32 v21, v133
	v_mov_b32_e32 v22, v134
	v_mov_b32_e32 v23, v135
	v_mov_b32_e32 v24, v136
	v_mov_b32_e32 v25, v137
	v_mov_b32_e32 v26, v138
	v_mov_b32_e32 v27, v139
	v_mov_b32_e32 v28, v132
	v_mov_b32_e32 v29, v133
	v_mov_b32_e32 v30, v134
	v_mov_b32_e32 v31, v135
	v_mov_b32_e32 v32, v136
	v_mov_b32_e32 v33, v137
	v_mov_b32_e32 v34, v138
	v_mov_b32_e32 v35, v139
	s_waitcnt vmcnt(4)
	v_cmp_eq_u32_e32 vcc, v44, v49
	s_nop 1
	v_cndmask_b32_e32 v0, 0, v0, vcc
	v_cndmask_b32_e32 v1, 0, v1, vcc
	v_cndmask_b32_e32 v2, 0, v2, vcc
	v_cndmask_b32_e32 v3, 0, v3, vcc
	v_lshlrev_b32_e32 v36, 16, v0
	v_and_b32_e32 v37, 0xffff0000, v0
	v_lshlrev_b32_e32 v38, 16, v1
	v_and_b32_e32 v39, 0xffff0000, v1
	v_lshlrev_b32_e32 v40, 16, v2
	v_and_b32_e32 v41, 0xffff0000, v2
	v_lshlrev_b32_e32 v42, 16, v3
	v_and_b32_e32 v43, 0xffff0000, v3
	v_fmac_f32_e32 v20, v100, v36
	v_fmac_f32_e32 v21, v101, v37
	v_fmac_f32_e32 v22, v102, v38
	v_fmac_f32_e32 v23, v103, v39
	v_fmac_f32_e32 v24, v104, v40
	v_fmac_f32_e32 v25, v105, v41
	v_fmac_f32_e32 v26, v106, v42
	v_fmac_f32_e32 v27, v107, v43
	s_waitcnt vmcnt(3)
	v_cmp_eq_u32_e32 vcc, v45, v50
	s_nop 1
	v_cndmask_b32_e32 v4, 0, v4, vcc
	v_cndmask_b32_e32 v5, 0, v5, vcc
	v_cndmask_b32_e32 v6, 0, v6, vcc
	v_cndmask_b32_e32 v7, 0, v7, vcc
	v_lshlrev_b32_e32 v36, 16, v4
	v_and_b32_e32 v37, 0xffff0000, v4
	v_lshlrev_b32_e32 v38, 16, v5
	v_and_b32_e32 v39, 0xffff0000, v5
	v_lshlrev_b32_e32 v40, 16, v6
	v_and_b32_e32 v41, 0xffff0000, v6
	v_lshlrev_b32_e32 v42, 16, v7
	v_and_b32_e32 v43, 0xffff0000, v7
	v_fmac_f32_e32 v20, v108, v36
	v_fmac_f32_e32 v21, v109, v37
	v_fmac_f32_e32 v22, v110, v38
	v_fmac_f32_e32 v23, v111, v39
	v_fmac_f32_e32 v24, v112, v40
	v_fmac_f32_e32 v25, v113, v41
	v_fmac_f32_e32 v26, v114, v42
	v_fmac_f32_e32 v27, v115, v43
	v_fmac_f32_e32 v28, v100, v36
	v_fmac_f32_e32 v29, v101, v37
	v_fmac_f32_e32 v30, v102, v38
	v_fmac_f32_e32 v31, v103, v39
	v_fmac_f32_e32 v32, v104, v40
	v_fmac_f32_e32 v33, v105, v41
	v_fmac_f32_e32 v34, v106, v42
	v_fmac_f32_e32 v35, v107, v43
	s_waitcnt vmcnt(2)
	v_cmp_eq_u32_e32 vcc, v46, v51
	s_nop 1
	v_cndmask_b32_e32 v8, 0, v8, vcc
	v_cndmask_b32_e32 v9, 0, v9, vcc
	v_cndmask_b32_e32 v10, 0, v10, vcc
	v_cndmask_b32_e32 v11, 0, v11, vcc
	v_lshlrev_b32_e32 v36, 16, v8
	v_and_b32_e32 v37, 0xffff0000, v8
	v_lshlrev_b32_e32 v38, 16, v9
	v_and_b32_e32 v39, 0xffff0000, v9
	v_lshlrev_b32_e32 v40, 16, v10
	v_and_b32_e32 v41, 0xffff0000, v10
	v_lshlrev_b32_e32 v42, 16, v11
	v_and_b32_e32 v43, 0xffff0000, v11
	v_fmac_f32_e32 v20, v116, v36
	v_fmac_f32_e32 v21, v117, v37
	v_fmac_f32_e32 v22, v118, v38
	v_fmac_f32_e32 v23, v119, v39
	v_fmac_f32_e32 v24, v120, v40
	v_fmac_f32_e32 v25, v121, v41
	v_fmac_f32_e32 v26, v122, v42
	v_fmac_f32_e32 v27, v123, v43
	v_fmac_f32_e32 v28, v108, v36
	v_fmac_f32_e32 v29, v109, v37
	v_fmac_f32_e32 v30, v110, v38
	v_fmac_f32_e32 v31, v111, v39
	v_fmac_f32_e32 v32, v112, v40
	v_fmac_f32_e32 v33, v113, v41
	v_fmac_f32_e32 v34, v114, v42
	v_fmac_f32_e32 v35, v115, v43
	s_waitcnt vmcnt(1)
	v_cmp_eq_u32_e32 vcc, v47, v52
	s_nop 1
	v_cndmask_b32_e32 v12, 0, v12, vcc
	v_cndmask_b32_e32 v13, 0, v13, vcc
	v_cndmask_b32_e32 v14, 0, v14, vcc
	v_cndmask_b32_e32 v15, 0, v15, vcc
	v_lshlrev_b32_e32 v36, 16, v12
	v_and_b32_e32 v37, 0xffff0000, v12
	v_lshlrev_b32_e32 v38, 16, v13
	v_and_b32_e32 v39, 0xffff0000, v13
	v_lshlrev_b32_e32 v40, 16, v14
	v_and_b32_e32 v41, 0xffff0000, v14
	v_lshlrev_b32_e32 v42, 16, v15
	v_and_b32_e32 v43, 0xffff0000, v15
	v_fmac_f32_e32 v20, v124, v36
	v_fmac_f32_e32 v21, v125, v37
	v_fmac_f32_e32 v22, v126, v38
	v_fmac_f32_e32 v23, v127, v39
	v_fmac_f32_e32 v24, v128, v40
	v_fmac_f32_e32 v25, v129, v41
	v_fmac_f32_e32 v26, v130, v42
	v_fmac_f32_e32 v27, v131, v43
	v_fmac_f32_e32 v28, v116, v36
	v_fmac_f32_e32 v29, v117, v37
	v_fmac_f32_e32 v30, v118, v38
	v_fmac_f32_e32 v31, v119, v39
	v_fmac_f32_e32 v32, v120, v40
	v_fmac_f32_e32 v33, v121, v41
	v_fmac_f32_e32 v34, v122, v42
	v_fmac_f32_e32 v35, v123, v43
	s_waitcnt vmcnt(0)
	v_cmp_eq_u32_e32 vcc, v48, v53
	s_nop 1
	v_cndmask_b32_e32 v16, 0, v16, vcc
	v_cndmask_b32_e32 v17, 0, v17, vcc
	v_cndmask_b32_e32 v18, 0, v18, vcc
	v_cndmask_b32_e32 v19, 0, v19, vcc
	v_lshlrev_b32_e32 v36, 16, v16
	v_and_b32_e32 v37, 0xffff0000, v16
	v_lshlrev_b32_e32 v38, 16, v17
	v_and_b32_e32 v39, 0xffff0000, v17
	v_lshlrev_b32_e32 v40, 16, v18
	v_and_b32_e32 v41, 0xffff0000, v18
	v_lshlrev_b32_e32 v42, 16, v19
	v_and_b32_e32 v43, 0xffff0000, v19
	v_fmac_f32_e32 v28, v124, v36
	v_fmac_f32_e32 v29, v125, v37
	v_fmac_f32_e32 v30, v126, v38
	v_fmac_f32_e32 v31, v127, v39
	v_fmac_f32_e32 v32, v128, v40
	v_fmac_f32_e32 v33, v129, v41
	v_fmac_f32_e32 v34, v130, v42
	v_fmac_f32_e32 v35, v131, v43
	v_cvt_pk_bf16_f32 v36, v20, v21
	v_cvt_pk_bf16_f32 v37, v22, v23
	v_cvt_pk_bf16_f32 v38, v24, v25
	v_cvt_pk_bf16_f32 v39, v26, v27
	v_cvt_pk_bf16_f32 v40, v28, v29
	v_cvt_pk_bf16_f32 v41, v30, v31
	v_cvt_pk_bf16_f32 v42, v32, v33
	v_cvt_pk_bf16_f32 v43, v34, v35
	ds_write_b128 v183, v[36:39]
	ds_write_b128 v184, v[40:43]
	s_waitcnt lgkmcnt(0)
	s_barrier
; template <int PASS>
; __device__ __forceinline__ void lru_tile_phase(const Params& p, int jl, int Mrows, char* smem, int tid, int bid) {
;     ...
;         bf16x8 af[8];
; #pragma unroll
;         for (int k16 = 0; k16 < 8; ++k16) af[k16] = *(const bf16x8*)(xcL + swz256(tb * 32 + l32, k16 * 2 + hi));
; #pragma unroll
;         for (int k16 = 0; k16 < 8; ++k16) {
;           acc0 = __builtin_amdgcn_mfma_f32_32x32x16_bf16(af[k16], wb0[k16], acc0, 0, 0, 0);
;           acc1 = __builtin_amdgcn_mfma_f32_32x32x16_bf16(af[k16], wb1[k16], acc1, 0, 0, 0);
;         }
	ds_read_b128 v[48:51], v185 offset:0
	v_xor_b32_e32 v196, 32, v185
	ds_read_b128 v[52:55], v196 offset:0
	v_xor_b32_e32 v195, 64, v185
	ds_read_b128 v[56:59], v195 offset:0
	v_xor_b32_e32 v196, 96, v185
	ds_read_b128 v[60:63], v196 offset:0
	v_xor_b32_e32 v195, 128, v185
	ds_read_b128 v[64:67], v195 offset:0
	v_xor_b32_e32 v196, 160, v185
	ds_read_b128 v[68:71], v196 offset:0
	v_xor_b32_e32 v195, 192, v185
	ds_read_b128 v[72:75], v195 offset:0
	v_xor_b32_e32 v196, 224, v185
	ds_read_b128 v[76:79], v196 offset:0
	s_waitcnt lgkmcnt(7)
	v_mfma_f32_32x32x16_bf16 v[0:15], v[48:51], v[140:143], 0
	v_mfma_f32_32x32x16_bf16 v[16:31], v[48:51], v[204:207], 0
	s_waitcnt lgkmcnt(6)
	v_mfma_f32_32x32x16_bf16 v[0:15], v[52:55], v[144:147], v[0:15]
	v_mfma_f32_32x32x16_bf16 v[16:31], v[52:55], v[208:211], v[16:31]
	s_waitcnt lgkmcnt(5)
	v_mfma_f32_32x32x16_bf16 v[0:15], v[56:59], v[148:151], v[0:15]
	v_mfma_f32_32x32x16_bf16 v[16:31], v[56:59], v[212:215], v[16:31]
	s_waitcnt lgkmcnt(4)
	v_mfma_f32_32x32x16_bf16 v[0:15], v[60:63], v[152:155], v[0:15]
	v_mfma_f32_32x32x16_bf16 v[16:31], v[60:63], v[216:219], v[16:31]
	s_waitcnt lgkmcnt(3)
	v_mfma_f32_32x32x16_bf16 v[0:15], v[64:67], v[156:159], v[0:15]
	v_mfma_f32_32x32x16_bf16 v[16:31], v[64:67], v[220:223], v[16:31]
	s_waitcnt lgkmcnt(2)
	v_mfma_f32_32x32x16_bf16 v[0:15], v[68:71], v[160:163], v[0:15]
	v_mfma_f32_32x32x16_bf16 v[16:31], v[68:71], v[224:227], v[16:31]
	s_waitcnt lgkmcnt(1)
	v_mfma_f32_32x32x16_bf16 v[0:15], v[72:75], v[164:167], v[0:15]
	v_mfma_f32_32x32x16_bf16 v[16:31], v[72:75], v[228:231], v[16:31]
	s_waitcnt lgkmcnt(0)
	v_mfma_f32_32x32x16_bf16 v[0:15], v[76:79], v[168:171], v[0:15]
	v_mfma_f32_32x32x16_bf16 v[16:31], v[76:79], v[232:235], v[16:31]
	s_and_b32 s0, s27, 3
	s_cmp_eq_u32 s0, 0
	s_cbranch_scc0 .Llru1_id0_0
	v_mfma_f32_32x32x16_bf16 v[32:47], v[48:51], v[172:175], 0
	v_mfma_f32_32x32x16_bf16 v[32:47], v[52:55], v[176:179], v[32:47]

; __device__ __forceinline__ float bf2f(u16 x) { return __uint_as_float(((unsigned)x) << 16); }
; __device__ __forceinline__ float fexp(float x) { return __builtin_amdgcn_exp2f(x * 1.4426950408889634f); }
; __device__ __forceinline__ int crow(int r, int hi) { return (r & 3) + 8 * (r >> 2) + 4 * hi; }
; template <int PASS>
; __device__ __forceinline__ void lru_tile_phase(const Params& p, int jl, int Mrows, char* smem, int tid, int bid) {
;     ...
;         for (int r = 0; r < 16; ++r) {
;           const int tok = tb * 32 + crow(r, hi);
;           const float xc = bf2f(*(const u16*)(xcL + swz256(tok, chl >> 3) + (chl & 7) * 2));
;           const float la = c_sp * __builtin_amdgcn_rcpf(1.f + fexp(-(acc0[r] + c_ba)));
;           const float ii = __builtin_amdgcn_rcpf(1.f + fexp(-(acc1[r] + c_bx)));
;           const float av = fexp(la);
;           aL[(dh * 64 + tok) * 128 + chl] = av;
;           uL[(dh * 64 + tok) * 128 + chl] = __builtin_amdgcn_sqrtf(fmaxf(1.f - av * av, 0.f)) * (ii * xc);
;         }
.Llru1_id1_3:
	s_nop 7
	s_nop 7
	v_mov_b32_e32 v80, v180
	v_fmac_f32_e32 v80, 0xbfb8aa3b, v0
	v_mov_b32_e32 v81, v181
	v_fmac_f32_e32 v81, 0xbfb8aa3b, v16
	v_exp_f32_e32 v80, v80
	v_exp_f32_e32 v81, v81
	v_add_f32_e32 v80, 1.0, v80
	v_add_f32_e32 v81, 1.0, v81
	v_rcp_f32_e32 v80, v80
	v_rcp_f32_e32 v81, v81
	s_nop 0
	v_mul_f32_e32 v80, v182, v80
	v_mul_f32_e32 v81, v81, v32
	v_exp_f32_e32 v80, v80
	s_nop 0
	v_fma_f32 v82, -v80, v80, 1.0
	v_max_f32_e32 v82, 0, v82
	v_sqrt_f32_e32 v82, v82
	ds_write_b32 v186, v80 offset:16384
	v_mul_f32_e32 v82, v82, v81
	ds_write_b32 v187, v82 offset:16384
	v_mov_b32_e32 v88, v180
	v_fmac_f32_e32 v88, 0xbfb8aa3b, v1
	v_mov_b32_e32 v89, v181
	v_fmac_f32_e32 v89, 0xbfb8aa3b, v17
	v_exp_f32_e32 v88, v88
	v_exp_f32_e32 v89, v89
	v_add_f32_e32 v88, 1.0, v88
	v_add_f32_e32 v89, 1.0, v89
	v_rcp_f32_e32 v88, v88
	v_rcp_f32_e32 v89, v89
	s_nop 0
	v_mul_f32_e32 v88, v182, v88
	v_mul_f32_e32 v89, v89, v33
	v_exp_f32_e32 v88, v88
	s_nop 0
	v_fma_f32 v90, -v88, v88, 1.0
	v_max_f32_e32 v90, 0, v90
	v_sqrt_f32_e32 v90, v90
	ds_write_b32 v186, v88 offset:16896
	v_mul_f32_e32 v90, v90, v89
	ds_write_b32 v187, v90 offset:16896
	v_mov_b32_e32 v80, v180
	v_fmac_f32_e32 v80, 0xbfb8aa3b, v2
	v_mov_b32_e32 v81, v181
	v_fmac_f32_e32 v81, 0xbfb8aa3b, v18
	v_exp_f32_e32 v80, v80
	v_exp_f32_e32 v81, v81
	v_add_f32_e32 v80, 1.0, v80
	v_add_f32_e32 v81, 1.0, v81
	v_rcp_f32_e32 v80, v80
	v_rcp_f32_e32 v81, v81
	s_nop 0
	v_mul_f32_e32 v80, v182, v80
	v_mul_f32_e32 v81, v81, v34
	v_exp_f32_e32 v80, v80
	s_nop 0
	v_fma_f32 v82, -v80, v80, 1.0
	v_max_f32_e32 v82, 0, v82
	v_sqrt_f32_e32 v82, v82
	ds_write_b32 v186, v80 offset:17408
	v_mul_f32_e32 v82, v82, v81
	ds_write_b32 v187, v82 offset:17408
	v_mov_b32_e32 v88, v180
	v_fmac_f32_e32 v88, 0xbfb8aa3b, v3
	v_mov_b32_e32 v89, v181
	v_fmac_f32_e32 v89, 0xbfb8aa3b, v19
	v_exp_f32_e32 v88, v88
	v_exp_f32_e32 v89, v89
	v_add_f32_e32 v88, 1.0, v88
	v_add_f32_e32 v89, 1.0, v89
	v_rcp_f32_e32 v88, v88
	v_rcp_f32_e32 v89, v89
	s_nop 0
	v_mul_f32_e32 v88, v182, v88
	v_mul_f32_e32 v89, v89, v35
	v_exp_f32_e32 v88, v88
	s_nop 0
	v_fma_f32 v90, -v88, v88, 1.0
	v_max_f32_e32 v90, 0, v90
	v_sqrt_f32_e32 v90, v90
	ds_write_b32 v186, v88 offset:17920
	v_mul_f32_e32 v90, v90, v89
	ds_write_b32 v187, v90 offset:17920
	v_mov_b32_e32 v80, v180
	v_fmac_f32_e32 v80, 0xbfb8aa3b, v4
	v_mov_b32_e32 v81, v181
	v_fmac_f32_e32 v81, 0xbfb8aa3b, v20
	v_exp_f32_e32 v80, v80
	v_exp_f32_e32 v81, v81
	v_add_f32_e32 v80, 1.0, v80
	v_add_f32_e32 v81, 1.0, v81
	v_rcp_f32_e32 v80, v80
	v_rcp_f32_e32 v81, v81
	s_nop 0
	v_mul_f32_e32 v80, v182, v80
	v_mul_f32_e32 v81, v81, v36
	v_exp_f32_e32 v80, v80
	s_nop 0
	v_fma_f32 v82, -v80, v80, 1.0
	v_max_f32_e32 v82, 0, v82
	v_sqrt_f32_e32 v82, v82
	ds_write_b32 v186, v80 offset:20480
	v_mul_f32_e32 v82, v82, v81
	ds_write_b32 v187, v82 offset:20480
	v_mov_b32_e32 v88, v180
	v_fmac_f32_e32 v88, 0xbfb8aa3b, v5
	v_mov_b32_e32 v89, v181
	v_fmac_f32_e32 v89, 0xbfb8aa3b, v21
	v_exp_f32_e32 v88, v88
	v_exp_f32_e32 v89, v89
	v_add_f32_e32 v88, 1.0, v88
	v_add_f32_e32 v89, 1.0, v89
	v_rcp_f32_e32 v88, v88
	v_rcp_f32_e32 v89, v89
	s_nop 0
	v_mul_f32_e32 v88, v182, v88
	v_mul_f32_e32 v89, v89, v37
	v_exp_f32_e32 v88, v88
	s_nop 0
	v_fma_f32 v90, -v88, v88, 1.0
	v_max_f32_e32 v90, 0, v90
	v_sqrt_f32_e32 v90, v90
	ds_write_b32 v186, v88 offset:20992
	v_mul_f32_e32 v90, v90, v89
	ds_write_b32 v187, v90 offset:20992
	v_mov_b32_e32 v80, v180
	v_fmac_f32_e32 v80, 0xbfb8aa3b, v6
	v_mov_b32_e32 v81, v181
	v_fmac_f32_e32 v81, 0xbfb8aa3b, v22
	v_exp_f32_e32 v80, v80
	v_exp_f32_e32 v81, v81
	v_add_f32_e32 v80, 1.0, v80
	v_add_f32_e32 v81, 1.0, v81
	v_rcp_f32_e32 v80, v80
	v_rcp_f32_e32 v81, v81
	s_nop 0
	v_mul_f32_e32 v80, v182, v80
	v_mul_f32_e32 v81, v81, v38
	v_exp_f32_e32 v80, v80
	s_nop 0
	v_fma_f32 v82, -v80, v80, 1.0
	v_max_f32_e32 v82, 0, v82
	v_sqrt_f32_e32 v82, v82
	ds_write_b32 v186, v80 offset:21504
	v_mul_f32_e32 v82, v82, v81
	ds_write_b32 v187, v82 offset:21504
	v_mov_b32_e32 v88, v180
	v_fmac_f32_e32 v88, 0xbfb8aa3b, v7
	v_mov_b32_e32 v89, v181
	v_fmac_f32_e32 v89, 0xbfb8aa3b, v23
	v_exp_f32_e32 v88, v88
	v_exp_f32_e32 v89, v89
	v_add_f32_e32 v88, 1.0, v88
	v_add_f32_e32 v89, 1.0, v89
	v_rcp_f32_e32 v88, v88
	v_rcp_f32_e32 v89, v89
	s_nop 0
	v_mul_f32_e32 v88, v182, v88
	v_mul_f32_e32 v89, v89, v39
	v_exp_f32_e32 v88, v88
	s_nop 0
	v_fma_f32 v90, -v88, v88, 1.0
	v_max_f32_e32 v90, 0, v90
	v_sqrt_f32_e32 v90, v90
	ds_write_b32 v186, v88 offset:22016
	v_mul_f32_e32 v90, v90, v89
	ds_write_b32 v187, v90 offset:22016
	v_mov_b32_e32 v80, v180
	v_fmac_f32_e32 v80, 0xbfb8aa3b, v8
	v_mov_b32_e32 v81, v181
	v_fmac_f32_e32 v81, 0xbfb8aa3b, v24
	v_exp_f32_e32 v80, v80
	v_exp_f32_e32 v81, v81
	v_add_f32_e32 v80, 1.0, v80
	v_add_f32_e32 v81, 1.0, v81
	v_rcp_f32_e32 v80, v80
	v_rcp_f32_e32 v81, v81
	s_nop 0
	v_mul_f32_e32 v80, v182, v80
	v_mul_f32_e32 v81, v81, v40
	v_exp_f32_e32 v80, v80
	s_nop 0
	v_fma_f32 v82, -v80, v80, 1.0
	v_max_f32_e32 v82, 0, v82
	v_sqrt_f32_e32 v82, v82
	ds_write_b32 v186, v80 offset:24576
	v_mul_f32_e32 v82, v82, v81
	ds_write_b32 v187, v82 offset:24576
	v_mov_b32_e32 v88, v180
	v_fmac_f32_e32 v88, 0xbfb8aa3b, v9
	v_mov_b32_e32 v89, v181
	v_fmac_f32_e32 v89, 0xbfb8aa3b, v25
	v_exp_f32_e32 v88, v88
	v_exp_f32_e32 v89, v89
	v_add_f32_e32 v88, 1.0, v88
	v_add_f32_e32 v89, 1.0, v89
	v_rcp_f32_e32 v88, v88
	v_rcp_f32_e32 v89, v89
	s_nop 0
	v_mul_f32_e32 v88, v182, v88
	v_mul_f32_e32 v89, v89, v41
	v_exp_f32_e32 v88, v88
	s_nop 0
	v_fma_f32 v90, -v88, v88, 1.0
	v_max_f32_e32 v90, 0, v90
	v_sqrt_f32_e32 v90, v90
	ds_write_b32 v186, v88 offset:25088
	v_mul_f32_e32 v90, v90, v89
; template <int PASS>
; __device__ __forceinline__ void lru_tile_phase(const Params& p, int jl, int Mrows, char* smem, int tid, int bid) {
;     ...
;     __syncthreads();
;     if (tid < 256) {
;       const int dir = tid >> 7, ch = tid & 127;
;       const size_t sidx = (size_t)(tt * 2 + dir) * 1024 + n * 128 + ch;
;       float hst = 0.f, ap = 1.f;
;       if (PASS == 2) hst = carry_in;
;       const float* ap_ = aL + (dir * 64) * 128 + ch;
;       float* up_ = uL + (dir * 64) * 128 + ch;
; #pragma unroll 1
;       for (int i0 = 0; i0 < 64; i0 += 16) {
;         float av[16], uv[16];
; #pragma unroll
;         for (int k = 0; k < 16; ++k) { const int t = dir ? 63 - (i0 + k) : i0 + k; av[k] = ap_[t * 128]; uv[k] = up_[t * 128]; }
; #pragma unroll
;         for (int k = 0; k < 16; ++k) { hst = fmaf(av[k], hst, uv[k]); if (PASS == 1) ap *= av[k]; else uv[k] = hst; }
;         if (PASS == 2) {
; #pragma unroll
;           for (int k = 0; k < 16; ++k) { const int t = dir ? 63 - (i0 + k) : i0 + k; up_[t * 128] = uv[k]; }
;         }
;       }
;       if (PASS == 1) summ[sidx] = make_float2(ap, hst);
	ds_write_b32 v187, v90 offset:25088
	v_mov_b32_e32 v80, v180
	v_fmac_f32_e32 v80, 0xbfb8aa3b, v10
	v_mov_b32_e32 v81, v181
	v_fmac_f32_e32 v81, 0xbfb8aa3b, v26
	v_exp_f32_e32 v80, v80
	v_exp_f32_e32 v81, v81
	v_add_f32_e32 v80, 1.0, v80
	v_add_f32_e32 v81, 1.0, v81
	v_rcp_f32_e32 v80, v80
	v_rcp_f32_e32 v81, v81
	s_nop 0
	v_mul_f32_e32 v80, v182, v80
	v_mul_f32_e32 v81, v81, v42
	v_exp_f32_e32 v80, v80
	s_nop 0
	v_fma_f32 v82, -v80, v80, 1.0
	v_max_f32_e32 v82, 0, v82
	v_sqrt_f32_e32 v82, v82
	ds_write_b32 v186, v80 offset:25600
	v_mul_f32_e32 v82, v82, v81
	ds_write_b32 v187, v82 offset:25600
	v_mov_b32_e32 v88, v180
	v_fmac_f32_e32 v88, 0xbfb8aa3b, v11
	v_mov_b32_e32 v89, v181
	v_fmac_f32_e32 v89, 0xbfb8aa3b, v27
	v_exp_f32_e32 v88, v88
	v_exp_f32_e32 v89, v89
	v_add_f32_e32 v88, 1.0, v88
	v_add_f32_e32 v89, 1.0, v89
	v_rcp_f32_e32 v88, v88
	v_rcp_f32_e32 v89, v89
	s_nop 0
	v_mul_f32_e32 v88, v182, v88
	v_mul_f32_e32 v89, v89, v43
	v_exp_f32_e32 v88, v88
	s_nop 0
	v_fma_f32 v90, -v88, v88, 1.0
	v_max_f32_e32 v90, 0, v90
	v_sqrt_f32_e32 v90, v90
	ds_write_b32 v186, v88 offset:26112
	v_mul_f32_e32 v90, v90, v89
	ds_write_b32 v187, v90 offset:26112
	v_mov_b32_e32 v80, v180
	v_fmac_f32_e32 v80, 0xbfb8aa3b, v12
	v_mov_b32_e32 v81, v181
	v_fmac_f32_e32 v81, 0xbfb8aa3b, v28
	v_exp_f32_e32 v80, v80
	v_exp_f32_e32 v81, v81
	v_add_f32_e32 v80, 1.0, v80
	v_add_f32_e32 v81, 1.0, v81
	v_rcp_f32_e32 v80, v80
	v_rcp_f32_e32 v81, v81
	s_nop 0
	v_mul_f32_e32 v80, v182, v80
	v_mul_f32_e32 v81, v81, v44
	v_exp_f32_e32 v80, v80
	s_nop 0
	v_fma_f32 v82, -v80, v80, 1.0
	v_max_f32_e32 v82, 0, v82
	v_sqrt_f32_e32 v82, v82
	ds_write_b32 v186, v80 offset:28672
	v_mul_f32_e32 v82, v82, v81
	ds_write_b32 v187, v82 offset:28672
	v_mov_b32_e32 v88, v180
	v_fmac_f32_e32 v88, 0xbfb8aa3b, v13
	v_mov_b32_e32 v89, v181
	v_fmac_f32_e32 v89, 0xbfb8aa3b, v29
	v_exp_f32_e32 v88, v88
	v_exp_f32_e32 v89, v89
	v_add_f32_e32 v88, 1.0, v88
	v_add_f32_e32 v89, 1.0, v89
	v_rcp_f32_e32 v88, v88
	v_rcp_f32_e32 v89, v89
	s_nop 0
	v_mul_f32_e32 v88, v182, v88
	v_mul_f32_e32 v89, v89, v45
	v_exp_f32_e32 v88, v88
	s_nop 0
	v_fma_f32 v90, -v88, v88, 1.0
	v_max_f32_e32 v90, 0, v90
	v_sqrt_f32_e32 v90, v90
	ds_write_b32 v186, v88 offset:29184
	v_mul_f32_e32 v90, v90, v89
	ds_write_b32 v187, v90 offset:29184
	v_mov_b32_e32 v80, v180
	v_fmac_f32_e32 v80, 0xbfb8aa3b, v14
	v_mov_b32_e32 v81, v181
	v_fmac_f32_e32 v81, 0xbfb8aa3b, v30
	v_exp_f32_e32 v80, v80
	v_exp_f32_e32 v81, v81
	v_add_f32_e32 v80, 1.0, v80
	v_add_f32_e32 v81, 1.0, v81
	v_rcp_f32_e32 v80, v80
	v_rcp_f32_e32 v81, v81
	s_nop 0
	v_mul_f32_e32 v80, v182, v80
	v_mul_f32_e32 v81, v81, v46
	v_exp_f32_e32 v80, v80
	s_nop 0
	v_fma_f32 v82, -v80, v80, 1.0
	v_max_f32_e32 v82, 0, v82
	v_sqrt_f32_e32 v82, v82
	ds_write_b32 v186, v80 offset:29696
	v_mul_f32_e32 v82, v82, v81
	ds_write_b32 v187, v82 offset:29696
	v_mov_b32_e32 v88, v180
	v_fmac_f32_e32 v88, 0xbfb8aa3b, v15
	v_mov_b32_e32 v89, v181
	v_fmac_f32_e32 v89, 0xbfb8aa3b, v31
	v_exp_f32_e32 v88, v88
	v_exp_f32_e32 v89, v89
	v_add_f32_e32 v88, 1.0, v88
	v_add_f32_e32 v89, 1.0, v89
	v_rcp_f32_e32 v88, v88
	v_rcp_f32_e32 v89, v89
	s_nop 0
	v_mul_f32_e32 v88, v182, v88
	v_mul_f32_e32 v89, v89, v47
	v_exp_f32_e32 v88, v88
	s_nop 0
	v_fma_f32 v90, -v88, v88, 1.0
	v_max_f32_e32 v90, 0, v90
	v_sqrt_f32_e32 v90, v90
	ds_write_b32 v186, v88 offset:30208
	v_mul_f32_e32 v90, v90, v89
	ds_write_b32 v187, v90 offset:30208
	s_waitcnt lgkmcnt(0)
	s_barrier
	s_cmp_gt_u32 s27, 3
	s_cbranch_scc1 .Llru1_scan_done
	v_mov_b32_e32 v96, 0
	v_mov_b32_e32 v97, 1.0
	v_add_u32_e32 v195, 0x10000, v188
	s_cmp_gt_u32 s27, 1
	s_cbranch_scc1 .Llru1_scan_bwd
	ds_read2st64_b32 v[0:1], v188 offset0:0 offset1:2
	ds_read2st64_b32 v[2:3], v188 offset0:4 offset1:6
	ds_read2st64_b32 v[4:5], v188 offset0:8 offset1:10
	ds_read2st64_b32 v[6:7], v188 offset0:12 offset1:14
	ds_read2st64_b32 v[8:9], v195 offset0:0 offset1:2
	ds_read2st64_b32 v[10:11], v195 offset0:4 offset1:6
	ds_read2st64_b32 v[12:13], v195 offset0:8 offset1:10
	ds_read2st64_b32 v[14:15], v195 offset0:12 offset1:14
	s_waitcnt lgkmcnt(0)
	ds_read2st64_b32 v[16:17], v188 offset0:16 offset1:18
	ds_read2st64_b32 v[18:19], v188 offset0:20 offset1:22
	ds_read2st64_b32 v[20:21], v188 offset0:24 offset1:26
	ds_read2st64_b32 v[22:23], v188 offset0:28 offset1:30
	ds_read2st64_b32 v[24:25], v195 offset0:16 offset1:18
	ds_read2st64_b32 v[26:27], v195 offset0:20 offset1:22
	ds_read2st64_b32 v[28:29], v195 offset0:24 offset1:26
	ds_read2st64_b32 v[30:31], v195 offset0:28 offset1:30
	v_fma_f32 v96, v0, v96, v8
	v_mul_f32_e32 v97, v97, v0
	v_fma_f32 v96, v1, v96, v9
	v_mul_f32_e32 v97, v97, v1
	v_fma_f32 v96, v2, v96, v10
	v_mul_f32_e32 v97, v97, v2
	v_fma_f32 v96, v3, v96, v11
	v_mul_f32_e32 v97, v97, v3
	v_fma_f32 v96, v4, v96, v12
	v_mul_f32_e32 v97, v97, v4
	v_fma_f32 v96, v5, v96, v13
	v_mul_f32_e32 v97, v97, v5
	v_fma_f32 v96, v6, v96, v14
	v_mul_f32_e32 v97, v97, v6
	v_fma_f32 v96, v7, v96, v15
	v_mul_f32_e32 v97, v97, v7
	s_waitcnt lgkmcnt(0)
	ds_read2st64_b32 v[0:1], v188 offset0:32 offset1:34
	ds_read2st64_b32 v[2:3], v188 offset0:36 offset1:38
	ds_read2st64_b32 v[4:5], v188 offset0:40 offset1:42
	ds_read2st64_b32 v[6:7], v188 offset0:44 offset1:46
	ds_read2st64_b32 v[8:9], v195 offset0:32 offset1:34
	ds_read2st64_b32 v[10:11], v195 offset0:36 offset1:38
	ds_read2st64_b32 v[12:13], v195 offset0:40 offset1:42
	ds_read2st64_b32 v[14:15], v195 offset0:44 offset1:46
	v_fma_f32 v96, v16, v96, v24
	v_mul_f32_e32 v97, v97, v16
	v_fma_f32 v96, v17, v96, v25
	v_mul_f32_e32 v97, v97, v17
	v_fma_f32 v96, v18, v96, v26
	v_mul_f32_e32 v97, v97, v18
	v_fma_f32 v96, v19, v96, v27
	v_mul_f32_e32 v97, v97, v19
	v_fma_f32 v96, v20, v96, v28
	v_mul_f32_e32 v97, v97, v20
	v_fma_f32 v96, v21, v96, v29
	v_mul_f32_e32 v97, v97, v21
	v_fma_f32 v96, v22, v96, v30
	v_mul_f32_e32 v97, v97, v22
	v_fma_f32 v96, v23, v96, v31
	v_mul_f32_e32 v97, v97, v23
	s_waitcnt lgkmcnt(0)
; template <int PASS>
; __device__ __forceinline__ void lru_tile_phase(const Params& p, int jl, int Mrows, char* smem, int tid, int bid) {
;     ...
;       for (int i0 = 0; i0 < 64; i0 += 16) {
;         float av[16], uv[16];
; #pragma unroll
;         for (int k = 0; k < 16; ++k) { const int t = dir ? 63 - (i0 + k) : i0 + k; av[k] = ap_[t * 128]; uv[k] = up_[t * 128]; }
; #pragma unroll
;         for (int k = 0; k < 16; ++k) { hst = fmaf(av[k], hst, uv[k]); if (PASS == 1) ap *= av[k]; else uv[k] = hst; }
;         if (PASS == 2) {
; #pragma unroll
;           for (int k = 0; k < 16; ++k) { const int t = dir ? 63 - (i0 + k) : i0 + k; up_[t * 128] = uv[k]; }
;         }
;       }
;       if (PASS == 1) summ[sidx] = make_float2(ap, hst);
	ds_read2st64_b32 v[16:17], v188 offset0:48 offset1:50
	ds_read2st64_b32 v[18:19], v188 offset0:52 offset1:54
	ds_read2st64_b32 v[20:21], v188 offset0:56 offset1:58
	ds_read2st64_b32 v[22:23], v188 offset0:60 offset1:62
	ds_read2st64_b32 v[24:25], v195 offset0:48 offset1:50
	ds_read2st64_b32 v[26:27], v195 offset0:52 offset1:54
	ds_read2st64_b32 v[28:29], v195 offset0:56 offset1:58
	ds_read2st64_b32 v[30:31], v195 offset0:60 offset1:62
	v_fma_f32 v96, v0, v96, v8
	v_mul_f32_e32 v97, v97, v0
	v_fma_f32 v96, v1, v96, v9
	v_mul_f32_e32 v97, v97, v1
	v_fma_f32 v96, v2, v96, v10
	v_mul_f32_e32 v97, v97, v2
	v_fma_f32 v96, v3, v96, v11
	v_mul_f32_e32 v97, v97, v3
	v_fma_f32 v96, v4, v96, v12
	v_mul_f32_e32 v97, v97, v4
	v_fma_f32 v96, v5, v96, v13
	v_mul_f32_e32 v97, v97, v5
	v_fma_f32 v96, v6, v96, v14
	v_mul_f32_e32 v97, v97, v6
	v_fma_f32 v96, v7, v96, v15
	v_mul_f32_e32 v97, v97, v7
	s_waitcnt lgkmcnt(0)
	ds_read2st64_b32 v[0:1], v188 offset0:64 offset1:66
	ds_read2st64_b32 v[2:3], v188 offset0:68 offset1:70
	ds_read2st64_b32 v[4:5], v188 offset0:72 offset1:74
	ds_read2st64_b32 v[6:7], v188 offset0:76 offset1:78
	ds_read2st64_b32 v[8:9], v195 offset0:64 offset1:66
	ds_read2st64_b32 v[10:11], v195 offset0:68 offset1:70
	ds_read2st64_b32 v[12:13], v195 offset0:72 offset1:74
	ds_read2st64_b32 v[14:15], v195 offset0:76 offset1:78
	v_fma_f32 v96, v16, v96, v24
	v_mul_f32_e32 v97, v97, v16
	v_fma_f32 v96, v17, v96, v25
	v_mul_f32_e32 v97, v97, v17
	v_fma_f32 v96, v18, v96, v26
	v_mul_f32_e32 v97, v97, v18
	v_fma_f32 v96, v19, v96, v27
	v_mul_f32_e32 v97, v97, v19
	v_fma_f32 v96, v20, v96, v28
	v_mul_f32_e32 v97, v97, v20
	v_fma_f32 v96, v21, v96, v29
	v_mul_f32_e32 v97, v97, v21
	v_fma_f32 v96, v22, v96, v30
	v_mul_f32_e32 v97, v97, v22
	v_fma_f32 v96, v23, v96, v31
	v_mul_f32_e32 v97, v97, v23
	s_waitcnt lgkmcnt(0)
	ds_read2st64_b32 v[16:17], v188 offset0:80 offset1:82
	ds_read2st64_b32 v[18:19], v188 offset0:84 offset1:86
	ds_read2st64_b32 v[20:21], v188 offset0:88 offset1:90
	ds_read2st64_b32 v[22:23], v188 offset0:92 offset1:94
	ds_read2st64_b32 v[24:25], v195 offset0:80 offset1:82
	ds_read2st64_b32 v[26:27], v195 offset0:84 offset1:86
	ds_read2st64_b32 v[28:29], v195 offset0:88 offset1:90
	ds_read2st64_b32 v[30:31], v195 offset0:92 offset1:94
	v_fma_f32 v96, v0, v96, v8
	v_mul_f32_e32 v97, v97, v0
	v_fma_f32 v96, v1, v96, v9
	v_mul_f32_e32 v97, v97, v1
	v_fma_f32 v96, v2, v96, v10
	v_mul_f32_e32 v97, v97, v2
	v_fma_f32 v96, v3, v96, v11
	v_mul_f32_e32 v97, v97, v3
	v_fma_f32 v96, v4, v96, v12
	v_mul_f32_e32 v97, v97, v4
	v_fma_f32 v96, v5, v96, v13
	v_mul_f32_e32 v97, v97, v5
	v_fma_f32 v96, v6, v96, v14
	v_mul_f32_e32 v97, v97, v6
	v_fma_f32 v96, v7, v96, v15
	v_mul_f32_e32 v97, v97, v7
	s_waitcnt lgkmcnt(0)
	ds_read2st64_b32 v[0:1], v188 offset0:96 offset1:98
	ds_read2st64_b32 v[2:3], v188 offset0:100 offset1:102
	ds_read2st64_b32 v[4:5], v188 offset0:104 offset1:106
	ds_read2st64_b32 v[6:7], v188 offset0:108 offset1:110
	ds_read2st64_b32 v[8:9], v195 offset0:96 offset1:98
	ds_read2st64_b32 v[10:11], v195 offset0:100 offset1:102
	ds_read2st64_b32 v[12:13], v195 offset0:104 offset1:106
	ds_read2st64_b32 v[14:15], v195 offset0:108 offset1:110
	v_fma_f32 v96, v16, v96, v24
	v_mul_f32_e32 v97, v97, v16
	v_fma_f32 v96, v17, v96, v25
	v_mul_f32_e32 v97, v97, v17
	v_fma_f32 v96, v18, v96, v26
	v_mul_f32_e32 v97, v97, v18
	v_fma_f32 v96, v19, v96, v27
	v_mul_f32_e32 v97, v97, v19
	v_fma_f32 v96, v20, v96, v28
	v_mul_f32_e32 v97, v97, v20
	v_fma_f32 v96, v21, v96, v29
	v_mul_f32_e32 v97, v97, v21
	v_fma_f32 v96, v22, v96, v30
	v_mul_f32_e32 v97, v97, v22
	v_fma_f32 v96, v23, v96, v31
	v_mul_f32_e32 v97, v97, v23
	s_waitcnt lgkmcnt(0)
	ds_read2st64_b32 v[16:17], v188 offset0:112 offset1:114
	ds_read2st64_b32 v[18:19], v188 offset0:116 offset1:118
	ds_read2st64_b32 v[20:21], v188 offset0:120 offset1:122
	ds_read2st64_b32 v[22:23], v188 offset0:124 offset1:126
	ds_read2st64_b32 v[24:25], v195 offset0:112 offset1:114
	ds_read2st64_b32 v[26:27], v195 offset0:116 offset1:118
	ds_read2st64_b32 v[28:29], v195 offset0:120 offset1:122
	ds_read2st64_b32 v[30:31], v195 offset0:124 offset1:126
	v_fma_f32 v96, v0, v96, v8
	v_mul_f32_e32 v97, v97, v0
	v_fma_f32 v96, v1, v96, v9
	v_mul_f32_e32 v97, v97, v1
	v_fma_f32 v96, v2, v96, v10
	v_mul_f32_e32 v97, v97, v2
	v_fma_f32 v96, v3, v96, v11
	v_mul_f32_e32 v97, v97, v3
	v_fma_f32 v96, v4, v96, v12
	v_mul_f32_e32 v97, v97, v4
	v_fma_f32 v96, v5, v96, v13
	v_mul_f32_e32 v97, v97, v5
	v_fma_f32 v96, v6, v96, v14
	v_mul_f32_e32 v97, v97, v6
	v_fma_f32 v96, v7, v96, v15
	v_mul_f32_e32 v97, v97, v7
	s_waitcnt lgkmcnt(0)
	v_fma_f32 v96, v16, v96, v24
	v_mul_f32_e32 v97, v97, v16
	v_fma_f32 v96, v17, v96, v25
	v_mul_f32_e32 v97, v97, v17
	v_fma_f32 v96, v18, v96, v26
	v_mul_f32_e32 v97, v97, v18
	v_fma_f32 v96, v19, v96, v27
	v_mul_f32_e32 v97, v97, v19
	v_fma_f32 v96, v20, v96, v28
	v_mul_f32_e32 v97, v97, v20
	v_fma_f32 v96, v21, v96, v29
	v_mul_f32_e32 v97, v97, v21
	v_fma_f32 v96, v22, v96, v30
	v_mul_f32_e32 v97, v97, v22
	v_fma_f32 v96, v23, v96, v31
	v_mul_f32_e32 v97, v97, v23
	s_branch .Llru1_scan_store
; template <int PASS>
; __device__ __forceinline__ void lru_tile_phase(const Params& p, int jl, int Mrows, char* smem, int tid, int bid) {
;     ...
;     if (tid < 256) {
;       const int dir = tid >> 7, ch = tid & 127;
;       const size_t sidx = (size_t)(tt * 2 + dir) * 1024 + n * 128 + ch;
;       float hst = 0.f, ap = 1.f;
;       if (PASS == 2) hst = carry_in;
;       const float* ap_ = aL + (dir * 64) * 128 + ch;
;       float* up_ = uL + (dir * 64) * 128 + ch;
; #pragma unroll 1
;       for (int i0 = 0; i0 < 64; i0 += 16) {
;         float av[16], uv[16];
; #pragma unroll
;         for (int k = 0; k < 16; ++k) { const int t = dir ? 63 - (i0 + k) : i0 + k; av[k] = ap_[t * 128]; uv[k] = up_[t * 128]; }
; #pragma unroll
;         for (int k = 0; k < 16; ++k) { hst = fmaf(av[k], hst, uv[k]); if (PASS == 1) ap *= av[k]; else uv[k] = hst; }
;         if (PASS == 2) {
; #pragma unroll
;           for (int k = 0; k < 16; ++k) { const int t = dir ? 63 - (i0 + k) : i0 + k; up_[t * 128] = uv[k]; }
;         }
;       }
;       if (PASS == 1) summ[sidx] = make_float2(ap, hst);
.Llru1_scan_bwd:
	ds_read2st64_b32 v[0:1], v188 offset0:126 offset1:124
	ds_read2st64_b32 v[2:3], v188 offset0:122 offset1:120
	ds_read2st64_b32 v[4:5], v188 offset0:118 offset1:116
	ds_read2st64_b32 v[6:7], v188 offset0:114 offset1:112
	ds_read2st64_b32 v[8:9], v195 offset0:126 offset1:124
	ds_read2st64_b32 v[10:11], v195 offset0:122 offset1:120
	ds_read2st64_b32 v[12:13], v195 offset0:118 offset1:116
	ds_read2st64_b32 v[14:15], v195 offset0:114 offset1:112
	s_waitcnt lgkmcnt(0)
	ds_read2st64_b32 v[16:17], v188 offset0:110 offset1:108
	ds_read2st64_b32 v[18:19], v188 offset0:106 offset1:104
	ds_read2st64_b32 v[20:21], v188 offset0:102 offset1:100
	ds_read2st64_b32 v[22:23], v188 offset0:98 offset1:96
	ds_read2st64_b32 v[24:25], v195 offset0:110 offset1:108
	ds_read2st64_b32 v[26:27], v195 offset0:106 offset1:104
	ds_read2st64_b32 v[28:29], v195 offset0:102 offset1:100
	ds_read2st64_b32 v[30:31], v195 offset0:98 offset1:96
	v_fma_f32 v96, v0, v96, v8
	v_mul_f32_e32 v97, v97, v0
	v_fma_f32 v96, v1, v96, v9
	v_mul_f32_e32 v97, v97, v1
	v_fma_f32 v96, v2, v96, v10
	v_mul_f32_e32 v97, v97, v2
	v_fma_f32 v96, v3, v96, v11
	v_mul_f32_e32 v97, v97, v3
	v_fma_f32 v96, v4, v96, v12
	v_mul_f32_e32 v97, v97, v4
	v_fma_f32 v96, v5, v96, v13
	v_mul_f32_e32 v97, v97, v5
	v_fma_f32 v96, v6, v96, v14
	v_mul_f32_e32 v97, v97, v6
	v_fma_f32 v96, v7, v96, v15
	v_mul_f32_e32 v97, v97, v7
	s_waitcnt lgkmcnt(0)
	ds_read2st64_b32 v[0:1], v188 offset0:94 offset1:92
	ds_read2st64_b32 v[2:3], v188 offset0:90 offset1:88
	ds_read2st64_b32 v[4:5], v188 offset0:86 offset1:84
	ds_read2st64_b32 v[6:7], v188 offset0:82 offset1:80
	ds_read2st64_b32 v[8:9], v195 offset0:94 offset1:92
	ds_read2st64_b32 v[10:11], v195 offset0:90 offset1:88
	ds_read2st64_b32 v[12:13], v195 offset0:86 offset1:84
	ds_read2st64_b32 v[14:15], v195 offset0:82 offset1:80
	v_fma_f32 v96, v16, v96, v24
	v_mul_f32_e32 v97, v97, v16
	v_fma_f32 v96, v17, v96, v25
	v_mul_f32_e32 v97, v97, v17
	v_fma_f32 v96, v18, v96, v26
	v_mul_f32_e32 v97, v97, v18
	v_fma_f32 v96, v19, v96, v27
	v_mul_f32_e32 v97, v97, v19
	v_fma_f32 v96, v20, v96, v28
	v_mul_f32_e32 v97, v97, v20
	v_fma_f32 v96, v21, v96, v29
	v_mul_f32_e32 v97, v97, v21
	v_fma_f32 v96, v22, v96, v30
	v_mul_f32_e32 v97, v97, v22
	v_fma_f32 v96, v23, v96, v31
	v_mul_f32_e32 v97, v97, v23
	s_waitcnt lgkmcnt(0)
	ds_read2st64_b32 v[16:17], v188 offset0:78 offset1:76
	ds_read2st64_b32 v[18:19], v188 offset0:74 offset1:72
	ds_read2st64_b32 v[20:21], v188 offset0:70 offset1:68
	ds_read2st64_b32 v[22:23], v188 offset0:66 offset1:64
	ds_read2st64_b32 v[24:25], v195 offset0:78 offset1:76
	ds_read2st64_b32 v[26:27], v195 offset0:74 offset1:72
	ds_read2st64_b32 v[28:29], v195 offset0:70 offset1:68
	ds_read2st64_b32 v[30:31], v195 offset0:66 offset1:64
	v_fma_f32 v96, v0, v96, v8
	v_mul_f32_e32 v97, v97, v0
	v_fma_f32 v96, v1, v96, v9
	v_mul_f32_e32 v97, v97, v1
	v_fma_f32 v96, v2, v96, v10
	v_mul_f32_e32 v97, v97, v2
	v_fma_f32 v96, v3, v96, v11
	v_mul_f32_e32 v97, v97, v3
	v_fma_f32 v96, v4, v96, v12
	v_mul_f32_e32 v97, v97, v4
	v_fma_f32 v96, v5, v96, v13
	v_mul_f32_e32 v97, v97, v5
	v_fma_f32 v96, v6, v96, v14
	v_mul_f32_e32 v97, v97, v6
	v_fma_f32 v96, v7, v96, v15
	v_mul_f32_e32 v97, v97, v7
	s_waitcnt lgkmcnt(0)
	ds_read2st64_b32 v[0:1], v188 offset0:62 offset1:60
	ds_read2st64_b32 v[2:3], v188 offset0:58 offset1:56
	ds_read2st64_b32 v[4:5], v188 offset0:54 offset1:52
	ds_read2st64_b32 v[6:7], v188 offset0:50 offset1:48
	ds_read2st64_b32 v[8:9], v195 offset0:62 offset1:60
	ds_read2st64_b32 v[10:11], v195 offset0:58 offset1:56
	ds_read2st64_b32 v[12:13], v195 offset0:54 offset1:52
	ds_read2st64_b32 v[14:15], v195 offset0:50 offset1:48
	v_fma_f32 v96, v16, v96, v24
	v_mul_f32_e32 v97, v97, v16
	v_fma_f32 v96, v17, v96, v25
	v_mul_f32_e32 v97, v97, v17
	v_fma_f32 v96, v18, v96, v26
	v_mul_f32_e32 v97, v97, v18
	v_fma_f32 v96, v19, v96, v27
	v_mul_f32_e32 v97, v97, v19
	v_fma_f32 v96, v20, v96, v28
	v_mul_f32_e32 v97, v97, v20
	v_fma_f32 v96, v21, v96, v29
	v_mul_f32_e32 v97, v97, v21
	v_fma_f32 v96, v22, v96, v30
	v_mul_f32_e32 v97, v97, v22
	v_fma_f32 v96, v23, v96, v31
	v_mul_f32_e32 v97, v97, v23
	s_waitcnt lgkmcnt(0)
; template <int PASS>
; __device__ __forceinline__ void lru_tile_phase(const Params& p, int jl, int Mrows, char* smem, int tid, int bid) {
;     ...
;       for (int i0 = 0; i0 < 64; i0 += 16) {
;         float av[16], uv[16];
; #pragma unroll
;         for (int k = 0; k < 16; ++k) { const int t = dir ? 63 - (i0 + k) : i0 + k; av[k] = ap_[t * 128]; uv[k] = up_[t * 128]; }
; #pragma unroll
;         for (int k = 0; k < 16; ++k) { hst = fmaf(av[k], hst, uv[k]); if (PASS == 1) ap *= av[k]; else uv[k] = hst; }
;         if (PASS == 2) {
; #pragma unroll
;           for (int k = 0; k < 16; ++k) { const int t = dir ? 63 - (i0 + k) : i0 + k; up_[t * 128] = uv[k]; }
;         }
;       }
;       if (PASS == 1) summ[sidx] = make_float2(ap, hst);
;     }
	ds_read2st64_b32 v[16:17], v188 offset0:46 offset1:44
	ds_read2st64_b32 v[18:19], v188 offset0:42 offset1:40
	ds_read2st64_b32 v[20:21], v188 offset0:38 offset1:36
	ds_read2st64_b32 v[22:23], v188 offset0:34 offset1:32
	ds_read2st64_b32 v[24:25], v195 offset0:46 offset1:44
	ds_read2st64_b32 v[26:27], v195 offset0:42 offset1:40
	ds_read2st64_b32 v[28:29], v195 offset0:38 offset1:36
	ds_read2st64_b32 v[30:31], v195 offset0:34 offset1:32
	v_fma_f32 v96, v0, v96, v8
	v_mul_f32_e32 v97, v97, v0
	v_fma_f32 v96, v1, v96, v9
	v_mul_f32_e32 v97, v97, v1
	v_fma_f32 v96, v2, v96, v10
	v_mul_f32_e32 v97, v97, v2
	v_fma_f32 v96, v3, v96, v11
	v_mul_f32_e32 v97, v97, v3
	v_fma_f32 v96, v4, v96, v12
	v_mul_f32_e32 v97, v97, v4
	v_fma_f32 v96, v5, v96, v13
	v_mul_f32_e32 v97, v97, v5
	v_fma_f32 v96, v6, v96, v14
	v_mul_f32_e32 v97, v97, v6
	v_fma_f32 v96, v7, v96, v15
	v_mul_f32_e32 v97, v97, v7
	s_waitcnt lgkmcnt(0)
	ds_read2st64_b32 v[0:1], v188 offset0:30 offset1:28
	ds_read2st64_b32 v[2:3], v188 offset0:26 offset1:24
	ds_read2st64_b32 v[4:5], v188 offset0:22 offset1:20
	ds_read2st64_b32 v[6:7], v188 offset0:18 offset1:16
	ds_read2st64_b32 v[8:9], v195 offset0:30 offset1:28
	ds_read2st64_b32 v[10:11], v195 offset0:26 offset1:24
	ds_read2st64_b32 v[12:13], v195 offset0:22 offset1:20
	ds_read2st64_b32 v[14:15], v195 offset0:18 offset1:16
	v_fma_f32 v96, v16, v96, v24
	v_mul_f32_e32 v97, v97, v16
	v_fma_f32 v96, v17, v96, v25
	v_mul_f32_e32 v97, v97, v17
	v_fma_f32 v96, v18, v96, v26
	v_mul_f32_e32 v97, v97, v18
	v_fma_f32 v96, v19, v96, v27
	v_mul_f32_e32 v97, v97, v19
	v_fma_f32 v96, v20, v96, v28
	v_mul_f32_e32 v97, v97, v20
	v_fma_f32 v96, v21, v96, v29
	v_mul_f32_e32 v97, v97, v21
	v_fma_f32 v96, v22, v96, v30
	v_mul_f32_e32 v97, v97, v22
	v_fma_f32 v96, v23, v96, v31
	v_mul_f32_e32 v97, v97, v23
	s_waitcnt lgkmcnt(0)
	ds_read2st64_b32 v[16:17], v188 offset0:14 offset1:12
	ds_read2st64_b32 v[18:19], v188 offset0:10 offset1:8
	ds_read2st64_b32 v[20:21], v188 offset0:6 offset1:4
	ds_read2st64_b32 v[22:23], v188 offset0:2 offset1:0
	ds_read2st64_b32 v[24:25], v195 offset0:14 offset1:12
	ds_read2st64_b32 v[26:27], v195 offset0:10 offset1:8
	ds_read2st64_b32 v[28:29], v195 offset0:6 offset1:4
	ds_read2st64_b32 v[30:31], v195 offset0:2 offset1:0
	v_fma_f32 v96, v0, v96, v8
	v_mul_f32_e32 v97, v97, v0
	v_fma_f32 v96, v1, v96, v9
	v_mul_f32_e32 v97, v97, v1
	v_fma_f32 v96, v2, v96, v10
	v_mul_f32_e32 v97, v97, v2
	v_fma_f32 v96, v3, v96, v11
	v_mul_f32_e32 v97, v97, v3
	v_fma_f32 v96, v4, v96, v12
	v_mul_f32_e32 v97, v97, v4
	v_fma_f32 v96, v5, v96, v13
	v_mul_f32_e32 v97, v97, v5
	v_fma_f32 v96, v6, v96, v14
	v_mul_f32_e32 v97, v97, v6
	v_fma_f32 v96, v7, v96, v15
	v_mul_f32_e32 v97, v97, v7
	s_waitcnt lgkmcnt(0)
	v_fma_f32 v96, v16, v96, v24
	v_mul_f32_e32 v97, v97, v16
	v_fma_f32 v96, v17, v96, v25
	v_mul_f32_e32 v97, v97, v17
	v_fma_f32 v96, v18, v96, v26
	v_mul_f32_e32 v97, v97, v18
	v_fma_f32 v96, v19, v96, v27
	v_mul_f32_e32 v97, v97, v19
	v_fma_f32 v96, v20, v96, v28
	v_mul_f32_e32 v97, v97, v20
	v_fma_f32 v96, v21, v96, v29
	v_mul_f32_e32 v97, v97, v21
	v_fma_f32 v96, v22, v96, v30
	v_mul_f32_e32 v97, v97, v22
	v_fma_f32 v96, v23, v96, v31
	v_mul_f32_e32 v97, v97, v23
.Llru1_scan_store:
	s_lshl_b32 s0, s8, 11
	s_lshl_b32 s1, s7, 7
	s_add_u32 s0, s0, s1
	s_lshl_b32 s0, s0, 3
	s_add_u32 s0, s22, s0
	s_addc_u32 s1, s23, 0
	v_lshlrev_b32_e32 v196, 3, v194
	v_mov_b32_e32 v98, v96
	v_mov_b32_e32 v96, v97
	v_mov_b32_e32 v97, v98
	global_store_dwordx2 v196, v[96:97], s[0:1]
.Llru1_scan_done:
	s_waitcnt vmcnt(0) lgkmcnt(0)
	s_barrier
	s_add_u32 s6, s6, s71
	s_cmp_lt_u32 s6, 0x1100
	s_cbranch_scc1 .Llru1_job
	v_readlane_b32 s36, v255, 11
	v_readlane_b32 s37, v255, 12
	v_readlane_b32 s38, v255, 13
	v_readlane_b32 s39, v255, 14
	v_readlane_b32 s40, v255, 15
	v_readlane_b32 s41, v255, 16
	v_readlane_b32 s42, v255, 17
	v_readlane_b32 s43, v255, 18
	v_readlane_b32 s44, v255, 19
	v_readlane_b32 s45, v255, 20
	v_readlane_b32 s46, v255, 21
	v_readlane_b32 s47, v255, 22
	v_readlane_b32 s48, v255, 23
	v_readlane_b32 s49, v255, 24
	v_readlane_b32 s50, v255, 25
	v_readlane_b32 s51, v255, 26
